# GEMM loops: deleted the back-to-back mid-segment s_setprio 0/1 flip pair (s_setprio A/B) on top of v36
# speedup vs baseline: 1.0053x; 1.0006x over previous
; #define PG8_LDA(dst, b, h) do { _Pragma("unroll") for (int m = 0; m < 4; ++m) _Pragma("unroll") for (int k = 0; k < 2; ++k) dst[m][k] = *(const LAS bf16x8*)(lds + PG8_SA(b, h) + aoff + m * 2048 + k * 1024); } while (0)
; #define PG8_LDB(dst, b, h) do { _Pragma("unroll") for (int n = 0; n < 2; ++n) _Pragma("unroll") for (int k = 0; k < 2; ++k) dst[n][k] = *(const LAS bf16x8*)(lds + PG8_SB(b, h) + boff + n * 2048 + k * 1024); } while (0)
; #define PG8_MMA(ai, bj, At, Bt) do { __builtin_amdgcn_s_setprio(1); _Pragma("unroll") for (int m = 0; m < 4; ++m) _Pragma("unroll") for (int n = 0; n < 2; ++n) _Pragma("unroll") for (int k = 0; k < 2; ++k) \
;         acc[ai][bj][m][n] = __builtin_amdgcn_mfma_f32_16x16x32_bf16(Bt[n][k], At[m][k], acc[ai][bj][m][n], 0, 0, 0); __builtin_amdgcn_s_setprio(0); } while (0)
; #define PG8_WAIT_V(n) asm volatile("s_waitcnt vmcnt(" #n ")" ::: "memory")
; #define PG8_WAIT_L(n) asm volatile("s_waitcnt lgkmcnt(" #n ")" ::: "memory")
; #define PG8_BAR __builtin_amdgcn_s_barrier()
; #define PG8_SCHED __builtin_amdgcn_sched_barrier(0)
; __device__ __forceinline__ void gemm_phase(LAS unsigned char* lds, const GemmP& g) {
;     ...
;         for (int t = 0; t < nt; t += 2) {
;             const bool last = (t == nt - 2);
;             const char* a1 = cA + (size_t)(t + 1) * kstep;
;             const char* a2 = last ? nA : cA + (size_t)(t + 2) * kstep; const char* b2 = last ? nB : cB + (size_t)(t + 2) * kstep;
;             const char* a3 = a2 + kstep; const char* b3 = b2 + kstep;
;             PG8_LDB(B0, 0, 0); PG8_LDB(B1, 0, 1); PG8_SCHED; PG8_LDA(At, 0, 0); PG8_STAGE(PG8_SA(1, 1), a1 + hstepA, voffA);
;             PG8_WAIT_V(8); PG8_WAIT_L(0); PG8_BAR; PG8_MMA(0, 0, At, B0); PG8_MMA(0, 1, At, B1); PG8_BAR; PG8_SCHED;
;             PG8_LDA(At, 0, 1); PG8_STAGE(PG8_SB(0, 0), b2, voffB); PG8_STAGE(PG8_SB(0, 1), b2 + hstepB, voffB); PG8_STAGE(PG8_SA(0, 0), a2, voffA);
;             PG8_WAIT_V(8); PG8_WAIT_L(0); PG8_BAR; PG8_MMA(1, 0, At, B0); PG8_MMA(1, 1, At, B1); PG8_BAR; PG8_SCHED;
.LBB0_273:
	ds_read_b128 v[158:161], v155
	ds_read_b128 v[162:165], v155 offset:1024
	ds_read_b128 v[166:169], v155 offset:2048
	ds_read_b128 v[170:173], v155 offset:3072
	ds_read_b128 v[174:177], v156
	ds_read_b128 v[178:181], v156 offset:1024
	ds_read_b128 v[182:185], v156 offset:2048
	ds_read_b128 v[186:189], v156 offset:3072
	s_cmp_eq_u32 s86, 28
	s_cselect_b32 s56, s7, s70
	s_cselect_b32 s57, s5, s71
	s_cselect_b32 s54, s15, s72
	s_cselect_b32 s55, s11, s73
	s_add_u32 s44, s56, 0x80
	s_addc_u32 s45, s57, 0
	v_lshl_add_u64 v[222:223], s[42:43], 0, v[128:129]
	s_add_i32 m0, s21, 0xc000
	ds_read_b128 v[190:193], v157
	ds_read_b128 v[194:197], v157 offset:1024
	ds_read_b128 v[198:201], v157 offset:2048
	ds_read_b128 v[202:205], v157 offset:3072
	ds_read_b128 v[206:209], v157 offset:4096
	ds_read_b128 v[210:213], v157 offset:5120
	ds_read_b128 v[214:217], v157 offset:6144
	ds_read_b128 v[218:221], v157 offset:7168
	global_load_lds_dwordx4 v[222:223], off
	v_lshl_add_u64 v[222:223], s[42:43], 0, v[132:133]
	s_add_i32 m0, s21, 0xe000
	s_nop 0
	global_load_lds_dwordx4 v[222:223], off
	s_waitcnt vmcnt(8)
	s_waitcnt lgkmcnt(0)
	s_barrier
	s_setprio 1
	s_waitcnt lgkmcnt(0)
	v_mfma_f32_16x16x32_bf16 v[124:127], v[158:161], v[190:193], v[124:127]
	v_mfma_f32_16x16x32_bf16 v[120:123], v[166:169], v[190:193], v[120:123]
	v_mfma_f32_16x16x32_bf16 v[116:119], v[158:161], v[198:201], v[116:119]
	v_mfma_f32_16x16x32_bf16 v[112:115], v[166:169], v[198:201], v[112:115]
	v_mfma_f32_16x16x32_bf16 v[100:103], v[158:161], v[206:209], v[100:103]
	v_mfma_f32_16x16x32_bf16 v[96:99], v[166:169], v[206:209], v[96:99]
	v_mfma_f32_16x16x32_bf16 v[84:87], v[158:161], v[214:217], v[84:87]
	v_mfma_f32_16x16x32_bf16 v[80:83], v[166:169], v[214:217], v[80:83]
	v_mfma_f32_16x16x32_bf16 v[124:127], v[162:165], v[194:197], v[124:127]
	v_mfma_f32_16x16x32_bf16 v[120:123], v[170:173], v[194:197], v[120:123]
	v_mfma_f32_16x16x32_bf16 v[116:119], v[162:165], v[202:205], v[116:119]
	v_mfma_f32_16x16x32_bf16 v[112:115], v[170:173], v[202:205], v[112:115]
	v_mfma_f32_16x16x32_bf16 v[100:103], v[162:165], v[210:213], v[100:103]
	v_mfma_f32_16x16x32_bf16 v[96:99], v[170:173], v[210:213], v[96:99]
	v_mfma_f32_16x16x32_bf16 v[84:87], v[162:165], v[218:221], v[84:87]
	v_mfma_f32_16x16x32_bf16 v[80:83], v[170:173], v[218:221], v[80:83]
	v_mfma_f32_16x16x32_bf16 v[108:111], v[174:177], v[190:193], v[108:111]
	v_mfma_f32_16x16x32_bf16 v[104:107], v[182:185], v[190:193], v[104:107]
	v_mfma_f32_16x16x32_bf16 v[92:95], v[174:177], v[198:201], v[92:95]
	v_mfma_f32_16x16x32_bf16 v[88:91], v[182:185], v[198:201], v[88:91]
	v_mfma_f32_16x16x32_bf16 v[76:79], v[174:177], v[206:209], v[76:79]
	v_mfma_f32_16x16x32_bf16 v[72:75], v[182:185], v[206:209], v[72:75]
	v_mfma_f32_16x16x32_bf16 v[68:71], v[174:177], v[214:217], v[68:71]
	v_mfma_f32_16x16x32_bf16 v[64:67], v[182:185], v[214:217], v[64:67]
	v_mfma_f32_16x16x32_bf16 v[108:111], v[178:181], v[194:197], v[108:111]
	v_mfma_f32_16x16x32_bf16 v[104:107], v[186:189], v[194:197], v[104:107]
	v_mfma_f32_16x16x32_bf16 v[92:95], v[178:181], v[202:205], v[92:95]
	v_mfma_f32_16x16x32_bf16 v[88:91], v[186:189], v[202:205], v[88:91]
	v_mfma_f32_16x16x32_bf16 v[76:79], v[178:181], v[210:213], v[76:79]
	v_mfma_f32_16x16x32_bf16 v[72:75], v[186:189], v[210:213], v[72:75]
	v_mfma_f32_16x16x32_bf16 v[68:71], v[178:181], v[218:221], v[68:71]
	v_mfma_f32_16x16x32_bf16 v[64:67], v[186:189], v[218:221], v[64:67]
	s_setprio 0
	s_barrier
	s_add_i32 s87, s63, s20
	v_lshl_add_u64 v[222:223], s[54:55], 0, v[130:131]
	s_mov_b32 m0, s87
	ds_read_b128 v[190:193], v157 offset:16384
	ds_read_b128 v[194:197], v157 offset:17408
	ds_read_b128 v[198:201], v157 offset:18432
	ds_read_b128 v[202:205], v157 offset:19456
	ds_read_b128 v[206:209], v157 offset:20480
	ds_read_b128 v[210:213], v157 offset:21504
	ds_read_b128 v[214:217], v157 offset:22528
	ds_read_b128 v[218:221], v157 offset:23552
	global_load_lds_dwordx4 v[222:223], off
	s_add_i32 m0, s87, 0x2000
	s_add_u32 s88, s54, 0x80000
	v_lshl_add_u64 v[222:223], s[54:55], 0, v[134:135]
	s_addc_u32 s89, s55, 0
	s_add_i32 s87, s68, s20
	global_load_lds_dwordx4 v[222:223], off
	v_lshl_add_u64 v[222:223], s[88:89], 0, v[130:131]
	s_mov_b32 m0, s87
	s_nop 0
	global_load_lds_dwordx4 v[222:223], off
	v_lshl_add_u64 v[222:223], s[88:89], 0, v[134:135]
	s_add_i32 m0, s87, 0x2000
	s_nop 0
	global_load_lds_dwordx4 v[222:223], off
	v_lshl_add_u64 v[222:223], s[56:57], 0, v[128:129]
	s_mov_b32 m0, s21
	s_nop 0
	global_load_lds_dwordx4 v[222:223], off
	v_lshl_add_u64 v[222:223], s[56:57], 0, v[132:133]
	s_mov_b32 m0, s28
	s_nop 0
	global_load_lds_dwordx4 v[222:223], off
	s_waitcnt vmcnt(8)
	s_waitcnt lgkmcnt(0)
	s_barrier
; #define PG8_LDA(dst, b, h) do { _Pragma("unroll") for (int m = 0; m < 4; ++m) _Pragma("unroll") for (int k = 0; k < 2; ++k) dst[m][k] = *(const LAS bf16x8*)(lds + PG8_SA(b, h) + aoff + m * 2048 + k * 1024); } while (0)
; #define PG8_LDB(dst, b, h) do { _Pragma("unroll") for (int n = 0; n < 2; ++n) _Pragma("unroll") for (int k = 0; k < 2; ++k) dst[n][k] = *(const LAS bf16x8*)(lds + PG8_SB(b, h) + boff + n * 2048 + k * 1024); } while (0)
; #define PG8_MMA(ai, bj, At, Bt) do { __builtin_amdgcn_s_setprio(1); _Pragma("unroll") for (int m = 0; m < 4; ++m) _Pragma("unroll") for (int n = 0; n < 2; ++n) _Pragma("unroll") for (int k = 0; k < 2; ++k) \
;         acc[ai][bj][m][n] = __builtin_amdgcn_mfma_f32_16x16x32_bf16(Bt[n][k], At[m][k], acc[ai][bj][m][n], 0, 0, 0); __builtin_amdgcn_s_setprio(0); } while (0)
; #define PG8_WAIT_V(n) asm volatile("s_waitcnt vmcnt(" #n ")" ::: "memory")
; #define PG8_WAIT_L(n) asm volatile("s_waitcnt lgkmcnt(" #n ")" ::: "memory")
; #define PG8_BAR __builtin_amdgcn_s_barrier()
; #define PG8_SCHED __builtin_amdgcn_sched_barrier(0)
; __device__ __forceinline__ void gemm_phase(LAS unsigned char* lds, const GemmP& g) {
;     ...
;             PG8_WAIT_V(8); PG8_WAIT_L(0); PG8_BAR; PG8_MMA(1, 0, At, B0); PG8_MMA(1, 1, At, B1); PG8_BAR; PG8_SCHED;
;             PG8_LDB(B0, 1, 0); PG8_LDB(B1, 1, 1); PG8_SCHED; PG8_LDA(At, 1, 0); PG8_STAGE(PG8_SA(0, 1), a2 + hstepA, voffA);
;             PG8_WAIT_V(8); PG8_WAIT_L(0); PG8_BAR; PG8_MMA(0, 0, At, B0); PG8_MMA(0, 1, At, B1); PG8_BAR; PG8_SCHED;
	s_setprio 1
	s_waitcnt lgkmcnt(0)
	v_mfma_f32_16x16x32_bf16 v[60:63], v[158:161], v[190:193], v[60:63]
	v_mfma_f32_16x16x32_bf16 v[56:59], v[166:169], v[190:193], v[56:59]
	v_mfma_f32_16x16x32_bf16 v[52:55], v[158:161], v[198:201], v[52:55]
	v_mfma_f32_16x16x32_bf16 v[48:51], v[166:169], v[198:201], v[48:51]
	v_mfma_f32_16x16x32_bf16 v[36:39], v[158:161], v[206:209], v[36:39]
	v_mfma_f32_16x16x32_bf16 v[32:35], v[166:169], v[206:209], v[32:35]
	v_mfma_f32_16x16x32_bf16 v[20:23], v[158:161], v[214:217], v[20:23]
	v_mfma_f32_16x16x32_bf16 v[16:19], v[166:169], v[214:217], v[16:19]
	v_mfma_f32_16x16x32_bf16 v[60:63], v[162:165], v[194:197], v[60:63]
	v_mfma_f32_16x16x32_bf16 v[56:59], v[170:173], v[194:197], v[56:59]
	v_mfma_f32_16x16x32_bf16 v[52:55], v[162:165], v[202:205], v[52:55]
	v_mfma_f32_16x16x32_bf16 v[48:51], v[170:173], v[202:205], v[48:51]
	v_mfma_f32_16x16x32_bf16 v[36:39], v[162:165], v[210:213], v[36:39]
	v_mfma_f32_16x16x32_bf16 v[32:35], v[170:173], v[210:213], v[32:35]
	v_mfma_f32_16x16x32_bf16 v[20:23], v[162:165], v[218:221], v[20:23]
	v_mfma_f32_16x16x32_bf16 v[16:19], v[170:173], v[218:221], v[16:19]
	v_mfma_f32_16x16x32_bf16 v[44:47], v[174:177], v[190:193], v[44:47]
	v_mfma_f32_16x16x32_bf16 v[40:43], v[182:185], v[190:193], v[40:43]
	v_mfma_f32_16x16x32_bf16 v[28:31], v[174:177], v[198:201], v[28:31]
	v_mfma_f32_16x16x32_bf16 v[24:27], v[182:185], v[198:201], v[24:27]
	v_mfma_f32_16x16x32_bf16 v[12:15], v[174:177], v[206:209], v[12:15]
	v_mfma_f32_16x16x32_bf16 v[8:11], v[182:185], v[206:209], v[8:11]
	v_mfma_f32_16x16x32_bf16 v[4:7], v[174:177], v[214:217], v[4:7]
	v_mfma_f32_16x16x32_bf16 v[0:3], v[182:185], v[214:217], v[0:3]
	v_mfma_f32_16x16x32_bf16 v[44:47], v[178:181], v[194:197], v[44:47]
	v_mfma_f32_16x16x32_bf16 v[40:43], v[186:189], v[194:197], v[40:43]
	v_mfma_f32_16x16x32_bf16 v[28:31], v[178:181], v[202:205], v[28:31]
	v_mfma_f32_16x16x32_bf16 v[24:27], v[186:189], v[202:205], v[24:27]
	v_mfma_f32_16x16x32_bf16 v[12:15], v[178:181], v[210:213], v[12:15]
	v_mfma_f32_16x16x32_bf16 v[8:11], v[186:189], v[210:213], v[8:11]
	v_mfma_f32_16x16x32_bf16 v[4:7], v[178:181], v[218:221], v[4:7]
	v_mfma_f32_16x16x32_bf16 v[0:3], v[186:189], v[218:221], v[0:3]
	s_setprio 0
	s_barrier
	s_add_i32 s87, 0, 0x18000
	s_add_i32 s88, 0, 0x1c000
	v_add_u32_e32 v170, s87, v154
	v_add_u32_e32 v186, s88, v154
	ds_read_b128 v[158:161], v170
	ds_read_b128 v[162:165], v170 offset:1024
	ds_read_b128 v[166:169], v170 offset:2048
	ds_read_b128 v[170:173], v170 offset:3072
	ds_read_b128 v[174:177], v186
	ds_read_b128 v[178:181], v186 offset:1024
	ds_read_b128 v[182:185], v186 offset:2048
	ds_read_b128 v[186:189], v186 offset:3072
	s_add_u32 s56, s56, 0x80000
	s_addc_u32 s57, s57, 0
	s_mov_b32 m0, s29
	v_lshl_add_u64 v[222:223], s[56:57], 0, v[128:129]
	ds_read_b128 v[190:193], v157 offset:32768
	ds_read_b128 v[194:197], v157 offset:33792
	ds_read_b128 v[198:201], v157 offset:34816
	ds_read_b128 v[202:205], v157 offset:35840
	ds_read_b128 v[206:209], v157 offset:36864
	ds_read_b128 v[210:213], v157 offset:37888
	ds_read_b128 v[214:217], v157 offset:38912
	ds_read_b128 v[218:221], v157 offset:39936
	global_load_lds_dwordx4 v[222:223], off
	v_lshl_add_u64 v[222:223], s[56:57], 0, v[132:133]
	s_mov_b32 m0, s30
	s_nop 0
	global_load_lds_dwordx4 v[222:223], off
	s_waitcnt vmcnt(8)
	s_waitcnt lgkmcnt(0)
	s_barrier
	s_setprio 1
	s_waitcnt lgkmcnt(0)
	v_mfma_f32_16x16x32_bf16 v[124:127], v[158:161], v[190:193], v[124:127]
	v_mfma_f32_16x16x32_bf16 v[120:123], v[166:169], v[190:193], v[120:123]
	v_mfma_f32_16x16x32_bf16 v[116:119], v[158:161], v[198:201], v[116:119]
	v_mfma_f32_16x16x32_bf16 v[112:115], v[166:169], v[198:201], v[112:115]
	v_mfma_f32_16x16x32_bf16 v[100:103], v[158:161], v[206:209], v[100:103]
	v_mfma_f32_16x16x32_bf16 v[96:99], v[166:169], v[206:209], v[96:99]
	v_mfma_f32_16x16x32_bf16 v[84:87], v[158:161], v[214:217], v[84:87]
	v_mfma_f32_16x16x32_bf16 v[80:83], v[166:169], v[214:217], v[80:83]
	v_mfma_f32_16x16x32_bf16 v[124:127], v[162:165], v[194:197], v[124:127]
	v_mfma_f32_16x16x32_bf16 v[120:123], v[170:173], v[194:197], v[120:123]
	v_mfma_f32_16x16x32_bf16 v[116:119], v[162:165], v[202:205], v[116:119]
	v_mfma_f32_16x16x32_bf16 v[112:115], v[170:173], v[202:205], v[112:115]
	v_mfma_f32_16x16x32_bf16 v[100:103], v[162:165], v[210:213], v[100:103]
	v_mfma_f32_16x16x32_bf16 v[96:99], v[170:173], v[210:213], v[96:99]
	v_mfma_f32_16x16x32_bf16 v[84:87], v[162:165], v[218:221], v[84:87]
	v_mfma_f32_16x16x32_bf16 v[80:83], v[170:173], v[218:221], v[80:83]
	v_mfma_f32_16x16x32_bf16 v[108:111], v[174:177], v[190:193], v[108:111]
	v_mfma_f32_16x16x32_bf16 v[104:107], v[182:185], v[190:193], v[104:107]
	v_mfma_f32_16x16x32_bf16 v[92:95], v[174:177], v[198:201], v[92:95]
	v_mfma_f32_16x16x32_bf16 v[88:91], v[182:185], v[198:201], v[88:91]
	v_mfma_f32_16x16x32_bf16 v[76:79], v[174:177], v[206:209], v[76:79]
	v_mfma_f32_16x16x32_bf16 v[72:75], v[182:185], v[206:209], v[72:75]
	v_mfma_f32_16x16x32_bf16 v[68:71], v[174:177], v[214:217], v[68:71]
	v_mfma_f32_16x16x32_bf16 v[64:67], v[182:185], v[214:217], v[64:67]
	v_mfma_f32_16x16x32_bf16 v[108:111], v[178:181], v[194:197], v[108:111]
	v_mfma_f32_16x16x32_bf16 v[104:107], v[186:189], v[194:197], v[104:107]
	v_mfma_f32_16x16x32_bf16 v[92:95], v[178:181], v[202:205], v[92:95]
	v_mfma_f32_16x16x32_bf16 v[88:91], v[186:189], v[202:205], v[88:91]
	v_mfma_f32_16x16x32_bf16 v[76:79], v[178:181], v[210:213], v[76:79]
	v_mfma_f32_16x16x32_bf16 v[72:75], v[186:189], v[210:213], v[72:75]
	v_mfma_f32_16x16x32_bf16 v[68:71], v[178:181], v[218:221], v[68:71]
	v_mfma_f32_16x16x32_bf16 v[64:67], v[186:189], v[218:221], v[64:67]
	s_setprio 0
	s_barrier
; #define PG8_LDA(dst, b, h) do { _Pragma("unroll") for (int m = 0; m < 4; ++m) _Pragma("unroll") for (int k = 0; k < 2; ++k) dst[m][k] = *(const LAS bf16x8*)(lds + PG8_SA(b, h) + aoff + m * 2048 + k * 1024); } while (0)
; #define PG8_MMA(ai, bj, At, Bt) do { __builtin_amdgcn_s_setprio(1); _Pragma("unroll") for (int m = 0; m < 4; ++m) _Pragma("unroll") for (int n = 0; n < 2; ++n) _Pragma("unroll") for (int k = 0; k < 2; ++k) \
;         acc[ai][bj][m][n] = __builtin_amdgcn_mfma_f32_16x16x32_bf16(Bt[n][k], At[m][k], acc[ai][bj][m][n], 0, 0, 0); __builtin_amdgcn_s_setprio(0); } while (0)
; #define PG8_WAIT_V(n) asm volatile("s_waitcnt vmcnt(" #n ")" ::: "memory")
; #define PG8_WAIT_L(n) asm volatile("s_waitcnt lgkmcnt(" #n ")" ::: "memory")
; #define PG8_BAR __builtin_amdgcn_s_barrier()
; #define PG8_SCHED __builtin_amdgcn_sched_barrier(0)
; __device__ __forceinline__ void gemm_phase(LAS unsigned char* lds, const GemmP& g) {
;     ...
;             PG8_LDA(At, 1, 1); PG8_STAGE(PG8_SB(1, 0), b3, voffB); PG8_STAGE(PG8_SB(1, 1), b3 + hstepB, voffB); PG8_STAGE(PG8_SA(1, 0), a3, voffA);
;             PG8_WAIT_V(8); PG8_WAIT_L(0); PG8_BAR; PG8_MMA(1, 0, At, B0); PG8_MMA(1, 1, At, B1); PG8_BAR; PG8_SCHED;
;         }
;         if (wr == 0) PG8_BAR;
	s_add_u32 s56, s54, 0x80
	s_addc_u32 s57, s55, 0
	s_add_i32 s87, s87, s20
	v_lshl_add_u64 v[222:223], s[56:57], 0, v[130:131]
	s_mov_b32 m0, s87
	ds_read_b128 v[190:193], v157 offset:49152
	ds_read_b128 v[194:197], v157 offset:50176
	ds_read_b128 v[198:201], v157 offset:51200
	ds_read_b128 v[202:205], v157 offset:52224
	ds_read_b128 v[206:209], v157 offset:53248
	ds_read_b128 v[210:213], v157 offset:54272
	ds_read_b128 v[214:217], v157 offset:55296
	ds_read_b128 v[218:221], v157 offset:56320
	global_load_lds_dwordx4 v[222:223], off
	s_add_i32 m0, s87, 0x2000
	s_add_u32 s54, s54, 0x80080
	v_lshl_add_u64 v[222:223], s[56:57], 0, v[134:135]
	s_addc_u32 s55, s55, 0
	s_add_i32 s56, s88, s20
	global_load_lds_dwordx4 v[222:223], off
	v_lshl_add_u64 v[222:223], s[54:55], 0, v[130:131]
	s_mov_b32 m0, s56
	s_nop 0
	global_load_lds_dwordx4 v[222:223], off
	v_lshl_add_u64 v[222:223], s[54:55], 0, v[134:135]
	s_add_i32 m0, s56, 0x2000
	s_nop 0
	global_load_lds_dwordx4 v[222:223], off
	v_lshl_add_u64 v[222:223], s[44:45], 0, v[128:129]
	s_mov_b32 m0, s59
	s_nop 0
	global_load_lds_dwordx4 v[222:223], off
	v_lshl_add_u64 v[222:223], s[44:45], 0, v[132:133]
	s_mov_b32 m0, s60
	s_nop 0
	global_load_lds_dwordx4 v[222:223], off
	s_waitcnt vmcnt(8)
	s_waitcnt lgkmcnt(0)
	s_barrier
	s_setprio 1
	s_waitcnt lgkmcnt(0)
	v_mfma_f32_16x16x32_bf16 v[60:63], v[158:161], v[190:193], v[60:63]
	v_mfma_f32_16x16x32_bf16 v[56:59], v[166:169], v[190:193], v[56:59]
	v_mfma_f32_16x16x32_bf16 v[52:55], v[158:161], v[198:201], v[52:55]
	v_mfma_f32_16x16x32_bf16 v[48:51], v[166:169], v[198:201], v[48:51]
	v_mfma_f32_16x16x32_bf16 v[36:39], v[158:161], v[206:209], v[36:39]
	v_mfma_f32_16x16x32_bf16 v[32:35], v[166:169], v[206:209], v[32:35]
	v_mfma_f32_16x16x32_bf16 v[20:23], v[158:161], v[214:217], v[20:23]
	v_mfma_f32_16x16x32_bf16 v[16:19], v[166:169], v[214:217], v[16:19]
	v_mfma_f32_16x16x32_bf16 v[60:63], v[162:165], v[194:197], v[60:63]
	v_mfma_f32_16x16x32_bf16 v[56:59], v[170:173], v[194:197], v[56:59]
	v_mfma_f32_16x16x32_bf16 v[52:55], v[162:165], v[202:205], v[52:55]
	v_mfma_f32_16x16x32_bf16 v[48:51], v[170:173], v[202:205], v[48:51]
	v_mfma_f32_16x16x32_bf16 v[36:39], v[162:165], v[210:213], v[36:39]
	v_mfma_f32_16x16x32_bf16 v[32:35], v[170:173], v[210:213], v[32:35]
	v_mfma_f32_16x16x32_bf16 v[20:23], v[162:165], v[218:221], v[20:23]
	v_mfma_f32_16x16x32_bf16 v[16:19], v[170:173], v[218:221], v[16:19]
	v_mfma_f32_16x16x32_bf16 v[44:47], v[174:177], v[190:193], v[44:47]
	v_mfma_f32_16x16x32_bf16 v[40:43], v[182:185], v[190:193], v[40:43]
	v_mfma_f32_16x16x32_bf16 v[28:31], v[174:177], v[198:201], v[28:31]
	v_mfma_f32_16x16x32_bf16 v[24:27], v[182:185], v[198:201], v[24:27]
	v_mfma_f32_16x16x32_bf16 v[12:15], v[174:177], v[206:209], v[12:15]
	v_mfma_f32_16x16x32_bf16 v[8:11], v[182:185], v[206:209], v[8:11]
	v_mfma_f32_16x16x32_bf16 v[4:7], v[174:177], v[214:217], v[4:7]
	v_mfma_f32_16x16x32_bf16 v[0:3], v[182:185], v[214:217], v[0:3]
	v_mfma_f32_16x16x32_bf16 v[44:47], v[178:181], v[194:197], v[44:47]
	v_mfma_f32_16x16x32_bf16 v[40:43], v[186:189], v[194:197], v[40:43]
	v_mfma_f32_16x16x32_bf16 v[28:31], v[178:181], v[202:205], v[28:31]
	v_mfma_f32_16x16x32_bf16 v[24:27], v[186:189], v[202:205], v[24:27]
	v_mfma_f32_16x16x32_bf16 v[12:15], v[178:181], v[210:213], v[12:15]
	v_mfma_f32_16x16x32_bf16 v[8:11], v[186:189], v[210:213], v[8:11]
	v_mfma_f32_16x16x32_bf16 v[4:7], v[178:181], v[218:221], v[4:7]
	v_mfma_f32_16x16x32_bf16 v[0:3], v[186:189], v[218:221], v[0:3]
	s_setprio 0
	s_barrier
	s_add_i32 s86, s86, 2
	s_add_u32 s70, s70, 0x100
	s_addc_u32 s71, s71, 0
	s_add_u32 s72, s72, 0x100
	s_addc_u32 s73, s73, 0
	s_add_u32 s42, s42, 0x100
	s_addc_u32 s43, s43, 0
	s_cmp_gt_u32 s86, 29
	s_cbranch_scc0 .LBB0_273
	s_and_b64 vcc, exec, s[8:9]
	s_cbranch_vccz .LBB0_276
	s_barrier

; __device__ __forceinline__ void gla_out_phase(const Params& P) {
;     const int tid = threadIdx.x, lane = tid & 63, wave = tid >> 6;
;     const bf16_t* proj = (const bf16_t*)(P.ws + WS_PROJ);
;     const float* of = (const float*)(P.ws + WS_X); const float* ob = of + (size_t)NTOK * 1024;
;     bf16_t* mix = (bf16_t*)(P.ws + WS_MIX);
;     const f32x4 gn = *(const f32x4*)(P.in[18] + lane * 4);
;     for (int idx = blockIdx.x * 8 + wave; idx < NTOK * 4; idx += gridDim.x * 8) {
;         const int row = idx >> 2, h = idx & 3; const size_t off = (size_t)row * 1024 + h * 256 + lane * 4;
;         const f32x4 o = *(const f32x4*)(of + off) + *(const f32x4*)(ob + off);
.LBB0_625:
	s_cmp_lt_i32 s24, 6
	s_cselect_b64 s[6:7], -1, 0
	s_and_b64 s[0:1], s[6:7], s[0:1]
	s_andn2_b64 vcc, exec, s[0:1]
	s_cbranch_vccnz .LBB0_630
	v_lshrrev_b32_e32 v6, 6, v224
	v_lshl_add_u32 v5, s22, 3, v6
	s_mov_b32 s0, 0x10000
	v_cmp_gt_i32_e32 vcc, s0, v5
	s_and_saveexec_b64 s[8:9], vcc
	s_cbranch_execz .LBB0_629
	v_lshlrev_b32_e32 v0, 2, v224
	s_waitcnt lgkmcnt(0)
	v_and_b32_e32 v4, 0xfc, v0
	v_lshlrev_b32_e32 v0, 2, v4
	global_load_dwordx4 v[0:3], v0, s[40:41]
	v_mbcnt_lo_u32_b32 v8, -1, 0
	v_mbcnt_hi_u32_b32 v8, -1, v8
	v_and_b32_e32 v9, 64, v8
	v_add_u32_e32 v9, 64, v9
	v_xor_b32_e32 v10, 1, v8
	v_cmp_lt_i32_e32 vcc, v10, v9
	s_add_u32 s10, s50, 0xf418000
	v_mov_b32_e32 v7, 0
	v_cndmask_b32_e32 v10, v8, v10, vcc
	v_lshlrev_b32_e32 v12, 2, v10
	v_xor_b32_e32 v10, 2, v8
	v_cmp_lt_i32_e32 vcc, v10, v9
	v_lshlrev_b32_e32 v6, 8, v6
	s_addc_u32 s11, s51, 0
	v_cndmask_b32_e32 v10, v8, v10, vcc
	v_lshlrev_b32_e32 v13, 2, v10
	v_xor_b32_e32 v10, 4, v8
	v_cmp_lt_i32_e32 vcc, v10, v9
	s_lshl_b32 s14, s26, 3
	v_lshl_add_u32 v18, s22, 11, v6
	v_cndmask_b32_e32 v10, v8, v10, vcc
	v_lshlrev_b32_e32 v14, 2, v10
	v_xor_b32_e32 v10, 8, v8
	v_cmp_lt_i32_e32 vcc, v10, v9
	s_lshl_b32 s15, s26, 11
	s_mov_b64 s[12:13], 0
	v_cndmask_b32_e32 v10, v8, v10, vcc
	v_lshlrev_b32_e32 v15, 2, v10
	v_xor_b32_e32 v10, 16, v8
	v_cmp_lt_i32_e32 vcc, v10, v9
	v_mov_b32_e32 v19, 0x358637bd
	s_mov_b32 s16, 0x800000
	v_cndmask_b32_e32 v10, v8, v10, vcc
	v_lshlrev_b32_e32 v16, 2, v10
	v_xor_b32_e32 v10, 32, v8
	v_cmp_lt_i32_e32 vcc, v10, v9
	s_movk_i32 s17, 0x2600
	v_mov_b32_e32 v11, v7
	v_cndmask_b32_e32 v8, v8, v10, vcc
	v_lshlrev_b32_e32 v17, 2, v8
	v_mov_b64_e32 v[8:9], s[50:51]
	v_lshlrev_b32_e32 v10, 1, v4
	s_mov_b32 s18, 0x1bc19000
	s_movk_i32 s19, 0xea00
	s_mov_b32 s20, 0xffff
	v_mov_b32_e32 v87, v7
	v_ashrrev_i32_e32 v68, 2, v5
	v_ashrrev_i32_e32 v69, 31, v68
	v_and_b32_e32 v76, 0x300, v18
	v_mad_i64_i32 v[70:71], s[0:1], v68, s17, v[8:9]
	v_lshlrev_b64 v[72:73], 10, v[68:69]
	v_lshlrev_b32_e32 v86, 1, v76
	v_mad_i64_i32 v[68:69], s[0:1], v68, s19, v[70:71]
	v_or_b32_e32 v72, v72, v76
	v_add_u32_e32 v5, s14, v5
	v_lshl_add_u64 v[74:75], v[70:71], 0, v[86:87]
	v_lshl_add_u64 v[68:69], v[68:69], 0, v[86:87]
	v_or_b32_e32 v72, v72, v4
	v_cmp_lt_i32_e32 vcc, s20, v5
	v_lshl_add_u64 v[70:71], v[74:75], 0, v[10:11]
	v_lshl_add_u64 v[78:79], v[68:69], 0, v[10:11]
	v_lshlrev_b64 v[68:69], 2, v[72:73]
	s_or_b64 s[12:13], vcc, s[12:13]
	v_add_co_u32_e32 v76, vcc, s18, v70
	v_lshl_add_u64 v[80:81], s[36:37], 0, v[68:69]
	s_nop 0
	v_addc_co_u32_e32 v77, vcc, 0, v71, vcc
	v_lshl_add_u64 v[82:83], s[10:11], 0, v[68:69]
	global_load_dwordx4 v[68:71], v[80:81], off
	global_load_dwordx4 v[72:75], v[82:83], off
	global_load_dwordx2 v[84:85], v[76:77], off offset:3072
	v_add_u32_e32 v18, s15, v18
	s_waitcnt vmcnt(0)
; __device__ __forceinline__ unsigned cvt_pk_bf16(float lo, float hi) { const f32x2 v = {lo, hi}; const bf16v2_t b = __builtin_convertvector(v, bf16v2_t); return __builtin_bit_cast(unsigned, b); }
; __device__ __forceinline__ float silu_f(float x) { return x / (1.f + __expf(-x)); }
; __device__ __forceinline__ void gla_out_phase(const Params& P) {
;     ...
;     for (int idx = blockIdx.x * 8 + wave; idx < NTOK * 4; idx += gridDim.x * 8) {
;         const int row = idx >> 2, h = idx & 3; const size_t off = (size_t)row * 1024 + h * 256 + lane * 4;
;         const f32x4 o = *(const f32x4*)(of + off) + *(const f32x4*)(ob + off);
;         const float ss = wave_sum((o[0] * o[0] + o[1] * o[1]) + (o[2] * o[2] + o[3] * o[3]));
;         const float rstd = rsqrtf(ss * (1.f / 256.f) + 1e-6f);
;         const u32x2 gw = *(const u32x2*)(proj + (size_t)row * INCP + C_BG + h * 256 + lane * 4);
;         const float g0 = __uint_as_float(gw.x << 16), g1 = __uint_as_float(gw.x & 0xffff0000u), g2 = __uint_as_float(gw.y << 16), g3 = __uint_as_float(gw.y & 0xffff0000u);
;         u32x2 w; w.x = cvt_pk_bf16(o[0] * rstd * gn[0] * silu_f(g0), o[1] * rstd * gn[1] * silu_f(g1)); w.y = cvt_pk_bf16(o[2] * rstd * gn[2] * silu_f(g2), o[3] * rstd * gn[3] * silu_f(g3));
;         *(u32x2*)(mix + (size_t)row * D + 1024 + h * 256 + lane * 4) = w;
.LBB0_628:
	s_waitcnt vmcnt(1)
	v_mov_b32_e32 v20, v68
	v_mov_b32_e32 v21, v69
	v_mov_b32_e32 v22, v70
	v_mov_b32_e32 v23, v71
	v_mov_b32_e32 v24, v72
	v_mov_b32_e32 v25, v73
	v_mov_b32_e32 v26, v74
	v_mov_b32_e32 v27, v75
	v_mov_b32_e32 v36, v84
	v_mov_b32_e32 v37, v85
	v_mov_b32_e32 v30, v78
	v_mov_b32_e32 v31, v79
	v_ashrrev_i32_e32 v68, 2, v5
	v_ashrrev_i32_e32 v69, 31, v68
	v_and_b32_e32 v76, 0x300, v18
	v_mad_i64_i32 v[70:71], s[0:1], v68, s17, v[8:9]
	v_lshlrev_b64 v[72:73], 10, v[68:69]
	v_lshlrev_b32_e32 v86, 1, v76
	v_mad_i64_i32 v[68:69], s[0:1], v68, s19, v[70:71]
	v_or_b32_e32 v72, v72, v76
	v_add_u32_e32 v5, s14, v5
	v_lshl_add_u64 v[74:75], v[70:71], 0, v[86:87]
	v_lshl_add_u64 v[68:69], v[68:69], 0, v[86:87]
	v_or_b32_e32 v72, v72, v4
	v_cmp_lt_i32_e32 vcc, s20, v5
	v_lshl_add_u64 v[70:71], v[74:75], 0, v[10:11]
	v_lshl_add_u64 v[78:79], v[68:69], 0, v[10:11]
	v_lshlrev_b64 v[68:69], 2, v[72:73]
	s_mov_b64 s[98:99], vcc
	v_add_co_u32_e32 v76, vcc, s18, v70
	v_lshl_add_u64 v[80:81], s[36:37], 0, v[68:69]
	s_nop 0
	v_addc_co_u32_e32 v77, vcc, 0, v71, vcc
	v_lshl_add_u64 v[82:83], s[10:11], 0, v[68:69]
	global_load_dwordx4 v[68:71], v[80:81], off
	global_load_dwordx4 v[72:75], v[82:83], off
	global_load_dwordx2 v[84:85], v[76:77], off offset:3072
	v_add_u32_e32 v18, s15, v18
	v_pk_add_f32 v[22:23], v[22:23], v[26:27]
	v_lshlrev_b32_e32 v6, 16, v36
	v_and_b32_e32 v36, 0xffff0000, v36
	v_lshlrev_b32_e32 v38, 16, v37
	v_and_b32_e32 v37, 0xffff0000, v37
	v_mul_f32_e32 v28, 0xbfb8aa3b, v6
	v_mul_f32_e32 v29, 0xbfb8aa3b, v36
	v_mul_f32_e32 v32, 0xbfb8aa3b, v38
	v_mul_f32_e32 v33, 0xbfb8aa3b, v37
	v_pk_add_f32 v[20:21], v[20:21], v[24:25]
	v_exp_f32_e32 v24, v28
	v_exp_f32_e32 v25, v29
	v_exp_f32_e32 v26, v32
	v_exp_f32_e32 v27, v33
	v_pk_mul_f32 v[28:29], v[22:23], v[22:23]
	v_pk_mul_f32 v[32:33], v[20:21], v[20:21]
	v_pk_add_f32 v[24:25], v[24:25], 1.0 op_sel_hi:[1,0]
	v_pk_mov_b32 v[34:35], v[32:33], v[28:29] op_sel:[1,0]
	v_mov_b32_e32 v33, v29
	v_pk_add_f32 v[28:29], v[34:35], v[32:33]
	v_pk_add_f32 v[26:27], v[26:27], 1.0 op_sel_hi:[1,0]
	v_add_f32_e32 v28, v28, v29
	ds_bpermute_b32 v29, v12, v28
	v_div_scale_f32 v32, s[0:1], v25, v25, v36
	v_div_scale_f32 v34, s[0:1], v24, v24, v6
	v_div_scale_f32 v39, s[2:3], v27, v27, v37
	v_rcp_f32_e32 v43, v32
	v_rcp_f32_e32 v44, v34
	v_rcp_f32_e32 v45, v39
	v_div_scale_f32 v41, s[4:5], v26, v26, v38
	s_waitcnt lgkmcnt(0)
	v_add_f32_e32 v28, v28, v29
	v_rcp_f32_e32 v46, v41
	v_fma_f32 v29, -v32, v43, 1.0
	v_fma_f32 v47, -v34, v44, 1.0
	v_fma_f32 v48, -v39, v45, 1.0
	ds_bpermute_b32 v50, v13, v28
	v_div_scale_f32 v33, vcc, v36, v25, v36
	v_div_scale_f32 v35, s[0:1], v6, v24, v6
	v_div_scale_f32 v40, s[2:3], v37, v27, v37
	v_fmac_f32_e32 v43, v29, v43
	v_fmac_f32_e32 v44, v47, v44
	v_fmac_f32_e32 v45, v48, v45
	v_mul_f32_e32 v29, v33, v43
	v_mul_f32_e32 v47, v35, v44
	v_mul_f32_e32 v48, v40, v45
	v_fma_f32 v51, -v32, v29, v33
	v_fma_f32 v52, -v34, v47, v35
	v_fma_f32 v53, -v39, v48, v40
	v_fma_f32 v49, -v41, v46, 1.0
	v_fmac_f32_e32 v29, v51, v43
	v_fmac_f32_e32 v47, v52, v44
	v_fmac_f32_e32 v48, v53, v45
	v_div_scale_f32 v42, s[4:5], v38, v26, v38
	v_fmac_f32_e32 v46, v49, v46
	v_fma_f32 v32, -v32, v29, v33
	v_fma_f32 v33, -v34, v47, v35
	v_fma_f32 v34, -v39, v48, v40
	s_waitcnt lgkmcnt(0)
	v_add_f32_e32 v39, v28, v50
	v_mul_f32_e32 v49, v42, v46
	v_div_fmas_f32 v28, v32, v43, v29
	ds_bpermute_b32 v32, v14, v39
	v_fma_f32 v54, -v41, v49, v42
	s_mov_b64 vcc, s[0:1]
	v_fmac_f32_e32 v49, v54, v46
	v_div_fixup_f32 v25, v28, v25, v36
	v_div_fmas_f32 v28, v33, v44, v47
	s_mov_b64 vcc, s[2:3]
	v_fma_f32 v35, -v41, v49, v42
	v_div_fixup_f32 v24, v28, v24, v6
	v_div_fmas_f32 v6, v34, v45, v48
	s_mov_b64 vcc, s[4:5]
	v_div_fixup_f32 v27, v6, v27, v37
	v_div_fmas_f32 v6, v35, v46, v49
	v_div_fixup_f32 v26, v6, v26, v38
	s_waitcnt lgkmcnt(0)
	v_add_f32_e32 v6, v39, v32
	v_add_co_u32_e32 v28, vcc, 0x17c18000, v30
	ds_bpermute_b32 v30, v15, v6
	s_nop 0
	v_addc_co_u32_e32 v29, vcc, 0, v31, vcc
	s_waitcnt lgkmcnt(0)
	v_add_f32_e32 v6, v6, v30
	ds_bpermute_b32 v30, v16, v6
	s_waitcnt lgkmcnt(0)
	v_add_f32_e32 v6, v6, v30
	ds_bpermute_b32 v30, v17, v6
	s_waitcnt lgkmcnt(0)
	v_add_f32_e32 v6, v6, v30
	v_fmamk_f32 v6, v6, 0x3b800000, v19
	v_mul_f32_e32 v30, 0x4b800000, v6
	v_cmp_gt_f32_e32 vcc, s16, v6
	s_nop 1
	v_cndmask_b32_e32 v6, v6, v30, vcc
	v_rsq_f32_e32 v6, v6
	s_nop 0
	v_mul_f32_e32 v30, 0x45800000, v6
	v_cndmask_b32_e32 v6, v6, v30, vcc
	v_pk_mul_f32 v[20:21], v[20:21], v[6:7] op_sel_hi:[1,0]
	v_pk_mul_f32 v[22:23], v[22:23], v[6:7] op_sel_hi:[1,0]
	v_pk_mul_f32 v[20:21], v[0:1], v[20:21]
	v_pk_mul_f32 v[22:23], v[2:3], v[22:23]
	v_pk_mul_f32 v[20:21], v[24:25], v[20:21]
	v_pk_mul_f32 v[22:23], v[26:27], v[22:23]
	v_cvt_pk_bf16_f32 v20, v20, v21
	v_cvt_pk_bf16_f32 v21, v22, v23
	global_store_dwordx2 v[28:29], v[20:21], off offset:2048
	s_andn2_b64 exec, exec, s[12:13]
	s_or_b64 s[12:13], s[12:13], s[98:99]
	s_cbranch_execnz .LBB0_628

; #define PG8_LDA(dst, b, h) do { _Pragma("unroll") for (int m = 0; m < 4; ++m) _Pragma("unroll") for (int k = 0; k < 2; ++k) dst[m][k] = *(const LAS bf16x8*)(lds + PG8_SA(b, h) + aoff + m * 2048 + k * 1024); } while (0)
; #define PG8_LDB(dst, b, h) do { _Pragma("unroll") for (int n = 0; n < 2; ++n) _Pragma("unroll") for (int k = 0; k < 2; ++k) dst[n][k] = *(const LAS bf16x8*)(lds + PG8_SB(b, h) + boff + n * 2048 + k * 1024); } while (0)
; #define PG8_MMA(ai, bj, At, Bt) do { __builtin_amdgcn_s_setprio(1); _Pragma("unroll") for (int m = 0; m < 4; ++m) _Pragma("unroll") for (int n = 0; n < 2; ++n) _Pragma("unroll") for (int k = 0; k < 2; ++k) \
;         acc[ai][bj][m][n] = __builtin_amdgcn_mfma_f32_16x16x32_bf16(Bt[n][k], At[m][k], acc[ai][bj][m][n], 0, 0, 0); __builtin_amdgcn_s_setprio(0); } while (0)
; #define PG8_WAIT_V(n) asm volatile("s_waitcnt vmcnt(" #n ")" ::: "memory")
; #define PG8_WAIT_L(n) asm volatile("s_waitcnt lgkmcnt(" #n ")" ::: "memory")
; #define PG8_BAR __builtin_amdgcn_s_barrier()
; #define PG8_SCHED __builtin_amdgcn_sched_barrier(0)
; __device__ __forceinline__ void gemm_phase(LAS unsigned char* lds, const GemmP& g) {
;     ...
;         for (int t = 0; t < nt; t += 2) {
;             const bool last = (t == nt - 2);
;             const char* a1 = cA + (size_t)(t + 1) * kstep;
;             const char* a2 = last ? nA : cA + (size_t)(t + 2) * kstep; const char* b2 = last ? nB : cB + (size_t)(t + 2) * kstep;
;             const char* a3 = a2 + kstep; const char* b3 = b2 + kstep;
;             PG8_LDB(B0, 0, 0); PG8_LDB(B1, 0, 1); PG8_SCHED; PG8_LDA(At, 0, 0); PG8_STAGE(PG8_SA(1, 1), a1 + hstepA, voffA);
;             PG8_WAIT_V(8); PG8_WAIT_L(0); PG8_BAR; PG8_MMA(0, 0, At, B0); PG8_MMA(0, 1, At, B1); PG8_BAR; PG8_SCHED;
;             PG8_LDA(At, 0, 1); PG8_STAGE(PG8_SB(0, 0), b2, voffB); PG8_STAGE(PG8_SB(0, 1), b2 + hstepB, voffB); PG8_STAGE(PG8_SA(0, 0), a2, voffA);
;             PG8_WAIT_V(8); PG8_WAIT_L(0); PG8_BAR; PG8_MMA(1, 0, At, B0); PG8_MMA(1, 1, At, B1); PG8_BAR; PG8_SCHED;
.LBB0_702:
	ds_read_b128 v[128:131], v164
	ds_read_b128 v[132:135], v164 offset:1024
	ds_read_b128 v[136:139], v164 offset:2048
	ds_read_b128 v[168:171], v164 offset:3072
	ds_read_b128 v[172:175], v165
	ds_read_b128 v[176:179], v165 offset:1024
	ds_read_b128 v[180:183], v165 offset:2048
	ds_read_b128 v[184:187], v165 offset:3072
	s_cmp_eq_u32 s72, 28
	s_cselect_b32 s54, s17, s20
	s_cselect_b32 s55, s9, s21
	s_cselect_b32 s44, s19, s30
	s_cselect_b32 s45, s11, s31
	s_add_u32 s42, s54, 0x80
	s_addc_u32 s43, s55, 0
	v_lshl_add_u64 v[162:163], s[40:41], 0, v[140:141]
	s_add_i32 m0, s56, 0xc000
	ds_read_b128 v[188:191], v166
	ds_read_b128 v[192:195], v166 offset:1024
	ds_read_b128 v[196:199], v166 offset:2048
	ds_read_b128 v[200:203], v166 offset:3072
	ds_read_b128 v[204:207], v166 offset:4096
	ds_read_b128 v[208:211], v166 offset:5120
	ds_read_b128 v[212:215], v166 offset:6144
	ds_read_b128 v[216:219], v166 offset:7168
	global_load_lds_dwordx4 v[162:163], off
	v_lshl_add_u64 v[162:163], s[40:41], 0, v[142:143]
	s_add_i32 m0, s56, 0xe000
	s_nop 0
	global_load_lds_dwordx4 v[162:163], off
	s_waitcnt vmcnt(8)
	s_waitcnt lgkmcnt(0)
	s_barrier
	s_setprio 1
	s_waitcnt lgkmcnt(0)
	v_mfma_f32_16x16x32_bf16 v[124:127], v[128:131], v[188:191], v[124:127]
	v_mfma_f32_16x16x32_bf16 v[120:123], v[136:139], v[188:191], v[120:123]
	v_mfma_f32_16x16x32_bf16 v[108:111], v[128:131], v[196:199], v[108:111]
	v_mfma_f32_16x16x32_bf16 v[104:107], v[136:139], v[196:199], v[104:107]
	v_mfma_f32_16x16x32_bf16 v[96:99], v[128:131], v[204:207], v[96:99]
	v_mfma_f32_16x16x32_bf16 v[88:91], v[136:139], v[204:207], v[88:91]
	v_mfma_f32_16x16x32_bf16 v[80:83], v[128:131], v[212:215], v[80:83]
	v_mfma_f32_16x16x32_bf16 v[72:75], v[136:139], v[212:215], v[72:75]
	v_mfma_f32_16x16x32_bf16 v[124:127], v[132:135], v[192:195], v[124:127]
	v_mfma_f32_16x16x32_bf16 v[120:123], v[168:171], v[192:195], v[120:123]
	v_mfma_f32_16x16x32_bf16 v[108:111], v[132:135], v[200:203], v[108:111]
	v_mfma_f32_16x16x32_bf16 v[104:107], v[168:171], v[200:203], v[104:107]
	v_mfma_f32_16x16x32_bf16 v[96:99], v[132:135], v[208:211], v[96:99]
	v_mfma_f32_16x16x32_bf16 v[88:91], v[168:171], v[208:211], v[88:91]
	v_mfma_f32_16x16x32_bf16 v[80:83], v[132:135], v[216:219], v[80:83]
	v_mfma_f32_16x16x32_bf16 v[72:75], v[168:171], v[216:219], v[72:75]
	v_mfma_f32_16x16x32_bf16 v[116:119], v[172:175], v[188:191], v[116:119]
	v_mfma_f32_16x16x32_bf16 v[112:115], v[180:183], v[188:191], v[112:115]
	v_mfma_f32_16x16x32_bf16 v[100:103], v[172:175], v[196:199], v[100:103]
	v_mfma_f32_16x16x32_bf16 v[92:95], v[180:183], v[196:199], v[92:95]
	v_mfma_f32_16x16x32_bf16 v[84:87], v[172:175], v[204:207], v[84:87]
	v_mfma_f32_16x16x32_bf16 v[76:79], v[180:183], v[204:207], v[76:79]
	v_mfma_f32_16x16x32_bf16 v[68:71], v[172:175], v[212:215], v[68:71]
	v_mfma_f32_16x16x32_bf16 v[64:67], v[180:183], v[212:215], v[64:67]
	v_mfma_f32_16x16x32_bf16 v[116:119], v[176:179], v[192:195], v[116:119]
	v_mfma_f32_16x16x32_bf16 v[112:115], v[184:187], v[192:195], v[112:115]
	v_mfma_f32_16x16x32_bf16 v[100:103], v[176:179], v[200:203], v[100:103]
	v_mfma_f32_16x16x32_bf16 v[92:95], v[184:187], v[200:203], v[92:95]
	v_mfma_f32_16x16x32_bf16 v[84:87], v[176:179], v[208:211], v[84:87]
	v_mfma_f32_16x16x32_bf16 v[76:79], v[184:187], v[208:211], v[76:79]
	v_mfma_f32_16x16x32_bf16 v[68:71], v[176:179], v[216:219], v[68:71]
	v_mfma_f32_16x16x32_bf16 v[64:67], v[184:187], v[216:219], v[64:67]
	s_setprio 0
	s_barrier
	s_add_i32 s73, s70, s33
	v_lshl_add_u64 v[162:163], s[44:45], 0, v[140:141]
	s_mov_b32 m0, s73
	ds_read_b128 v[188:191], v166 offset:16384
	ds_read_b128 v[192:195], v166 offset:17408
	ds_read_b128 v[196:199], v166 offset:18432
	ds_read_b128 v[200:203], v166 offset:19456
	ds_read_b128 v[204:207], v166 offset:20480
	ds_read_b128 v[208:211], v166 offset:21504
	ds_read_b128 v[212:215], v166 offset:22528
	ds_read_b128 v[216:219], v166 offset:23552
	global_load_lds_dwordx4 v[162:163], off
	s_add_i32 m0, s73, 0x2000
	s_add_u32 s74, s44, 0x80000
	v_lshl_add_u64 v[162:163], s[44:45], 0, v[142:143]
	s_addc_u32 s75, s45, 0
	s_add_i32 s73, s71, s33
	global_load_lds_dwordx4 v[162:163], off
	v_lshl_add_u64 v[162:163], s[74:75], 0, v[140:141]
	s_mov_b32 m0, s73
	s_nop 0
	global_load_lds_dwordx4 v[162:163], off
	v_lshl_add_u64 v[162:163], s[74:75], 0, v[142:143]
	s_add_i32 m0, s73, 0x2000
	s_nop 0
	global_load_lds_dwordx4 v[162:163], off
	v_lshl_add_u64 v[162:163], s[54:55], 0, v[140:141]
	s_mov_b32 m0, s56
	s_nop 0
	global_load_lds_dwordx4 v[162:163], off
	v_lshl_add_u64 v[162:163], s[54:55], 0, v[142:143]
	s_mov_b32 m0, s57
	s_nop 0
	global_load_lds_dwordx4 v[162:163], off
	s_waitcnt vmcnt(8)
	s_waitcnt lgkmcnt(0)
	s_barrier
; #define PG8_LDA(dst, b, h) do { _Pragma("unroll") for (int m = 0; m < 4; ++m) _Pragma("unroll") for (int k = 0; k < 2; ++k) dst[m][k] = *(const LAS bf16x8*)(lds + PG8_SA(b, h) + aoff + m * 2048 + k * 1024); } while (0)
; #define PG8_LDB(dst, b, h) do { _Pragma("unroll") for (int n = 0; n < 2; ++n) _Pragma("unroll") for (int k = 0; k < 2; ++k) dst[n][k] = *(const LAS bf16x8*)(lds + PG8_SB(b, h) + boff + n * 2048 + k * 1024); } while (0)
; #define PG8_MMA(ai, bj, At, Bt) do { __builtin_amdgcn_s_setprio(1); _Pragma("unroll") for (int m = 0; m < 4; ++m) _Pragma("unroll") for (int n = 0; n < 2; ++n) _Pragma("unroll") for (int k = 0; k < 2; ++k) \
;         acc[ai][bj][m][n] = __builtin_amdgcn_mfma_f32_16x16x32_bf16(Bt[n][k], At[m][k], acc[ai][bj][m][n], 0, 0, 0); __builtin_amdgcn_s_setprio(0); } while (0)
; #define PG8_WAIT_V(n) asm volatile("s_waitcnt vmcnt(" #n ")" ::: "memory")
; #define PG8_WAIT_L(n) asm volatile("s_waitcnt lgkmcnt(" #n ")" ::: "memory")
; #define PG8_BAR __builtin_amdgcn_s_barrier()
; #define PG8_SCHED __builtin_amdgcn_sched_barrier(0)
; __device__ __forceinline__ void gemm_phase(LAS unsigned char* lds, const GemmP& g) {
;     ...
;             PG8_WAIT_V(8); PG8_WAIT_L(0); PG8_BAR; PG8_MMA(1, 0, At, B0); PG8_MMA(1, 1, At, B1); PG8_BAR; PG8_SCHED;
;             PG8_LDB(B0, 1, 0); PG8_LDB(B1, 1, 1); PG8_SCHED; PG8_LDA(At, 1, 0); PG8_STAGE(PG8_SA(0, 1), a2 + hstepA, voffA);
;             PG8_WAIT_V(8); PG8_WAIT_L(0); PG8_BAR; PG8_MMA(0, 0, At, B0); PG8_MMA(0, 1, At, B1); PG8_BAR; PG8_SCHED;
	s_setprio 1
	s_waitcnt lgkmcnt(0)
	v_mfma_f32_16x16x32_bf16 v[60:63], v[128:131], v[188:191], v[60:63]
	v_mfma_f32_16x16x32_bf16 v[56:59], v[136:139], v[188:191], v[56:59]
	v_mfma_f32_16x16x32_bf16 v[48:51], v[128:131], v[196:199], v[48:51]
	v_mfma_f32_16x16x32_bf16 v[40:43], v[136:139], v[196:199], v[40:43]
	v_mfma_f32_16x16x32_bf16 v[32:35], v[128:131], v[204:207], v[32:35]
	v_mfma_f32_16x16x32_bf16 v[24:27], v[136:139], v[204:207], v[24:27]
	v_mfma_f32_16x16x32_bf16 v[16:19], v[128:131], v[212:215], v[16:19]
	v_mfma_f32_16x16x32_bf16 v[8:11], v[136:139], v[212:215], v[8:11]
	v_mfma_f32_16x16x32_bf16 v[60:63], v[132:135], v[192:195], v[60:63]
	v_mfma_f32_16x16x32_bf16 v[56:59], v[168:171], v[192:195], v[56:59]
	v_mfma_f32_16x16x32_bf16 v[48:51], v[132:135], v[200:203], v[48:51]
	v_mfma_f32_16x16x32_bf16 v[40:43], v[168:171], v[200:203], v[40:43]
	v_mfma_f32_16x16x32_bf16 v[32:35], v[132:135], v[208:211], v[32:35]
	v_mfma_f32_16x16x32_bf16 v[24:27], v[168:171], v[208:211], v[24:27]
	v_mfma_f32_16x16x32_bf16 v[16:19], v[132:135], v[216:219], v[16:19]
	v_mfma_f32_16x16x32_bf16 v[8:11], v[168:171], v[216:219], v[8:11]
	v_mfma_f32_16x16x32_bf16 v[52:55], v[172:175], v[188:191], v[52:55]
	v_mfma_f32_16x16x32_bf16 v[44:47], v[180:183], v[188:191], v[44:47]
	v_mfma_f32_16x16x32_bf16 v[36:39], v[172:175], v[196:199], v[36:39]
	v_mfma_f32_16x16x32_bf16 v[28:31], v[180:183], v[196:199], v[28:31]
	v_mfma_f32_16x16x32_bf16 v[20:23], v[172:175], v[204:207], v[20:23]
	v_mfma_f32_16x16x32_bf16 v[12:15], v[180:183], v[204:207], v[12:15]
	v_mfma_f32_16x16x32_bf16 v[4:7], v[172:175], v[212:215], v[4:7]
	v_mfma_f32_16x16x32_bf16 v[0:3], v[180:183], v[212:215], v[0:3]
	v_mfma_f32_16x16x32_bf16 v[52:55], v[176:179], v[192:195], v[52:55]
	v_mfma_f32_16x16x32_bf16 v[44:47], v[184:187], v[192:195], v[44:47]
	v_mfma_f32_16x16x32_bf16 v[36:39], v[176:179], v[200:203], v[36:39]
	v_mfma_f32_16x16x32_bf16 v[28:31], v[184:187], v[200:203], v[28:31]
	v_mfma_f32_16x16x32_bf16 v[20:23], v[176:179], v[208:211], v[20:23]
	v_mfma_f32_16x16x32_bf16 v[12:15], v[184:187], v[208:211], v[12:15]
	v_mfma_f32_16x16x32_bf16 v[4:7], v[176:179], v[216:219], v[4:7]
	v_mfma_f32_16x16x32_bf16 v[0:3], v[184:187], v[216:219], v[0:3]
	s_setprio 0
	s_barrier
	s_add_i32 s73, 0, 0x18000
	v_add_u32_e32 v162, s73, v145
	s_add_i32 s74, 0, 0x1c000
	ds_read_b128 v[128:131], v162
	ds_read_b128 v[132:135], v162 offset:1024
	ds_read_b128 v[136:139], v162 offset:2048
	ds_read_b128 v[168:171], v162 offset:3072
	v_add_u32_e32 v162, s74, v145
	ds_read_b128 v[172:175], v162
	ds_read_b128 v[176:179], v162 offset:1024
	ds_read_b128 v[180:183], v162 offset:2048
	ds_read_b128 v[184:187], v162 offset:3072
	s_add_u32 s54, s54, 0x80000
	s_addc_u32 s55, s55, 0
	s_mov_b32 m0, s58
	v_lshl_add_u64 v[162:163], s[54:55], 0, v[140:141]
	ds_read_b128 v[188:191], v166 offset:32768
	ds_read_b128 v[192:195], v166 offset:33792
	ds_read_b128 v[196:199], v166 offset:34816
	ds_read_b128 v[200:203], v166 offset:35840
	ds_read_b128 v[204:207], v166 offset:36864
	ds_read_b128 v[208:211], v166 offset:37888
	ds_read_b128 v[212:215], v166 offset:38912
	ds_read_b128 v[216:219], v166 offset:39936
	global_load_lds_dwordx4 v[162:163], off
	v_lshl_add_u64 v[162:163], s[54:55], 0, v[142:143]
	s_mov_b32 m0, s59
	s_nop 0
	global_load_lds_dwordx4 v[162:163], off
	s_waitcnt vmcnt(8)
	s_waitcnt lgkmcnt(0)
	s_barrier
	s_setprio 1
	s_waitcnt lgkmcnt(0)
	v_mfma_f32_16x16x32_bf16 v[124:127], v[128:131], v[188:191], v[124:127]
	v_mfma_f32_16x16x32_bf16 v[120:123], v[136:139], v[188:191], v[120:123]
	v_mfma_f32_16x16x32_bf16 v[108:111], v[128:131], v[196:199], v[108:111]
	v_mfma_f32_16x16x32_bf16 v[104:107], v[136:139], v[196:199], v[104:107]
	v_mfma_f32_16x16x32_bf16 v[96:99], v[128:131], v[204:207], v[96:99]
	v_mfma_f32_16x16x32_bf16 v[88:91], v[136:139], v[204:207], v[88:91]
	v_mfma_f32_16x16x32_bf16 v[80:83], v[128:131], v[212:215], v[80:83]
	v_mfma_f32_16x16x32_bf16 v[72:75], v[136:139], v[212:215], v[72:75]
	v_mfma_f32_16x16x32_bf16 v[124:127], v[132:135], v[192:195], v[124:127]
	v_mfma_f32_16x16x32_bf16 v[120:123], v[168:171], v[192:195], v[120:123]
	v_mfma_f32_16x16x32_bf16 v[108:111], v[132:135], v[200:203], v[108:111]
	v_mfma_f32_16x16x32_bf16 v[104:107], v[168:171], v[200:203], v[104:107]
	v_mfma_f32_16x16x32_bf16 v[96:99], v[132:135], v[208:211], v[96:99]
	v_mfma_f32_16x16x32_bf16 v[88:91], v[168:171], v[208:211], v[88:91]
	v_mfma_f32_16x16x32_bf16 v[80:83], v[132:135], v[216:219], v[80:83]
	v_mfma_f32_16x16x32_bf16 v[72:75], v[168:171], v[216:219], v[72:75]
	v_mfma_f32_16x16x32_bf16 v[116:119], v[172:175], v[188:191], v[116:119]
	v_mfma_f32_16x16x32_bf16 v[112:115], v[180:183], v[188:191], v[112:115]
	v_mfma_f32_16x16x32_bf16 v[100:103], v[172:175], v[196:199], v[100:103]
	v_mfma_f32_16x16x32_bf16 v[92:95], v[180:183], v[196:199], v[92:95]
	v_mfma_f32_16x16x32_bf16 v[84:87], v[172:175], v[204:207], v[84:87]
	v_mfma_f32_16x16x32_bf16 v[76:79], v[180:183], v[204:207], v[76:79]
	v_mfma_f32_16x16x32_bf16 v[68:71], v[172:175], v[212:215], v[68:71]
	v_mfma_f32_16x16x32_bf16 v[64:67], v[180:183], v[212:215], v[64:67]
	v_mfma_f32_16x16x32_bf16 v[116:119], v[176:179], v[192:195], v[116:119]
	v_mfma_f32_16x16x32_bf16 v[112:115], v[184:187], v[192:195], v[112:115]
	v_mfma_f32_16x16x32_bf16 v[100:103], v[176:179], v[200:203], v[100:103]
	v_mfma_f32_16x16x32_bf16 v[92:95], v[184:187], v[200:203], v[92:95]
	v_mfma_f32_16x16x32_bf16 v[84:87], v[176:179], v[208:211], v[84:87]
	v_mfma_f32_16x16x32_bf16 v[76:79], v[184:187], v[208:211], v[76:79]
	v_mfma_f32_16x16x32_bf16 v[68:71], v[176:179], v[216:219], v[68:71]
	v_mfma_f32_16x16x32_bf16 v[64:67], v[184:187], v[216:219], v[64:67]
	s_setprio 0
	s_barrier
; #define PG8_LDA(dst, b, h) do { _Pragma("unroll") for (int m = 0; m < 4; ++m) _Pragma("unroll") for (int k = 0; k < 2; ++k) dst[m][k] = *(const LAS bf16x8*)(lds + PG8_SA(b, h) + aoff + m * 2048 + k * 1024); } while (0)
; #define PG8_MMA(ai, bj, At, Bt) do { __builtin_amdgcn_s_setprio(1); _Pragma("unroll") for (int m = 0; m < 4; ++m) _Pragma("unroll") for (int n = 0; n < 2; ++n) _Pragma("unroll") for (int k = 0; k < 2; ++k) \
;         acc[ai][bj][m][n] = __builtin_amdgcn_mfma_f32_16x16x32_bf16(Bt[n][k], At[m][k], acc[ai][bj][m][n], 0, 0, 0); __builtin_amdgcn_s_setprio(0); } while (0)
; #define PG8_WAIT_V(n) asm volatile("s_waitcnt vmcnt(" #n ")" ::: "memory")
; #define PG8_WAIT_L(n) asm volatile("s_waitcnt lgkmcnt(" #n ")" ::: "memory")
; #define PG8_BAR __builtin_amdgcn_s_barrier()
; #define PG8_SCHED __builtin_amdgcn_sched_barrier(0)
; __device__ __forceinline__ void gemm_phase(LAS unsigned char* lds, const GemmP& g) {
;     ...
;             PG8_LDA(At, 1, 1); PG8_STAGE(PG8_SB(1, 0), b3, voffB); PG8_STAGE(PG8_SB(1, 1), b3 + hstepB, voffB); PG8_STAGE(PG8_SA(1, 0), a3, voffA);
;             PG8_WAIT_V(8); PG8_WAIT_L(0); PG8_BAR; PG8_MMA(1, 0, At, B0); PG8_MMA(1, 1, At, B1); PG8_BAR; PG8_SCHED;
;         }
;         if (wr == 0) PG8_BAR;
	s_add_u32 s54, s44, 0x80
	s_addc_u32 s55, s45, 0
	s_add_i32 s73, s73, s33
	v_lshl_add_u64 v[162:163], s[54:55], 0, v[140:141]
	s_mov_b32 m0, s73
	ds_read_b128 v[188:191], v166 offset:49152
	ds_read_b128 v[192:195], v166 offset:50176
	ds_read_b128 v[196:199], v166 offset:51200
	ds_read_b128 v[200:203], v166 offset:52224
	ds_read_b128 v[204:207], v166 offset:53248
	ds_read_b128 v[208:211], v166 offset:54272
	ds_read_b128 v[212:215], v166 offset:55296
	ds_read_b128 v[216:219], v166 offset:56320
	global_load_lds_dwordx4 v[162:163], off
	s_add_i32 m0, s73, 0x2000
	s_add_u32 s44, s44, 0x80080
	v_lshl_add_u64 v[162:163], s[54:55], 0, v[142:143]
	s_addc_u32 s45, s45, 0
	s_add_i32 s54, s74, s33
	global_load_lds_dwordx4 v[162:163], off
	v_lshl_add_u64 v[162:163], s[44:45], 0, v[140:141]
	s_mov_b32 m0, s54
	s_nop 0
	global_load_lds_dwordx4 v[162:163], off
	v_lshl_add_u64 v[162:163], s[44:45], 0, v[142:143]
	s_add_i32 m0, s54, 0x2000
	s_nop 0
	global_load_lds_dwordx4 v[162:163], off
	v_lshl_add_u64 v[162:163], s[42:43], 0, v[140:141]
	s_mov_b32 m0, s63
	s_nop 0
	global_load_lds_dwordx4 v[162:163], off
	v_lshl_add_u64 v[162:163], s[42:43], 0, v[142:143]
	s_mov_b32 m0, s68
	s_nop 0
	global_load_lds_dwordx4 v[162:163], off
	s_waitcnt vmcnt(8)
	s_waitcnt lgkmcnt(0)
	s_barrier
	s_setprio 1
	s_waitcnt lgkmcnt(0)
	v_mfma_f32_16x16x32_bf16 v[60:63], v[128:131], v[188:191], v[60:63]
	v_mfma_f32_16x16x32_bf16 v[56:59], v[136:139], v[188:191], v[56:59]
	v_mfma_f32_16x16x32_bf16 v[48:51], v[128:131], v[196:199], v[48:51]
	v_mfma_f32_16x16x32_bf16 v[40:43], v[136:139], v[196:199], v[40:43]
	v_mfma_f32_16x16x32_bf16 v[32:35], v[128:131], v[204:207], v[32:35]
	v_mfma_f32_16x16x32_bf16 v[24:27], v[136:139], v[204:207], v[24:27]
	v_mfma_f32_16x16x32_bf16 v[16:19], v[128:131], v[212:215], v[16:19]
	v_mfma_f32_16x16x32_bf16 v[8:11], v[136:139], v[212:215], v[8:11]
	v_mfma_f32_16x16x32_bf16 v[60:63], v[132:135], v[192:195], v[60:63]
	v_mfma_f32_16x16x32_bf16 v[56:59], v[168:171], v[192:195], v[56:59]
	v_mfma_f32_16x16x32_bf16 v[48:51], v[132:135], v[200:203], v[48:51]
	v_mfma_f32_16x16x32_bf16 v[40:43], v[168:171], v[200:203], v[40:43]
	v_mfma_f32_16x16x32_bf16 v[32:35], v[132:135], v[208:211], v[32:35]
	v_mfma_f32_16x16x32_bf16 v[24:27], v[168:171], v[208:211], v[24:27]
	v_mfma_f32_16x16x32_bf16 v[16:19], v[132:135], v[216:219], v[16:19]
	v_mfma_f32_16x16x32_bf16 v[8:11], v[168:171], v[216:219], v[8:11]
	v_mfma_f32_16x16x32_bf16 v[52:55], v[172:175], v[188:191], v[52:55]
	v_mfma_f32_16x16x32_bf16 v[44:47], v[180:183], v[188:191], v[44:47]
	v_mfma_f32_16x16x32_bf16 v[36:39], v[172:175], v[196:199], v[36:39]
	v_mfma_f32_16x16x32_bf16 v[28:31], v[180:183], v[196:199], v[28:31]
	v_mfma_f32_16x16x32_bf16 v[20:23], v[172:175], v[204:207], v[20:23]
	v_mfma_f32_16x16x32_bf16 v[12:15], v[180:183], v[204:207], v[12:15]
	v_mfma_f32_16x16x32_bf16 v[4:7], v[172:175], v[212:215], v[4:7]
	v_mfma_f32_16x16x32_bf16 v[0:3], v[180:183], v[212:215], v[0:3]
	v_mfma_f32_16x16x32_bf16 v[52:55], v[176:179], v[192:195], v[52:55]
	v_mfma_f32_16x16x32_bf16 v[44:47], v[184:187], v[192:195], v[44:47]
	v_mfma_f32_16x16x32_bf16 v[36:39], v[176:179], v[200:203], v[36:39]
	v_mfma_f32_16x16x32_bf16 v[28:31], v[184:187], v[200:203], v[28:31]
	v_mfma_f32_16x16x32_bf16 v[20:23], v[176:179], v[208:211], v[20:23]
	v_mfma_f32_16x16x32_bf16 v[12:15], v[184:187], v[208:211], v[12:15]
	v_mfma_f32_16x16x32_bf16 v[4:7], v[176:179], v[216:219], v[4:7]
	v_mfma_f32_16x16x32_bf16 v[0:3], v[184:187], v[216:219], v[0:3]
	s_setprio 0
	s_barrier
	s_add_i32 s72, s72, 2
	s_add_u32 s20, s20, 0x100
	s_addc_u32 s21, s21, 0
	s_add_u32 s30, s30, 0x100
	s_addc_u32 s31, s31, 0
	s_add_u32 s40, s40, 0x100
	s_addc_u32 s41, s41, 0
	s_cmp_gt_u32 s72, 29
	s_cbranch_scc0 .LBB0_702
	s_and_b64 vcc, exec, s[4:5]
	s_cbranch_vccz .LBB0_705
	s_barrier

; #define PG8_LDA(dst, b, h) do { _Pragma("unroll") for (int m = 0; m < 4; ++m) _Pragma("unroll") for (int k = 0; k < 2; ++k) dst[m][k] = *(const LAS bf16x8*)(lds + PG8_SA(b, h) + aoff + m * 2048 + k * 1024); } while (0)
; #define PG8_LDB(dst, b, h) do { _Pragma("unroll") for (int n = 0; n < 2; ++n) _Pragma("unroll") for (int k = 0; k < 2; ++k) dst[n][k] = *(const LAS bf16x8*)(lds + PG8_SB(b, h) + boff + n * 2048 + k * 1024); } while (0)
; #define PG8_MMA(ai, bj, At, Bt) do { __builtin_amdgcn_s_setprio(1); _Pragma("unroll") for (int m = 0; m < 4; ++m) _Pragma("unroll") for (int n = 0; n < 2; ++n) _Pragma("unroll") for (int k = 0; k < 2; ++k) \
;         acc[ai][bj][m][n] = __builtin_amdgcn_mfma_f32_16x16x32_bf16(Bt[n][k], At[m][k], acc[ai][bj][m][n], 0, 0, 0); __builtin_amdgcn_s_setprio(0); } while (0)
; #define PG8_WAIT_V(n) asm volatile("s_waitcnt vmcnt(" #n ")" ::: "memory")
; #define PG8_WAIT_L(n) asm volatile("s_waitcnt lgkmcnt(" #n ")" ::: "memory")
; #define PG8_BAR __builtin_amdgcn_s_barrier()
; #define PG8_SCHED __builtin_amdgcn_sched_barrier(0)
; __device__ __forceinline__ void gemm_phase(LAS unsigned char* lds, const GemmP& g) {
;     ...
;         for (int t = 0; t < nt; t += 2) {
;             const bool last = (t == nt - 2);
;             const char* a1 = cA + (size_t)(t + 1) * kstep;
;             const char* a2 = last ? nA : cA + (size_t)(t + 2) * kstep; const char* b2 = last ? nB : cB + (size_t)(t + 2) * kstep;
;             const char* a3 = a2 + kstep; const char* b3 = b2 + kstep;
;             PG8_LDB(B0, 0, 0); PG8_LDB(B1, 0, 1); PG8_SCHED; PG8_LDA(At, 0, 0); PG8_STAGE(PG8_SA(1, 1), a1 + hstepA, voffA);
;             PG8_WAIT_V(8); PG8_WAIT_L(0); PG8_BAR; PG8_MMA(0, 0, At, B0); PG8_MMA(0, 1, At, B1); PG8_BAR; PG8_SCHED;
;             PG8_LDA(At, 0, 1); PG8_STAGE(PG8_SB(0, 0), b2, voffB); PG8_STAGE(PG8_SB(0, 1), b2 + hstepB, voffB); PG8_STAGE(PG8_SA(0, 0), a2, voffA);
;             PG8_WAIT_V(8); PG8_WAIT_L(0); PG8_BAR; PG8_MMA(1, 0, At, B0); PG8_MMA(1, 1, At, B1); PG8_BAR; PG8_SCHED;
.LBB0_848:
	ds_read_b128 v[160:163], v157
	ds_read_b128 v[164:167], v157 offset:1024
	ds_read_b128 v[168:171], v157 offset:2048
	ds_read_b128 v[172:175], v157 offset:3072
	ds_read_b128 v[176:179], v158
	ds_read_b128 v[180:183], v158 offset:1024
	ds_read_b128 v[184:187], v158 offset:2048
	ds_read_b128 v[188:191], v158 offset:3072
	s_cmp_eq_u32 s71, 28
	s_cselect_b32 s52, s17, s63
	s_cselect_b32 s53, s9, s68
	s_cselect_b32 s44, s19, s69
	s_cselect_b32 s45, s11, s70
	s_add_u32 s42, s52, 0x80
	s_addc_u32 s43, s53, 0
	v_lshl_add_u64 v[154:155], s[40:41], 0, v[128:129]
	s_add_i32 m0, s54, 0xc000
	ds_read_b128 v[192:195], v159
	ds_read_b128 v[196:199], v159 offset:1024
	ds_read_b128 v[200:203], v159 offset:2048
	ds_read_b128 v[204:207], v159 offset:3072
	ds_read_b128 v[208:211], v159 offset:4096
	ds_read_b128 v[212:215], v159 offset:5120
	ds_read_b128 v[216:219], v159 offset:6144
	ds_read_b128 v[220:223], v159 offset:7168
	global_load_lds_dwordx4 v[154:155], off
	v_lshl_add_u64 v[154:155], s[40:41], 0, v[132:133]
	s_add_i32 m0, s54, 0xe000
	s_nop 0
	global_load_lds_dwordx4 v[154:155], off
	s_waitcnt vmcnt(8)
	s_waitcnt lgkmcnt(0)
	s_barrier
	s_setprio 1
	s_waitcnt lgkmcnt(0)
	v_mfma_f32_16x16x32_bf16 v[124:127], v[160:163], v[192:195], v[124:127]
	v_mfma_f32_16x16x32_bf16 v[120:123], v[168:171], v[192:195], v[120:123]
	v_mfma_f32_16x16x32_bf16 v[108:111], v[160:163], v[200:203], v[108:111]
	v_mfma_f32_16x16x32_bf16 v[104:107], v[168:171], v[200:203], v[104:107]
	v_mfma_f32_16x16x32_bf16 v[92:95], v[160:163], v[208:211], v[92:95]
	v_mfma_f32_16x16x32_bf16 v[88:91], v[168:171], v[208:211], v[88:91]
	v_mfma_f32_16x16x32_bf16 v[76:79], v[160:163], v[216:219], v[76:79]
	v_mfma_f32_16x16x32_bf16 v[72:75], v[168:171], v[216:219], v[72:75]
	v_mfma_f32_16x16x32_bf16 v[124:127], v[164:167], v[196:199], v[124:127]
	v_mfma_f32_16x16x32_bf16 v[120:123], v[172:175], v[196:199], v[120:123]
	v_mfma_f32_16x16x32_bf16 v[108:111], v[164:167], v[204:207], v[108:111]
	v_mfma_f32_16x16x32_bf16 v[104:107], v[172:175], v[204:207], v[104:107]
	v_mfma_f32_16x16x32_bf16 v[92:95], v[164:167], v[212:215], v[92:95]
	v_mfma_f32_16x16x32_bf16 v[88:91], v[172:175], v[212:215], v[88:91]
	v_mfma_f32_16x16x32_bf16 v[76:79], v[164:167], v[220:223], v[76:79]
	v_mfma_f32_16x16x32_bf16 v[72:75], v[172:175], v[220:223], v[72:75]
	v_mfma_f32_16x16x32_bf16 v[116:119], v[176:179], v[192:195], v[116:119]
	v_mfma_f32_16x16x32_bf16 v[112:115], v[184:187], v[192:195], v[112:115]
	v_mfma_f32_16x16x32_bf16 v[100:103], v[176:179], v[200:203], v[100:103]
	v_mfma_f32_16x16x32_bf16 v[96:99], v[184:187], v[200:203], v[96:99]
	v_mfma_f32_16x16x32_bf16 v[84:87], v[176:179], v[208:211], v[84:87]
	v_mfma_f32_16x16x32_bf16 v[80:83], v[184:187], v[208:211], v[80:83]
	v_mfma_f32_16x16x32_bf16 v[68:71], v[176:179], v[216:219], v[68:71]
	v_mfma_f32_16x16x32_bf16 v[64:67], v[184:187], v[216:219], v[64:67]
	v_mfma_f32_16x16x32_bf16 v[116:119], v[180:183], v[196:199], v[116:119]
	v_mfma_f32_16x16x32_bf16 v[112:115], v[188:191], v[196:199], v[112:115]
	v_mfma_f32_16x16x32_bf16 v[100:103], v[180:183], v[204:207], v[100:103]
	v_mfma_f32_16x16x32_bf16 v[96:99], v[188:191], v[204:207], v[96:99]
	v_mfma_f32_16x16x32_bf16 v[84:87], v[180:183], v[212:215], v[84:87]
	v_mfma_f32_16x16x32_bf16 v[80:83], v[188:191], v[212:215], v[80:83]
	v_mfma_f32_16x16x32_bf16 v[68:71], v[180:183], v[220:223], v[68:71]
	v_mfma_f32_16x16x32_bf16 v[64:67], v[188:191], v[220:223], v[64:67]
	s_setprio 0
	s_barrier
	s_add_i32 s72, s31, s33
	v_lshl_add_u64 v[154:155], s[44:45], 0, v[130:131]
	s_mov_b32 m0, s72
	ds_read_b128 v[192:195], v159 offset:16384
	ds_read_b128 v[196:199], v159 offset:17408
	ds_read_b128 v[200:203], v159 offset:18432
	ds_read_b128 v[204:207], v159 offset:19456
	ds_read_b128 v[208:211], v159 offset:20480
	ds_read_b128 v[212:215], v159 offset:21504
	ds_read_b128 v[216:219], v159 offset:22528
	ds_read_b128 v[220:223], v159 offset:23552
	global_load_lds_dwordx4 v[154:155], off
	s_add_i32 m0, s72, 0x2000
	s_add_u32 s72, s44, 0x80000
	v_lshl_add_u64 v[154:155], s[44:45], 0, v[134:135]
	s_addc_u32 s73, s45, 0
	s_add_i32 s74, s61, s33
	global_load_lds_dwordx4 v[154:155], off
	v_lshl_add_u64 v[154:155], s[72:73], 0, v[130:131]
	s_mov_b32 m0, s74
	s_nop 0
	global_load_lds_dwordx4 v[154:155], off
	v_lshl_add_u64 v[154:155], s[72:73], 0, v[134:135]
	s_add_i32 m0, s74, 0x2000
	s_nop 0
	global_load_lds_dwordx4 v[154:155], off
	v_lshl_add_u64 v[154:155], s[52:53], 0, v[128:129]
	s_mov_b32 m0, s54
	s_nop 0
	global_load_lds_dwordx4 v[154:155], off
	v_lshl_add_u64 v[154:155], s[52:53], 0, v[132:133]
	s_mov_b32 m0, s55
	s_nop 0
	global_load_lds_dwordx4 v[154:155], off
	s_waitcnt vmcnt(8)
	s_waitcnt lgkmcnt(0)
	s_barrier
; #define PG8_LDA(dst, b, h) do { _Pragma("unroll") for (int m = 0; m < 4; ++m) _Pragma("unroll") for (int k = 0; k < 2; ++k) dst[m][k] = *(const LAS bf16x8*)(lds + PG8_SA(b, h) + aoff + m * 2048 + k * 1024); } while (0)
; #define PG8_LDB(dst, b, h) do { _Pragma("unroll") for (int n = 0; n < 2; ++n) _Pragma("unroll") for (int k = 0; k < 2; ++k) dst[n][k] = *(const LAS bf16x8*)(lds + PG8_SB(b, h) + boff + n * 2048 + k * 1024); } while (0)
; #define PG8_MMA(ai, bj, At, Bt) do { __builtin_amdgcn_s_setprio(1); _Pragma("unroll") for (int m = 0; m < 4; ++m) _Pragma("unroll") for (int n = 0; n < 2; ++n) _Pragma("unroll") for (int k = 0; k < 2; ++k) \
;         acc[ai][bj][m][n] = __builtin_amdgcn_mfma_f32_16x16x32_bf16(Bt[n][k], At[m][k], acc[ai][bj][m][n], 0, 0, 0); __builtin_amdgcn_s_setprio(0); } while (0)
; #define PG8_WAIT_V(n) asm volatile("s_waitcnt vmcnt(" #n ")" ::: "memory")
; #define PG8_WAIT_L(n) asm volatile("s_waitcnt lgkmcnt(" #n ")" ::: "memory")
; #define PG8_BAR __builtin_amdgcn_s_barrier()
; #define PG8_SCHED __builtin_amdgcn_sched_barrier(0)
; __device__ __forceinline__ void gemm_phase(LAS unsigned char* lds, const GemmP& g) {
;     ...
;             PG8_WAIT_V(8); PG8_WAIT_L(0); PG8_BAR; PG8_MMA(1, 0, At, B0); PG8_MMA(1, 1, At, B1); PG8_BAR; PG8_SCHED;
;             PG8_LDB(B0, 1, 0); PG8_LDB(B1, 1, 1); PG8_SCHED; PG8_LDA(At, 1, 0); PG8_STAGE(PG8_SA(0, 1), a2 + hstepA, voffA);
;             PG8_WAIT_V(8); PG8_WAIT_L(0); PG8_BAR; PG8_MMA(0, 0, At, B0); PG8_MMA(0, 1, At, B1); PG8_BAR; PG8_SCHED;
	s_setprio 1
	s_waitcnt lgkmcnt(0)
	v_mfma_f32_16x16x32_bf16 v[60:63], v[160:163], v[192:195], v[60:63]
	v_mfma_f32_16x16x32_bf16 v[56:59], v[168:171], v[192:195], v[56:59]
	v_mfma_f32_16x16x32_bf16 v[44:47], v[160:163], v[200:203], v[44:47]
	v_mfma_f32_16x16x32_bf16 v[40:43], v[168:171], v[200:203], v[40:43]
	v_mfma_f32_16x16x32_bf16 v[28:31], v[160:163], v[208:211], v[28:31]
	v_mfma_f32_16x16x32_bf16 v[24:27], v[168:171], v[208:211], v[24:27]
	v_mfma_f32_16x16x32_bf16 v[12:15], v[160:163], v[216:219], v[12:15]
	v_mfma_f32_16x16x32_bf16 v[8:11], v[168:171], v[216:219], v[8:11]
	v_mfma_f32_16x16x32_bf16 v[60:63], v[164:167], v[196:199], v[60:63]
	v_mfma_f32_16x16x32_bf16 v[56:59], v[172:175], v[196:199], v[56:59]
	v_mfma_f32_16x16x32_bf16 v[44:47], v[164:167], v[204:207], v[44:47]
	v_mfma_f32_16x16x32_bf16 v[40:43], v[172:175], v[204:207], v[40:43]
	v_mfma_f32_16x16x32_bf16 v[28:31], v[164:167], v[212:215], v[28:31]
	v_mfma_f32_16x16x32_bf16 v[24:27], v[172:175], v[212:215], v[24:27]
	v_mfma_f32_16x16x32_bf16 v[12:15], v[164:167], v[220:223], v[12:15]
	v_mfma_f32_16x16x32_bf16 v[8:11], v[172:175], v[220:223], v[8:11]
	v_mfma_f32_16x16x32_bf16 v[52:55], v[176:179], v[192:195], v[52:55]
	v_mfma_f32_16x16x32_bf16 v[48:51], v[184:187], v[192:195], v[48:51]
	v_mfma_f32_16x16x32_bf16 v[36:39], v[176:179], v[200:203], v[36:39]
	v_mfma_f32_16x16x32_bf16 v[32:35], v[184:187], v[200:203], v[32:35]
	v_mfma_f32_16x16x32_bf16 v[20:23], v[176:179], v[208:211], v[20:23]
	v_mfma_f32_16x16x32_bf16 v[16:19], v[184:187], v[208:211], v[16:19]
	v_mfma_f32_16x16x32_bf16 v[4:7], v[176:179], v[216:219], v[4:7]
	v_mfma_f32_16x16x32_bf16 v[0:3], v[184:187], v[216:219], v[0:3]
	v_mfma_f32_16x16x32_bf16 v[52:55], v[180:183], v[196:199], v[52:55]
	v_mfma_f32_16x16x32_bf16 v[48:51], v[188:191], v[196:199], v[48:51]
	v_mfma_f32_16x16x32_bf16 v[36:39], v[180:183], v[204:207], v[36:39]
	v_mfma_f32_16x16x32_bf16 v[32:35], v[188:191], v[204:207], v[32:35]
	v_mfma_f32_16x16x32_bf16 v[20:23], v[180:183], v[212:215], v[20:23]
	v_mfma_f32_16x16x32_bf16 v[16:19], v[188:191], v[212:215], v[16:19]
	v_mfma_f32_16x16x32_bf16 v[4:7], v[180:183], v[220:223], v[4:7]
	v_mfma_f32_16x16x32_bf16 v[0:3], v[188:191], v[220:223], v[0:3]
	s_setprio 0
	s_barrier
	s_add_i32 s72, 0, 0x18000
	v_add_u32_e32 v154, s72, v156
	s_add_i32 s73, 0, 0x1c000
	ds_read_b128 v[160:163], v154
	ds_read_b128 v[164:167], v154 offset:1024
	ds_read_b128 v[168:171], v154 offset:2048
	ds_read_b128 v[172:175], v154 offset:3072
	v_add_u32_e32 v154, s73, v156
	ds_read_b128 v[176:179], v154
	ds_read_b128 v[180:183], v154 offset:1024
	ds_read_b128 v[184:187], v154 offset:2048
	ds_read_b128 v[188:191], v154 offset:3072
	s_add_u32 s52, s52, 0x80000
	s_addc_u32 s53, s53, 0
	s_mov_b32 m0, s56
	v_lshl_add_u64 v[154:155], s[52:53], 0, v[128:129]
	ds_read_b128 v[192:195], v159 offset:32768
	ds_read_b128 v[196:199], v159 offset:33792
	ds_read_b128 v[200:203], v159 offset:34816
	ds_read_b128 v[204:207], v159 offset:35840
	ds_read_b128 v[208:211], v159 offset:36864
	ds_read_b128 v[212:215], v159 offset:37888
	ds_read_b128 v[216:219], v159 offset:38912
	ds_read_b128 v[220:223], v159 offset:39936
	global_load_lds_dwordx4 v[154:155], off
	v_lshl_add_u64 v[154:155], s[52:53], 0, v[132:133]
	s_mov_b32 m0, s57
	s_nop 0
	global_load_lds_dwordx4 v[154:155], off
	s_waitcnt vmcnt(8)
	s_waitcnt lgkmcnt(0)
	s_barrier
	s_setprio 1
	s_waitcnt lgkmcnt(0)
	v_mfma_f32_16x16x32_bf16 v[124:127], v[160:163], v[192:195], v[124:127]
	v_mfma_f32_16x16x32_bf16 v[120:123], v[168:171], v[192:195], v[120:123]
	v_mfma_f32_16x16x32_bf16 v[108:111], v[160:163], v[200:203], v[108:111]
	v_mfma_f32_16x16x32_bf16 v[104:107], v[168:171], v[200:203], v[104:107]
	v_mfma_f32_16x16x32_bf16 v[92:95], v[160:163], v[208:211], v[92:95]
	v_mfma_f32_16x16x32_bf16 v[88:91], v[168:171], v[208:211], v[88:91]
	v_mfma_f32_16x16x32_bf16 v[76:79], v[160:163], v[216:219], v[76:79]
	v_mfma_f32_16x16x32_bf16 v[72:75], v[168:171], v[216:219], v[72:75]
	v_mfma_f32_16x16x32_bf16 v[124:127], v[164:167], v[196:199], v[124:127]
	v_mfma_f32_16x16x32_bf16 v[120:123], v[172:175], v[196:199], v[120:123]
	v_mfma_f32_16x16x32_bf16 v[108:111], v[164:167], v[204:207], v[108:111]
	v_mfma_f32_16x16x32_bf16 v[104:107], v[172:175], v[204:207], v[104:107]
	v_mfma_f32_16x16x32_bf16 v[92:95], v[164:167], v[212:215], v[92:95]
	v_mfma_f32_16x16x32_bf16 v[88:91], v[172:175], v[212:215], v[88:91]
	v_mfma_f32_16x16x32_bf16 v[76:79], v[164:167], v[220:223], v[76:79]
	v_mfma_f32_16x16x32_bf16 v[72:75], v[172:175], v[220:223], v[72:75]
	v_mfma_f32_16x16x32_bf16 v[116:119], v[176:179], v[192:195], v[116:119]
	v_mfma_f32_16x16x32_bf16 v[112:115], v[184:187], v[192:195], v[112:115]
	v_mfma_f32_16x16x32_bf16 v[100:103], v[176:179], v[200:203], v[100:103]
	v_mfma_f32_16x16x32_bf16 v[96:99], v[184:187], v[200:203], v[96:99]
	v_mfma_f32_16x16x32_bf16 v[84:87], v[176:179], v[208:211], v[84:87]
	v_mfma_f32_16x16x32_bf16 v[80:83], v[184:187], v[208:211], v[80:83]
	v_mfma_f32_16x16x32_bf16 v[68:71], v[176:179], v[216:219], v[68:71]
	v_mfma_f32_16x16x32_bf16 v[64:67], v[184:187], v[216:219], v[64:67]
	v_mfma_f32_16x16x32_bf16 v[116:119], v[180:183], v[196:199], v[116:119]
	v_mfma_f32_16x16x32_bf16 v[112:115], v[188:191], v[196:199], v[112:115]
	v_mfma_f32_16x16x32_bf16 v[100:103], v[180:183], v[204:207], v[100:103]
	v_mfma_f32_16x16x32_bf16 v[96:99], v[188:191], v[204:207], v[96:99]
	v_mfma_f32_16x16x32_bf16 v[84:87], v[180:183], v[212:215], v[84:87]
	v_mfma_f32_16x16x32_bf16 v[80:83], v[188:191], v[212:215], v[80:83]
	v_mfma_f32_16x16x32_bf16 v[68:71], v[180:183], v[220:223], v[68:71]
	v_mfma_f32_16x16x32_bf16 v[64:67], v[188:191], v[220:223], v[64:67]
	s_setprio 0
	s_barrier
; #define PG8_LDA(dst, b, h) do { _Pragma("unroll") for (int m = 0; m < 4; ++m) _Pragma("unroll") for (int k = 0; k < 2; ++k) dst[m][k] = *(const LAS bf16x8*)(lds + PG8_SA(b, h) + aoff + m * 2048 + k * 1024); } while (0)
; #define PG8_MMA(ai, bj, At, Bt) do { __builtin_amdgcn_s_setprio(1); _Pragma("unroll") for (int m = 0; m < 4; ++m) _Pragma("unroll") for (int n = 0; n < 2; ++n) _Pragma("unroll") for (int k = 0; k < 2; ++k) \
;         acc[ai][bj][m][n] = __builtin_amdgcn_mfma_f32_16x16x32_bf16(Bt[n][k], At[m][k], acc[ai][bj][m][n], 0, 0, 0); __builtin_amdgcn_s_setprio(0); } while (0)
; #define PG8_WAIT_V(n) asm volatile("s_waitcnt vmcnt(" #n ")" ::: "memory")
; #define PG8_WAIT_L(n) asm volatile("s_waitcnt lgkmcnt(" #n ")" ::: "memory")
; #define PG8_BAR __builtin_amdgcn_s_barrier()
; #define PG8_SCHED __builtin_amdgcn_sched_barrier(0)
; __device__ __forceinline__ void gemm_phase(LAS unsigned char* lds, const GemmP& g) {
;     ...
;             PG8_LDA(At, 1, 1); PG8_STAGE(PG8_SB(1, 0), b3, voffB); PG8_STAGE(PG8_SB(1, 1), b3 + hstepB, voffB); PG8_STAGE(PG8_SA(1, 0), a3, voffA);
;             PG8_WAIT_V(8); PG8_WAIT_L(0); PG8_BAR; PG8_MMA(1, 0, At, B0); PG8_MMA(1, 1, At, B1); PG8_BAR; PG8_SCHED;
;         }
;         if (wr == 0) PG8_BAR;
	s_add_u32 s52, s44, 0x80
	s_addc_u32 s53, s45, 0
	s_add_i32 s72, s72, s33
	v_lshl_add_u64 v[154:155], s[52:53], 0, v[130:131]
	s_mov_b32 m0, s72
	ds_read_b128 v[192:195], v159 offset:49152
	ds_read_b128 v[196:199], v159 offset:50176
	ds_read_b128 v[200:203], v159 offset:51200
	ds_read_b128 v[204:207], v159 offset:52224
	ds_read_b128 v[208:211], v159 offset:53248
	ds_read_b128 v[212:215], v159 offset:54272
	ds_read_b128 v[216:219], v159 offset:55296
	ds_read_b128 v[220:223], v159 offset:56320
	global_load_lds_dwordx4 v[154:155], off
	s_add_i32 m0, s72, 0x2000
	s_add_u32 s44, s44, 0x80080
	v_lshl_add_u64 v[154:155], s[52:53], 0, v[134:135]
	s_addc_u32 s45, s45, 0
	s_add_i32 s52, s73, s33
	global_load_lds_dwordx4 v[154:155], off
	v_lshl_add_u64 v[154:155], s[44:45], 0, v[130:131]
	s_mov_b32 m0, s52
	s_nop 0
	global_load_lds_dwordx4 v[154:155], off
	v_lshl_add_u64 v[154:155], s[44:45], 0, v[134:135]
	s_add_i32 m0, s52, 0x2000
	s_nop 0
	global_load_lds_dwordx4 v[154:155], off
	v_lshl_add_u64 v[154:155], s[42:43], 0, v[128:129]
	s_mov_b32 m0, s20
	s_nop 0
	global_load_lds_dwordx4 v[154:155], off
	v_lshl_add_u64 v[154:155], s[42:43], 0, v[132:133]
	s_mov_b32 m0, s21
	s_nop 0
	global_load_lds_dwordx4 v[154:155], off
	s_waitcnt vmcnt(8)
	s_waitcnt lgkmcnt(0)
	s_barrier
	s_setprio 1
	s_waitcnt lgkmcnt(0)
	v_mfma_f32_16x16x32_bf16 v[60:63], v[160:163], v[192:195], v[60:63]
	v_mfma_f32_16x16x32_bf16 v[56:59], v[168:171], v[192:195], v[56:59]
	v_mfma_f32_16x16x32_bf16 v[44:47], v[160:163], v[200:203], v[44:47]
	v_mfma_f32_16x16x32_bf16 v[40:43], v[168:171], v[200:203], v[40:43]
	v_mfma_f32_16x16x32_bf16 v[28:31], v[160:163], v[208:211], v[28:31]
	v_mfma_f32_16x16x32_bf16 v[24:27], v[168:171], v[208:211], v[24:27]
	v_mfma_f32_16x16x32_bf16 v[12:15], v[160:163], v[216:219], v[12:15]
	v_mfma_f32_16x16x32_bf16 v[8:11], v[168:171], v[216:219], v[8:11]
	v_mfma_f32_16x16x32_bf16 v[60:63], v[164:167], v[196:199], v[60:63]
	v_mfma_f32_16x16x32_bf16 v[56:59], v[172:175], v[196:199], v[56:59]
	v_mfma_f32_16x16x32_bf16 v[44:47], v[164:167], v[204:207], v[44:47]
	v_mfma_f32_16x16x32_bf16 v[40:43], v[172:175], v[204:207], v[40:43]
	v_mfma_f32_16x16x32_bf16 v[28:31], v[164:167], v[212:215], v[28:31]
	v_mfma_f32_16x16x32_bf16 v[24:27], v[172:175], v[212:215], v[24:27]
	v_mfma_f32_16x16x32_bf16 v[12:15], v[164:167], v[220:223], v[12:15]
	v_mfma_f32_16x16x32_bf16 v[8:11], v[172:175], v[220:223], v[8:11]
	v_mfma_f32_16x16x32_bf16 v[52:55], v[176:179], v[192:195], v[52:55]
	v_mfma_f32_16x16x32_bf16 v[48:51], v[184:187], v[192:195], v[48:51]
	v_mfma_f32_16x16x32_bf16 v[36:39], v[176:179], v[200:203], v[36:39]
	v_mfma_f32_16x16x32_bf16 v[32:35], v[184:187], v[200:203], v[32:35]
	v_mfma_f32_16x16x32_bf16 v[20:23], v[176:179], v[208:211], v[20:23]
	v_mfma_f32_16x16x32_bf16 v[16:19], v[184:187], v[208:211], v[16:19]
	v_mfma_f32_16x16x32_bf16 v[4:7], v[176:179], v[216:219], v[4:7]
	v_mfma_f32_16x16x32_bf16 v[0:3], v[184:187], v[216:219], v[0:3]
	v_mfma_f32_16x16x32_bf16 v[52:55], v[180:183], v[196:199], v[52:55]
	v_mfma_f32_16x16x32_bf16 v[48:51], v[188:191], v[196:199], v[48:51]
	v_mfma_f32_16x16x32_bf16 v[36:39], v[180:183], v[204:207], v[36:39]
	v_mfma_f32_16x16x32_bf16 v[32:35], v[188:191], v[204:207], v[32:35]
	v_mfma_f32_16x16x32_bf16 v[20:23], v[180:183], v[212:215], v[20:23]
	v_mfma_f32_16x16x32_bf16 v[16:19], v[188:191], v[212:215], v[16:19]
	v_mfma_f32_16x16x32_bf16 v[4:7], v[180:183], v[220:223], v[4:7]
	v_mfma_f32_16x16x32_bf16 v[0:3], v[188:191], v[220:223], v[0:3]
	s_setprio 0
	s_barrier
	s_add_i32 s71, s71, 2
	s_add_u32 s63, s63, 0x100
	s_addc_u32 s68, s68, 0
	s_add_u32 s69, s69, 0x100
	s_addc_u32 s70, s70, 0
	s_add_u32 s40, s40, 0x100
	s_addc_u32 s41, s41, 0
	s_cmp_gt_u32 s71, 29
	s_cbranch_scc0 .LBB0_848
	s_and_b64 vcc, exec, s[4:5]
	s_cbranch_vccz .LBB0_851
	s_barrier

; #define PG8_LDA(dst, b, h) do { _Pragma("unroll") for (int m = 0; m < 4; ++m) _Pragma("unroll") for (int k = 0; k < 2; ++k) dst[m][k] = *(const LAS bf16x8*)(lds + PG8_SA(b, h) + aoff + m * 2048 + k * 1024); } while (0)
; #define PG8_LDB(dst, b, h) do { _Pragma("unroll") for (int n = 0; n < 2; ++n) _Pragma("unroll") for (int k = 0; k < 2; ++k) dst[n][k] = *(const LAS bf16x8*)(lds + PG8_SB(b, h) + boff + n * 2048 + k * 1024); } while (0)
; #define PG8_MMA(ai, bj, At, Bt) do { __builtin_amdgcn_s_setprio(1); _Pragma("unroll") for (int m = 0; m < 4; ++m) _Pragma("unroll") for (int n = 0; n < 2; ++n) _Pragma("unroll") for (int k = 0; k < 2; ++k) \
;         acc[ai][bj][m][n] = __builtin_amdgcn_mfma_f32_16x16x32_bf16(Bt[n][k], At[m][k], acc[ai][bj][m][n], 0, 0, 0); __builtin_amdgcn_s_setprio(0); } while (0)
; #define PG8_WAIT_V(n) asm volatile("s_waitcnt vmcnt(" #n ")" ::: "memory")
; #define PG8_WAIT_L(n) asm volatile("s_waitcnt lgkmcnt(" #n ")" ::: "memory")
; #define PG8_BAR __builtin_amdgcn_s_barrier()
; #define PG8_SCHED __builtin_amdgcn_sched_barrier(0)
; __device__ __forceinline__ void gemm_phase(LAS unsigned char* lds, const GemmP& g) {
;     ...
;         for (int t = 0; t < nt; t += 2) {
;             const bool last = (t == nt - 2);
;             const char* a1 = cA + (size_t)(t + 1) * kstep;
;             const char* a2 = last ? nA : cA + (size_t)(t + 2) * kstep; const char* b2 = last ? nB : cB + (size_t)(t + 2) * kstep;
;             const char* a3 = a2 + kstep; const char* b3 = b2 + kstep;
;             PG8_LDB(B0, 0, 0); PG8_LDB(B1, 0, 1); PG8_SCHED; PG8_LDA(At, 0, 0); PG8_STAGE(PG8_SA(1, 1), a1 + hstepA, voffA);
;             PG8_WAIT_V(8); PG8_WAIT_L(0); PG8_BAR; PG8_MMA(0, 0, At, B0); PG8_MMA(0, 1, At, B1); PG8_BAR; PG8_SCHED;
;             PG8_LDA(At, 0, 1); PG8_STAGE(PG8_SB(0, 0), b2, voffB); PG8_STAGE(PG8_SB(0, 1), b2 + hstepB, voffB); PG8_STAGE(PG8_SA(0, 0), a2, voffA);
;             PG8_WAIT_V(8); PG8_WAIT_L(0); PG8_BAR; PG8_MMA(1, 0, At, B0); PG8_MMA(1, 1, At, B1); PG8_BAR; PG8_SCHED;
.LBB0_927:
	ds_read_b128 v[128:131], v187
	ds_read_b128 v[132:135], v187 offset:1024
	ds_read_b128 v[136:139], v187 offset:2048
	ds_read_b128 v[140:143], v187 offset:3072
	ds_read_b128 v[190:193], v188
	ds_read_b128 v[194:197], v188 offset:1024
	ds_read_b128 v[198:201], v188 offset:2048
	ds_read_b128 v[202:205], v188 offset:3072
	s_cmpk_eq_i32 s72, 0x7c
	s_cselect_b32 s52, s17, s20
	s_cselect_b32 s53, s9, s21
	s_cselect_b32 s44, s19, s30
	s_cselect_b32 s45, s11, s31
	s_add_u32 s42, s52, 0x80
	s_addc_u32 s43, s53, 0
	v_lshl_add_u64 v[184:185], s[40:41], 0, v[144:145]
	s_add_i32 m0, s56, 0xc000
	ds_read_b128 v[206:209], v186
	ds_read_b128 v[210:213], v186 offset:1024
	ds_read_b128 v[214:217], v186 offset:2048
	ds_read_b128 v[218:221], v186 offset:3072
	ds_read_b128 v[226:229], v186 offset:4096
	ds_read_b128 v[230:233], v186 offset:5120
	ds_read_b128 v[234:237], v186 offset:6144
	ds_read_b128 v[238:241], v186 offset:7168
	global_load_lds_dwordx4 v[184:185], off
	v_lshl_add_u64 v[184:185], s[40:41], 0, v[146:147]
	s_add_i32 m0, s56, 0xe000
	s_nop 0
	global_load_lds_dwordx4 v[184:185], off
	s_waitcnt vmcnt(8)
	s_waitcnt lgkmcnt(0)
	s_barrier
	s_setprio 1
	s_waitcnt lgkmcnt(0)
	v_mfma_f32_16x16x32_bf16 v[124:127], v[128:131], v[206:209], v[124:127]
	v_mfma_f32_16x16x32_bf16 v[120:123], v[136:139], v[206:209], v[120:123]
	v_mfma_f32_16x16x32_bf16 v[108:111], v[128:131], v[214:217], v[108:111]
	v_mfma_f32_16x16x32_bf16 v[104:107], v[136:139], v[214:217], v[104:107]
	v_mfma_f32_16x16x32_bf16 v[96:99], v[128:131], v[226:229], v[96:99]
	v_mfma_f32_16x16x32_bf16 v[88:91], v[136:139], v[226:229], v[88:91]
	v_mfma_f32_16x16x32_bf16 v[80:83], v[128:131], v[234:237], v[80:83]
	v_mfma_f32_16x16x32_bf16 v[72:75], v[136:139], v[234:237], v[72:75]
	v_mfma_f32_16x16x32_bf16 v[124:127], v[132:135], v[210:213], v[124:127]
	v_mfma_f32_16x16x32_bf16 v[120:123], v[140:143], v[210:213], v[120:123]
	v_mfma_f32_16x16x32_bf16 v[108:111], v[132:135], v[218:221], v[108:111]
	v_mfma_f32_16x16x32_bf16 v[104:107], v[140:143], v[218:221], v[104:107]
	v_mfma_f32_16x16x32_bf16 v[96:99], v[132:135], v[230:233], v[96:99]
	v_mfma_f32_16x16x32_bf16 v[88:91], v[140:143], v[230:233], v[88:91]
	v_mfma_f32_16x16x32_bf16 v[80:83], v[132:135], v[238:241], v[80:83]
	v_mfma_f32_16x16x32_bf16 v[72:75], v[140:143], v[238:241], v[72:75]
	v_mfma_f32_16x16x32_bf16 v[116:119], v[190:193], v[206:209], v[116:119]
	v_mfma_f32_16x16x32_bf16 v[112:115], v[198:201], v[206:209], v[112:115]
	v_mfma_f32_16x16x32_bf16 v[100:103], v[190:193], v[214:217], v[100:103]
	v_mfma_f32_16x16x32_bf16 v[92:95], v[198:201], v[214:217], v[92:95]
	v_mfma_f32_16x16x32_bf16 v[84:87], v[190:193], v[226:229], v[84:87]
	v_mfma_f32_16x16x32_bf16 v[76:79], v[198:201], v[226:229], v[76:79]
	v_mfma_f32_16x16x32_bf16 v[68:71], v[190:193], v[234:237], v[68:71]
	v_mfma_f32_16x16x32_bf16 v[64:67], v[198:201], v[234:237], v[64:67]
	v_mfma_f32_16x16x32_bf16 v[116:119], v[194:197], v[210:213], v[116:119]
	v_mfma_f32_16x16x32_bf16 v[112:115], v[202:205], v[210:213], v[112:115]
	v_mfma_f32_16x16x32_bf16 v[100:103], v[194:197], v[218:221], v[100:103]
	v_mfma_f32_16x16x32_bf16 v[92:95], v[202:205], v[218:221], v[92:95]
	v_mfma_f32_16x16x32_bf16 v[84:87], v[194:197], v[230:233], v[84:87]
	v_mfma_f32_16x16x32_bf16 v[76:79], v[202:205], v[230:233], v[76:79]
	v_mfma_f32_16x16x32_bf16 v[68:71], v[194:197], v[238:241], v[68:71]
	v_mfma_f32_16x16x32_bf16 v[64:67], v[202:205], v[238:241], v[64:67]
	s_setprio 0
	s_barrier
	s_add_i32 s73, s70, s55
	v_lshl_add_u64 v[184:185], s[44:45], 0, v[144:145]
	s_mov_b32 m0, s73
	ds_read_b128 v[206:209], v186 offset:16384
	ds_read_b128 v[210:213], v186 offset:17408
	ds_read_b128 v[214:217], v186 offset:18432
	ds_read_b128 v[218:221], v186 offset:19456
	ds_read_b128 v[226:229], v186 offset:20480
	ds_read_b128 v[230:233], v186 offset:21504
	ds_read_b128 v[234:237], v186 offset:22528
	ds_read_b128 v[238:241], v186 offset:23552
	global_load_lds_dwordx4 v[184:185], off
	s_add_i32 m0, s73, 0x2000
	s_add_u32 s74, s44, 0x200000
	v_lshl_add_u64 v[184:185], s[44:45], 0, v[146:147]
	s_addc_u32 s75, s45, 0
	s_add_i32 s73, s71, s55
	global_load_lds_dwordx4 v[184:185], off
	v_lshl_add_u64 v[184:185], s[74:75], 0, v[144:145]
	s_mov_b32 m0, s73
	s_nop 0
	global_load_lds_dwordx4 v[184:185], off
	v_lshl_add_u64 v[184:185], s[74:75], 0, v[146:147]
	s_add_i32 m0, s73, 0x2000
	s_nop 0
	global_load_lds_dwordx4 v[184:185], off
	v_lshl_add_u64 v[184:185], s[52:53], 0, v[144:145]
	s_mov_b32 m0, s56
	s_nop 0
	global_load_lds_dwordx4 v[184:185], off
	v_lshl_add_u64 v[184:185], s[52:53], 0, v[146:147]
	s_mov_b32 m0, s57
	s_nop 0
	global_load_lds_dwordx4 v[184:185], off
	s_waitcnt vmcnt(8)
	s_waitcnt lgkmcnt(0)
	s_barrier
; #define PG8_LDA(dst, b, h) do { _Pragma("unroll") for (int m = 0; m < 4; ++m) _Pragma("unroll") for (int k = 0; k < 2; ++k) dst[m][k] = *(const LAS bf16x8*)(lds + PG8_SA(b, h) + aoff + m * 2048 + k * 1024); } while (0)
; #define PG8_LDB(dst, b, h) do { _Pragma("unroll") for (int n = 0; n < 2; ++n) _Pragma("unroll") for (int k = 0; k < 2; ++k) dst[n][k] = *(const LAS bf16x8*)(lds + PG8_SB(b, h) + boff + n * 2048 + k * 1024); } while (0)
; #define PG8_MMA(ai, bj, At, Bt) do { __builtin_amdgcn_s_setprio(1); _Pragma("unroll") for (int m = 0; m < 4; ++m) _Pragma("unroll") for (int n = 0; n < 2; ++n) _Pragma("unroll") for (int k = 0; k < 2; ++k) \
;         acc[ai][bj][m][n] = __builtin_amdgcn_mfma_f32_16x16x32_bf16(Bt[n][k], At[m][k], acc[ai][bj][m][n], 0, 0, 0); __builtin_amdgcn_s_setprio(0); } while (0)
; #define PG8_WAIT_V(n) asm volatile("s_waitcnt vmcnt(" #n ")" ::: "memory")
; #define PG8_WAIT_L(n) asm volatile("s_waitcnt lgkmcnt(" #n ")" ::: "memory")
; #define PG8_BAR __builtin_amdgcn_s_barrier()
; #define PG8_SCHED __builtin_amdgcn_sched_barrier(0)
; __device__ __forceinline__ void gemm_phase(LAS unsigned char* lds, const GemmP& g) {
;     ...
;             PG8_WAIT_V(8); PG8_WAIT_L(0); PG8_BAR; PG8_MMA(1, 0, At, B0); PG8_MMA(1, 1, At, B1); PG8_BAR; PG8_SCHED;
;             PG8_LDB(B0, 1, 0); PG8_LDB(B1, 1, 1); PG8_SCHED; PG8_LDA(At, 1, 0); PG8_STAGE(PG8_SA(0, 1), a2 + hstepA, voffA);
;             PG8_WAIT_V(8); PG8_WAIT_L(0); PG8_BAR; PG8_MMA(0, 0, At, B0); PG8_MMA(0, 1, At, B1); PG8_BAR; PG8_SCHED;
	s_setprio 1
	s_waitcnt lgkmcnt(0)
	v_mfma_f32_16x16x32_bf16 v[60:63], v[128:131], v[206:209], v[60:63]
	v_mfma_f32_16x16x32_bf16 v[56:59], v[136:139], v[206:209], v[56:59]
	v_mfma_f32_16x16x32_bf16 v[48:51], v[128:131], v[214:217], v[48:51]
	v_mfma_f32_16x16x32_bf16 v[40:43], v[136:139], v[214:217], v[40:43]
	v_mfma_f32_16x16x32_bf16 v[32:35], v[128:131], v[226:229], v[32:35]
	v_mfma_f32_16x16x32_bf16 v[24:27], v[136:139], v[226:229], v[24:27]
	v_mfma_f32_16x16x32_bf16 v[16:19], v[128:131], v[234:237], v[16:19]
	v_mfma_f32_16x16x32_bf16 v[8:11], v[136:139], v[234:237], v[8:11]
	v_mfma_f32_16x16x32_bf16 v[60:63], v[132:135], v[210:213], v[60:63]
	v_mfma_f32_16x16x32_bf16 v[56:59], v[140:143], v[210:213], v[56:59]
	v_mfma_f32_16x16x32_bf16 v[48:51], v[132:135], v[218:221], v[48:51]
	v_mfma_f32_16x16x32_bf16 v[40:43], v[140:143], v[218:221], v[40:43]
	v_mfma_f32_16x16x32_bf16 v[32:35], v[132:135], v[230:233], v[32:35]
	v_mfma_f32_16x16x32_bf16 v[24:27], v[140:143], v[230:233], v[24:27]
	v_mfma_f32_16x16x32_bf16 v[16:19], v[132:135], v[238:241], v[16:19]
	v_mfma_f32_16x16x32_bf16 v[8:11], v[140:143], v[238:241], v[8:11]
	v_mfma_f32_16x16x32_bf16 v[52:55], v[190:193], v[206:209], v[52:55]
	v_mfma_f32_16x16x32_bf16 v[44:47], v[198:201], v[206:209], v[44:47]
	v_mfma_f32_16x16x32_bf16 v[36:39], v[190:193], v[214:217], v[36:39]
	v_mfma_f32_16x16x32_bf16 v[28:31], v[198:201], v[214:217], v[28:31]
	v_mfma_f32_16x16x32_bf16 v[20:23], v[190:193], v[226:229], v[20:23]
	v_mfma_f32_16x16x32_bf16 v[12:15], v[198:201], v[226:229], v[12:15]
	v_mfma_f32_16x16x32_bf16 v[4:7], v[190:193], v[234:237], v[4:7]
	v_mfma_f32_16x16x32_bf16 v[0:3], v[198:201], v[234:237], v[0:3]
	v_mfma_f32_16x16x32_bf16 v[52:55], v[194:197], v[210:213], v[52:55]
	v_mfma_f32_16x16x32_bf16 v[44:47], v[202:205], v[210:213], v[44:47]
	v_mfma_f32_16x16x32_bf16 v[36:39], v[194:197], v[218:221], v[36:39]
	v_mfma_f32_16x16x32_bf16 v[28:31], v[202:205], v[218:221], v[28:31]
	v_mfma_f32_16x16x32_bf16 v[20:23], v[194:197], v[230:233], v[20:23]
	v_mfma_f32_16x16x32_bf16 v[12:15], v[202:205], v[230:233], v[12:15]
	v_mfma_f32_16x16x32_bf16 v[4:7], v[194:197], v[238:241], v[4:7]
	v_mfma_f32_16x16x32_bf16 v[0:3], v[202:205], v[238:241], v[0:3]
	s_setprio 0
	s_barrier
	s_add_i32 s73, 0, 0x18000
	s_add_i32 s74, 0, 0x1c000
	v_add_u32_e32 v140, s73, v149
	v_add_u32_e32 v184, s74, v149
	ds_read_b128 v[128:131], v140
	ds_read_b128 v[132:135], v140 offset:1024
	ds_read_b128 v[136:139], v140 offset:2048
	ds_read_b128 v[140:143], v140 offset:3072
	ds_read_b128 v[190:193], v184
	ds_read_b128 v[194:197], v184 offset:1024
	ds_read_b128 v[198:201], v184 offset:2048
	ds_read_b128 v[202:205], v184 offset:3072
	s_add_u32 s52, s52, 0x200000
	s_addc_u32 s53, s53, 0
	s_mov_b32 m0, s58
	v_lshl_add_u64 v[184:185], s[52:53], 0, v[144:145]
	ds_read_b128 v[206:209], v186 offset:32768
	ds_read_b128 v[210:213], v186 offset:33792
	ds_read_b128 v[214:217], v186 offset:34816
	ds_read_b128 v[218:221], v186 offset:35840
	ds_read_b128 v[226:229], v186 offset:36864
	ds_read_b128 v[230:233], v186 offset:37888
	ds_read_b128 v[234:237], v186 offset:38912
	ds_read_b128 v[238:241], v186 offset:39936
	global_load_lds_dwordx4 v[184:185], off
	v_lshl_add_u64 v[184:185], s[52:53], 0, v[146:147]
	s_mov_b32 m0, s59
	s_nop 0
	global_load_lds_dwordx4 v[184:185], off
	s_waitcnt vmcnt(8)
	s_waitcnt lgkmcnt(0)
	s_barrier
	s_setprio 1
	s_waitcnt lgkmcnt(0)
	v_mfma_f32_16x16x32_bf16 v[124:127], v[128:131], v[206:209], v[124:127]
	v_mfma_f32_16x16x32_bf16 v[120:123], v[136:139], v[206:209], v[120:123]
	v_mfma_f32_16x16x32_bf16 v[108:111], v[128:131], v[214:217], v[108:111]
	v_mfma_f32_16x16x32_bf16 v[104:107], v[136:139], v[214:217], v[104:107]
	v_mfma_f32_16x16x32_bf16 v[96:99], v[128:131], v[226:229], v[96:99]
	v_mfma_f32_16x16x32_bf16 v[88:91], v[136:139], v[226:229], v[88:91]
	v_mfma_f32_16x16x32_bf16 v[80:83], v[128:131], v[234:237], v[80:83]
	v_mfma_f32_16x16x32_bf16 v[72:75], v[136:139], v[234:237], v[72:75]
	v_mfma_f32_16x16x32_bf16 v[124:127], v[132:135], v[210:213], v[124:127]
	v_mfma_f32_16x16x32_bf16 v[120:123], v[140:143], v[210:213], v[120:123]
	v_mfma_f32_16x16x32_bf16 v[108:111], v[132:135], v[218:221], v[108:111]
	v_mfma_f32_16x16x32_bf16 v[104:107], v[140:143], v[218:221], v[104:107]
	v_mfma_f32_16x16x32_bf16 v[96:99], v[132:135], v[230:233], v[96:99]
	v_mfma_f32_16x16x32_bf16 v[88:91], v[140:143], v[230:233], v[88:91]
	v_mfma_f32_16x16x32_bf16 v[80:83], v[132:135], v[238:241], v[80:83]
	v_mfma_f32_16x16x32_bf16 v[72:75], v[140:143], v[238:241], v[72:75]
	v_mfma_f32_16x16x32_bf16 v[116:119], v[190:193], v[206:209], v[116:119]
	v_mfma_f32_16x16x32_bf16 v[112:115], v[198:201], v[206:209], v[112:115]
	v_mfma_f32_16x16x32_bf16 v[100:103], v[190:193], v[214:217], v[100:103]
	v_mfma_f32_16x16x32_bf16 v[92:95], v[198:201], v[214:217], v[92:95]
	v_mfma_f32_16x16x32_bf16 v[84:87], v[190:193], v[226:229], v[84:87]
	v_mfma_f32_16x16x32_bf16 v[76:79], v[198:201], v[226:229], v[76:79]
	v_mfma_f32_16x16x32_bf16 v[68:71], v[190:193], v[234:237], v[68:71]
	v_mfma_f32_16x16x32_bf16 v[64:67], v[198:201], v[234:237], v[64:67]
	v_mfma_f32_16x16x32_bf16 v[116:119], v[194:197], v[210:213], v[116:119]
	v_mfma_f32_16x16x32_bf16 v[112:115], v[202:205], v[210:213], v[112:115]
	v_mfma_f32_16x16x32_bf16 v[100:103], v[194:197], v[218:221], v[100:103]
	v_mfma_f32_16x16x32_bf16 v[92:95], v[202:205], v[218:221], v[92:95]
	v_mfma_f32_16x16x32_bf16 v[84:87], v[194:197], v[230:233], v[84:87]
	v_mfma_f32_16x16x32_bf16 v[76:79], v[202:205], v[230:233], v[76:79]
	v_mfma_f32_16x16x32_bf16 v[68:71], v[194:197], v[238:241], v[68:71]
	v_mfma_f32_16x16x32_bf16 v[64:67], v[202:205], v[238:241], v[64:67]
	s_setprio 0
	s_barrier
; #define PG8_LDA(dst, b, h) do { _Pragma("unroll") for (int m = 0; m < 4; ++m) _Pragma("unroll") for (int k = 0; k < 2; ++k) dst[m][k] = *(const LAS bf16x8*)(lds + PG8_SA(b, h) + aoff + m * 2048 + k * 1024); } while (0)
; #define PG8_MMA(ai, bj, At, Bt) do { __builtin_amdgcn_s_setprio(1); _Pragma("unroll") for (int m = 0; m < 4; ++m) _Pragma("unroll") for (int n = 0; n < 2; ++n) _Pragma("unroll") for (int k = 0; k < 2; ++k) \
;         acc[ai][bj][m][n] = __builtin_amdgcn_mfma_f32_16x16x32_bf16(Bt[n][k], At[m][k], acc[ai][bj][m][n], 0, 0, 0); __builtin_amdgcn_s_setprio(0); } while (0)
; #define PG8_WAIT_V(n) asm volatile("s_waitcnt vmcnt(" #n ")" ::: "memory")
; #define PG8_WAIT_L(n) asm volatile("s_waitcnt lgkmcnt(" #n ")" ::: "memory")
; #define PG8_BAR __builtin_amdgcn_s_barrier()
; #define PG8_SCHED __builtin_amdgcn_sched_barrier(0)
; __device__ __forceinline__ void gemm_phase(LAS unsigned char* lds, const GemmP& g) {
;     ...
;             PG8_LDA(At, 1, 1); PG8_STAGE(PG8_SB(1, 0), b3, voffB); PG8_STAGE(PG8_SB(1, 1), b3 + hstepB, voffB); PG8_STAGE(PG8_SA(1, 0), a3, voffA);
;             PG8_WAIT_V(8); PG8_WAIT_L(0); PG8_BAR; PG8_MMA(1, 0, At, B0); PG8_MMA(1, 1, At, B1); PG8_BAR; PG8_SCHED;
;         }
;         if (wr == 0) PG8_BAR;
	s_add_u32 s52, s44, 0x80
	s_addc_u32 s53, s45, 0
	s_add_i32 s73, s73, s55
	v_lshl_add_u64 v[184:185], s[52:53], 0, v[144:145]
	s_mov_b32 m0, s73
	ds_read_b128 v[206:209], v186 offset:49152
	ds_read_b128 v[210:213], v186 offset:50176
	ds_read_b128 v[214:217], v186 offset:51200
	ds_read_b128 v[218:221], v186 offset:52224
	ds_read_b128 v[226:229], v186 offset:53248
	ds_read_b128 v[230:233], v186 offset:54272
	ds_read_b128 v[234:237], v186 offset:55296
	ds_read_b128 v[238:241], v186 offset:56320
	global_load_lds_dwordx4 v[184:185], off
	s_add_i32 m0, s73, 0x2000
	s_add_u32 s44, s44, 0x200080
	v_lshl_add_u64 v[184:185], s[52:53], 0, v[146:147]
	s_addc_u32 s45, s45, 0
	s_add_i32 s52, s74, s55
	global_load_lds_dwordx4 v[184:185], off
	v_lshl_add_u64 v[184:185], s[44:45], 0, v[144:145]
	s_mov_b32 m0, s52
	s_nop 0
	global_load_lds_dwordx4 v[184:185], off
	v_lshl_add_u64 v[184:185], s[44:45], 0, v[146:147]
	s_add_i32 m0, s52, 0x2000
	s_nop 0
	global_load_lds_dwordx4 v[184:185], off
	v_lshl_add_u64 v[184:185], s[42:43], 0, v[144:145]
	s_mov_b32 m0, s63
	s_nop 0
	global_load_lds_dwordx4 v[184:185], off
	v_lshl_add_u64 v[184:185], s[42:43], 0, v[146:147]
	s_mov_b32 m0, s68
	s_nop 0
	global_load_lds_dwordx4 v[184:185], off
	s_waitcnt vmcnt(8)
	s_waitcnt lgkmcnt(0)
	s_barrier
	s_setprio 1
	s_waitcnt lgkmcnt(0)
	v_mfma_f32_16x16x32_bf16 v[60:63], v[128:131], v[206:209], v[60:63]
	v_mfma_f32_16x16x32_bf16 v[56:59], v[136:139], v[206:209], v[56:59]
	v_mfma_f32_16x16x32_bf16 v[48:51], v[128:131], v[214:217], v[48:51]
	v_mfma_f32_16x16x32_bf16 v[40:43], v[136:139], v[214:217], v[40:43]
	v_mfma_f32_16x16x32_bf16 v[32:35], v[128:131], v[226:229], v[32:35]
	v_mfma_f32_16x16x32_bf16 v[24:27], v[136:139], v[226:229], v[24:27]
	v_mfma_f32_16x16x32_bf16 v[16:19], v[128:131], v[234:237], v[16:19]
	v_mfma_f32_16x16x32_bf16 v[8:11], v[136:139], v[234:237], v[8:11]
	v_mfma_f32_16x16x32_bf16 v[60:63], v[132:135], v[210:213], v[60:63]
	v_mfma_f32_16x16x32_bf16 v[56:59], v[140:143], v[210:213], v[56:59]
	v_mfma_f32_16x16x32_bf16 v[48:51], v[132:135], v[218:221], v[48:51]
	v_mfma_f32_16x16x32_bf16 v[40:43], v[140:143], v[218:221], v[40:43]
	v_mfma_f32_16x16x32_bf16 v[32:35], v[132:135], v[230:233], v[32:35]
	v_mfma_f32_16x16x32_bf16 v[24:27], v[140:143], v[230:233], v[24:27]
	v_mfma_f32_16x16x32_bf16 v[16:19], v[132:135], v[238:241], v[16:19]
	v_mfma_f32_16x16x32_bf16 v[8:11], v[140:143], v[238:241], v[8:11]
	v_mfma_f32_16x16x32_bf16 v[52:55], v[190:193], v[206:209], v[52:55]
	v_mfma_f32_16x16x32_bf16 v[44:47], v[198:201], v[206:209], v[44:47]
	v_mfma_f32_16x16x32_bf16 v[36:39], v[190:193], v[214:217], v[36:39]
	v_mfma_f32_16x16x32_bf16 v[28:31], v[198:201], v[214:217], v[28:31]
	v_mfma_f32_16x16x32_bf16 v[20:23], v[190:193], v[226:229], v[20:23]
	v_mfma_f32_16x16x32_bf16 v[12:15], v[198:201], v[226:229], v[12:15]
	v_mfma_f32_16x16x32_bf16 v[4:7], v[190:193], v[234:237], v[4:7]
	v_mfma_f32_16x16x32_bf16 v[0:3], v[198:201], v[234:237], v[0:3]
	v_mfma_f32_16x16x32_bf16 v[52:55], v[194:197], v[210:213], v[52:55]
	v_mfma_f32_16x16x32_bf16 v[44:47], v[202:205], v[210:213], v[44:47]
	v_mfma_f32_16x16x32_bf16 v[36:39], v[194:197], v[218:221], v[36:39]
	v_mfma_f32_16x16x32_bf16 v[28:31], v[202:205], v[218:221], v[28:31]
	v_mfma_f32_16x16x32_bf16 v[20:23], v[194:197], v[230:233], v[20:23]
	v_mfma_f32_16x16x32_bf16 v[12:15], v[202:205], v[230:233], v[12:15]
	v_mfma_f32_16x16x32_bf16 v[4:7], v[194:197], v[238:241], v[4:7]
	v_mfma_f32_16x16x32_bf16 v[0:3], v[202:205], v[238:241], v[0:3]
	s_setprio 0
	s_barrier
	s_add_i32 s72, s72, 2
	s_add_u32 s20, s20, 0x100
	s_addc_u32 s21, s21, 0
	s_add_u32 s30, s30, 0x100
	s_addc_u32 s31, s31, 0
	s_add_u32 s40, s40, 0x100
	s_addc_u32 s41, s41, 0
	s_cmpk_gt_u32 s72, 0x7d
	s_cbranch_scc0 .LBB0_927
	s_and_b64 vcc, exec, s[4:5]
	s_cbranch_vccz .LBB0_930
	s_barrier

; #define PG8_LDA(dst, b, h) do { _Pragma("unroll") for (int m = 0; m < 4; ++m) _Pragma("unroll") for (int k = 0; k < 2; ++k) dst[m][k] = *(const LAS bf16x8*)(lds + PG8_SA(b, h) + aoff + m * 2048 + k * 1024); } while (0)
; #define PG8_LDB(dst, b, h) do { _Pragma("unroll") for (int n = 0; n < 2; ++n) _Pragma("unroll") for (int k = 0; k < 2; ++k) dst[n][k] = *(const LAS bf16x8*)(lds + PG8_SB(b, h) + boff + n * 2048 + k * 1024); } while (0)
; #define PG8_MMA(ai, bj, At, Bt) do { __builtin_amdgcn_s_setprio(1); _Pragma("unroll") for (int m = 0; m < 4; ++m) _Pragma("unroll") for (int n = 0; n < 2; ++n) _Pragma("unroll") for (int k = 0; k < 2; ++k) \
;         acc[ai][bj][m][n] = __builtin_amdgcn_mfma_f32_16x16x32_bf16(Bt[n][k], At[m][k], acc[ai][bj][m][n], 0, 0, 0); __builtin_amdgcn_s_setprio(0); } while (0)
; #define PG8_WAIT_V(n) asm volatile("s_waitcnt vmcnt(" #n ")" ::: "memory")
; #define PG8_WAIT_L(n) asm volatile("s_waitcnt lgkmcnt(" #n ")" ::: "memory")
; #define PG8_BAR __builtin_amdgcn_s_barrier()
; #define PG8_SCHED __builtin_amdgcn_sched_barrier(0)
; __device__ __forceinline__ void gemm_phase(LAS unsigned char* lds, const GemmP& g) {
;     ...
;         for (int t = 0; t < nt; t += 2) {
;             const bool last = (t == nt - 2);
;             const char* a1 = cA + (size_t)(t + 1) * kstep;
;             const char* a2 = last ? nA : cA + (size_t)(t + 2) * kstep; const char* b2 = last ? nB : cB + (size_t)(t + 2) * kstep;
;             const char* a3 = a2 + kstep; const char* b3 = b2 + kstep;
;             PG8_LDB(B0, 0, 0); PG8_LDB(B1, 0, 1); PG8_SCHED; PG8_LDA(At, 0, 0); PG8_STAGE(PG8_SA(1, 1), a1 + hstepA, voffA);
;             PG8_WAIT_V(8); PG8_WAIT_L(0); PG8_BAR; PG8_MMA(0, 0, At, B0); PG8_MMA(0, 1, At, B1); PG8_BAR; PG8_SCHED;
;             PG8_LDA(At, 0, 1); PG8_STAGE(PG8_SB(0, 0), b2, voffB); PG8_STAGE(PG8_SB(0, 1), b2 + hstepB, voffB); PG8_STAGE(PG8_SA(0, 0), a2, voffA);
;             PG8_WAIT_V(8); PG8_WAIT_L(0); PG8_BAR; PG8_MMA(1, 0, At, B0); PG8_MMA(1, 1, At, B1); PG8_BAR; PG8_SCHED;
.LBB0_1100:
	s_add_u32 s31, s52, s30
	s_addc_u32 s41, s53, 0
	s_add_u32 s31, s31, 0x100
	s_addc_u32 s41, s41, 0
	s_and_b64 s[58:59], s[56:57], exec
	s_cselect_b32 s65, s7, s41
	s_cselect_b32 s64, s9, s31
	s_add_u32 s31, s10, s30
	s_addc_u32 s41, s11, 0
	s_add_u32 s31, s31, 0x100
	s_addc_u32 s41, s41, 0
	s_add_u32 s58, s64, 0x80
	s_addc_u32 s59, s65, 0
	s_and_b64 s[56:57], s[56:57], exec
	s_cselect_b32 s69, s43, s41
	s_cselect_b32 s68, s42, s31
	s_add_u32 s30, s19, s30
	s_addc_u32 s31, s21, 0
	s_add_u32 s72, s30, 0x80
	s_addc_u32 s73, s31, 0
	s_add_i32 s94, s84, s33
	s_add_i32 m0, s74, 0xc000
	s_add_i32 s95, s74, 0xe000
	s_add_i32 s91, s94, 0x2000
	ds_read_b128 v[154:157], v159
	ds_read_b128 v[162:165], v159 offset:1024
	ds_read_b128 v[166:169], v159 offset:2048
	ds_read_b128 v[170:173], v159 offset:3072
	ds_read_b128 v[174:177], v160
	ds_read_b128 v[178:181], v160 offset:1024
	ds_read_b128 v[182:185], v160 offset:2048
	ds_read_b128 v[186:189], v160 offset:3072
	s_add_u32 s70, s68, 0x80000
	s_addc_u32 s71, s69, 0
	s_add_i32 s90, s85, s33
	s_add_i32 s89, s90, 0x2000
	s_add_i32 s88, 0, 0x18000
	s_add_i32 s41, 0, 0x1c000
	s_add_u32 s62, s64, 0x10000
	s_addc_u32 s63, s65, 0
	s_add_u32 s60, s68, 0x80
	s_addc_u32 s61, s69, 0
	s_add_i32 s31, s88, s33
	s_add_i32 s30, s31, 0x2000
	s_add_u32 s56, s68, 0x80080
	s_addc_u32 s57, s69, 0
	s_add_i32 s93, s41, s33
	s_add_i32 s92, s93, 0x2000
	v_lshl_add_u64 v[222:223], s[72:73], 0, v[128:129]
	ds_read_b128 v[190:193], v161
	ds_read_b128 v[194:197], v161 offset:1024
	ds_read_b128 v[198:201], v161 offset:2048
	ds_read_b128 v[202:205], v161 offset:3072
	ds_read_b128 v[206:209], v161 offset:4096
	ds_read_b128 v[210:213], v161 offset:5120
	ds_read_b128 v[214:217], v161 offset:6144
	ds_read_b128 v[218:221], v161 offset:7168
	global_load_lds_dwordx4 v[222:223], off
	v_lshl_add_u64 v[222:223], s[72:73], 0, v[132:133]
	s_mov_b32 m0, s95
	s_nop 0
	global_load_lds_dwordx4 v[222:223], off
	s_waitcnt vmcnt(8)
	s_waitcnt lgkmcnt(0)
	s_barrier
	s_setprio 1
	s_waitcnt lgkmcnt(0)
	v_mfma_f32_16x16x32_bf16 v[124:127], v[154:157], v[190:193], v[124:127]
	v_mfma_f32_16x16x32_bf16 v[120:123], v[166:169], v[190:193], v[120:123]
	v_mfma_f32_16x16x32_bf16 v[116:119], v[154:157], v[198:201], v[116:119]
	v_mfma_f32_16x16x32_bf16 v[112:115], v[166:169], v[198:201], v[112:115]
	v_mfma_f32_16x16x32_bf16 v[100:103], v[154:157], v[206:209], v[100:103]
	v_mfma_f32_16x16x32_bf16 v[96:99], v[166:169], v[206:209], v[96:99]
	v_mfma_f32_16x16x32_bf16 v[84:87], v[154:157], v[214:217], v[84:87]
	v_mfma_f32_16x16x32_bf16 v[80:83], v[166:169], v[214:217], v[80:83]
	v_mfma_f32_16x16x32_bf16 v[124:127], v[162:165], v[194:197], v[124:127]
	v_mfma_f32_16x16x32_bf16 v[120:123], v[170:173], v[194:197], v[120:123]
	v_mfma_f32_16x16x32_bf16 v[116:119], v[162:165], v[202:205], v[116:119]
	v_mfma_f32_16x16x32_bf16 v[112:115], v[170:173], v[202:205], v[112:115]
	v_mfma_f32_16x16x32_bf16 v[100:103], v[162:165], v[210:213], v[100:103]
	v_mfma_f32_16x16x32_bf16 v[96:99], v[170:173], v[210:213], v[96:99]
	v_mfma_f32_16x16x32_bf16 v[84:87], v[162:165], v[218:221], v[84:87]
	v_mfma_f32_16x16x32_bf16 v[80:83], v[170:173], v[218:221], v[80:83]
	v_mfma_f32_16x16x32_bf16 v[108:111], v[174:177], v[190:193], v[108:111]
	v_mfma_f32_16x16x32_bf16 v[104:107], v[182:185], v[190:193], v[104:107]
	v_mfma_f32_16x16x32_bf16 v[92:95], v[174:177], v[198:201], v[92:95]
	v_mfma_f32_16x16x32_bf16 v[88:91], v[182:185], v[198:201], v[88:91]
	v_mfma_f32_16x16x32_bf16 v[76:79], v[174:177], v[206:209], v[76:79]
	v_mfma_f32_16x16x32_bf16 v[72:75], v[182:185], v[206:209], v[72:75]
	v_mfma_f32_16x16x32_bf16 v[68:71], v[174:177], v[214:217], v[68:71]
	v_mfma_f32_16x16x32_bf16 v[64:67], v[182:185], v[214:217], v[64:67]
	v_mfma_f32_16x16x32_bf16 v[108:111], v[178:181], v[194:197], v[108:111]
	v_mfma_f32_16x16x32_bf16 v[104:107], v[186:189], v[194:197], v[104:107]
	v_mfma_f32_16x16x32_bf16 v[92:95], v[178:181], v[202:205], v[92:95]
	v_mfma_f32_16x16x32_bf16 v[88:91], v[186:189], v[202:205], v[88:91]
	v_mfma_f32_16x16x32_bf16 v[76:79], v[178:181], v[210:213], v[76:79]
	v_mfma_f32_16x16x32_bf16 v[72:75], v[186:189], v[210:213], v[72:75]
	v_mfma_f32_16x16x32_bf16 v[68:71], v[178:181], v[218:221], v[68:71]
	v_mfma_f32_16x16x32_bf16 v[64:67], v[186:189], v[218:221], v[64:67]
	s_setprio 0
	s_barrier
	s_mov_b32 m0, s94
	v_lshl_add_u64 v[222:223], s[68:69], 0, v[130:131]
	ds_read_b128 v[190:193], v161 offset:16384
	ds_read_b128 v[194:197], v161 offset:17408
	ds_read_b128 v[198:201], v161 offset:18432
	ds_read_b128 v[202:205], v161 offset:19456
	ds_read_b128 v[206:209], v161 offset:20480
	ds_read_b128 v[210:213], v161 offset:21504
	ds_read_b128 v[214:217], v161 offset:22528
	ds_read_b128 v[218:221], v161 offset:23552
	global_load_lds_dwordx4 v[222:223], off
	v_lshl_add_u64 v[222:223], s[68:69], 0, v[134:135]
	s_mov_b32 m0, s91
	s_nop 0
	global_load_lds_dwordx4 v[222:223], off
	v_lshl_add_u64 v[222:223], s[70:71], 0, v[130:131]
	s_mov_b32 m0, s90
	s_nop 0
	global_load_lds_dwordx4 v[222:223], off
	v_lshl_add_u64 v[222:223], s[70:71], 0, v[134:135]
	s_mov_b32 m0, s89
	s_nop 0
	global_load_lds_dwordx4 v[222:223], off
	v_lshl_add_u64 v[222:223], s[64:65], 0, v[128:129]
	s_mov_b32 m0, s74
	s_nop 0
	global_load_lds_dwordx4 v[222:223], off
	v_lshl_add_u64 v[222:223], s[64:65], 0, v[132:133]
	s_mov_b32 m0, s75
	s_nop 0
	global_load_lds_dwordx4 v[222:223], off
	s_waitcnt vmcnt(8)
	s_waitcnt lgkmcnt(0)
	s_barrier
; #define PG8_LDA(dst, b, h) do { _Pragma("unroll") for (int m = 0; m < 4; ++m) _Pragma("unroll") for (int k = 0; k < 2; ++k) dst[m][k] = *(const LAS bf16x8*)(lds + PG8_SA(b, h) + aoff + m * 2048 + k * 1024); } while (0)
; #define PG8_LDB(dst, b, h) do { _Pragma("unroll") for (int n = 0; n < 2; ++n) _Pragma("unroll") for (int k = 0; k < 2; ++k) dst[n][k] = *(const LAS bf16x8*)(lds + PG8_SB(b, h) + boff + n * 2048 + k * 1024); } while (0)
; #define PG8_MMA(ai, bj, At, Bt) do { __builtin_amdgcn_s_setprio(1); _Pragma("unroll") for (int m = 0; m < 4; ++m) _Pragma("unroll") for (int n = 0; n < 2; ++n) _Pragma("unroll") for (int k = 0; k < 2; ++k) \
;         acc[ai][bj][m][n] = __builtin_amdgcn_mfma_f32_16x16x32_bf16(Bt[n][k], At[m][k], acc[ai][bj][m][n], 0, 0, 0); __builtin_amdgcn_s_setprio(0); } while (0)
; #define PG8_WAIT_V(n) asm volatile("s_waitcnt vmcnt(" #n ")" ::: "memory")
; #define PG8_WAIT_L(n) asm volatile("s_waitcnt lgkmcnt(" #n ")" ::: "memory")
; #define PG8_BAR __builtin_amdgcn_s_barrier()
; #define PG8_SCHED __builtin_amdgcn_sched_barrier(0)
; __device__ __forceinline__ void gemm_phase(LAS unsigned char* lds, const GemmP& g) {
;     ...
;             PG8_WAIT_V(8); PG8_WAIT_L(0); PG8_BAR; PG8_MMA(1, 0, At, B0); PG8_MMA(1, 1, At, B1); PG8_BAR; PG8_SCHED;
;             PG8_LDB(B0, 1, 0); PG8_LDB(B1, 1, 1); PG8_SCHED; PG8_LDA(At, 1, 0); PG8_STAGE(PG8_SA(0, 1), a2 + hstepA, voffA);
;             PG8_WAIT_V(8); PG8_WAIT_L(0); PG8_BAR; PG8_MMA(0, 0, At, B0); PG8_MMA(0, 1, At, B1); PG8_BAR; PG8_SCHED;
	s_setprio 1
	s_waitcnt lgkmcnt(0)
	v_mfma_f32_16x16x32_bf16 v[60:63], v[154:157], v[190:193], v[60:63]
	v_mfma_f32_16x16x32_bf16 v[56:59], v[166:169], v[190:193], v[56:59]
	v_mfma_f32_16x16x32_bf16 v[52:55], v[154:157], v[198:201], v[52:55]
	v_mfma_f32_16x16x32_bf16 v[48:51], v[166:169], v[198:201], v[48:51]
	v_mfma_f32_16x16x32_bf16 v[36:39], v[154:157], v[206:209], v[36:39]
	v_mfma_f32_16x16x32_bf16 v[32:35], v[166:169], v[206:209], v[32:35]
	v_mfma_f32_16x16x32_bf16 v[20:23], v[154:157], v[214:217], v[20:23]
	v_mfma_f32_16x16x32_bf16 v[16:19], v[166:169], v[214:217], v[16:19]
	v_mfma_f32_16x16x32_bf16 v[60:63], v[162:165], v[194:197], v[60:63]
	v_mfma_f32_16x16x32_bf16 v[56:59], v[170:173], v[194:197], v[56:59]
	v_mfma_f32_16x16x32_bf16 v[52:55], v[162:165], v[202:205], v[52:55]
	v_mfma_f32_16x16x32_bf16 v[48:51], v[170:173], v[202:205], v[48:51]
	v_mfma_f32_16x16x32_bf16 v[36:39], v[162:165], v[210:213], v[36:39]
	v_mfma_f32_16x16x32_bf16 v[32:35], v[170:173], v[210:213], v[32:35]
	v_mfma_f32_16x16x32_bf16 v[20:23], v[162:165], v[218:221], v[20:23]
	v_mfma_f32_16x16x32_bf16 v[16:19], v[170:173], v[218:221], v[16:19]
	v_mfma_f32_16x16x32_bf16 v[44:47], v[174:177], v[190:193], v[44:47]
	v_mfma_f32_16x16x32_bf16 v[40:43], v[182:185], v[190:193], v[40:43]
	v_mfma_f32_16x16x32_bf16 v[28:31], v[174:177], v[198:201], v[28:31]
	v_mfma_f32_16x16x32_bf16 v[24:27], v[182:185], v[198:201], v[24:27]
	v_mfma_f32_16x16x32_bf16 v[12:15], v[174:177], v[206:209], v[12:15]
	v_mfma_f32_16x16x32_bf16 v[8:11], v[182:185], v[206:209], v[8:11]
	v_mfma_f32_16x16x32_bf16 v[4:7], v[174:177], v[214:217], v[4:7]
	v_mfma_f32_16x16x32_bf16 v[0:3], v[182:185], v[214:217], v[0:3]
	v_mfma_f32_16x16x32_bf16 v[44:47], v[178:181], v[194:197], v[44:47]
	v_mfma_f32_16x16x32_bf16 v[40:43], v[186:189], v[194:197], v[40:43]
	v_mfma_f32_16x16x32_bf16 v[28:31], v[178:181], v[202:205], v[28:31]
	v_mfma_f32_16x16x32_bf16 v[24:27], v[186:189], v[202:205], v[24:27]
	v_mfma_f32_16x16x32_bf16 v[12:15], v[178:181], v[210:213], v[12:15]
	v_mfma_f32_16x16x32_bf16 v[8:11], v[186:189], v[210:213], v[8:11]
	v_mfma_f32_16x16x32_bf16 v[4:7], v[178:181], v[218:221], v[4:7]
	v_mfma_f32_16x16x32_bf16 v[0:3], v[186:189], v[218:221], v[0:3]
	s_setprio 0
	s_barrier
	v_add_u32_e32 v170, s88, v158
	v_add_u32_e32 v186, s41, v158
	ds_read_b128 v[154:157], v170
	ds_read_b128 v[162:165], v170 offset:1024
	ds_read_b128 v[166:169], v170 offset:2048
	ds_read_b128 v[170:173], v170 offset:3072
	ds_read_b128 v[174:177], v186
	ds_read_b128 v[178:181], v186 offset:1024
	ds_read_b128 v[182:185], v186 offset:2048
	ds_read_b128 v[186:189], v186 offset:3072
	s_mov_b32 m0, s76
	v_lshl_add_u64 v[222:223], s[62:63], 0, v[128:129]
	ds_read_b128 v[190:193], v161 offset:32768
	ds_read_b128 v[194:197], v161 offset:33792
	ds_read_b128 v[198:201], v161 offset:34816
	ds_read_b128 v[202:205], v161 offset:35840
	ds_read_b128 v[206:209], v161 offset:36864
	ds_read_b128 v[210:213], v161 offset:37888
	ds_read_b128 v[214:217], v161 offset:38912
	ds_read_b128 v[218:221], v161 offset:39936
	global_load_lds_dwordx4 v[222:223], off
	v_lshl_add_u64 v[222:223], s[62:63], 0, v[132:133]
	s_mov_b32 m0, s77
	s_nop 0
	global_load_lds_dwordx4 v[222:223], off
	s_waitcnt vmcnt(8)
	s_waitcnt lgkmcnt(0)
	s_barrier
	s_setprio 1
	s_waitcnt lgkmcnt(0)
	v_mfma_f32_16x16x32_bf16 v[124:127], v[154:157], v[190:193], v[124:127]
	v_mfma_f32_16x16x32_bf16 v[120:123], v[166:169], v[190:193], v[120:123]
	v_mfma_f32_16x16x32_bf16 v[116:119], v[154:157], v[198:201], v[116:119]
	v_mfma_f32_16x16x32_bf16 v[112:115], v[166:169], v[198:201], v[112:115]
	v_mfma_f32_16x16x32_bf16 v[100:103], v[154:157], v[206:209], v[100:103]
	v_mfma_f32_16x16x32_bf16 v[96:99], v[166:169], v[206:209], v[96:99]
	v_mfma_f32_16x16x32_bf16 v[84:87], v[154:157], v[214:217], v[84:87]
	v_mfma_f32_16x16x32_bf16 v[80:83], v[166:169], v[214:217], v[80:83]
	v_mfma_f32_16x16x32_bf16 v[124:127], v[162:165], v[194:197], v[124:127]
	v_mfma_f32_16x16x32_bf16 v[120:123], v[170:173], v[194:197], v[120:123]
	v_mfma_f32_16x16x32_bf16 v[116:119], v[162:165], v[202:205], v[116:119]
	v_mfma_f32_16x16x32_bf16 v[112:115], v[170:173], v[202:205], v[112:115]
	v_mfma_f32_16x16x32_bf16 v[100:103], v[162:165], v[210:213], v[100:103]
	v_mfma_f32_16x16x32_bf16 v[96:99], v[170:173], v[210:213], v[96:99]
	v_mfma_f32_16x16x32_bf16 v[84:87], v[162:165], v[218:221], v[84:87]
	v_mfma_f32_16x16x32_bf16 v[80:83], v[170:173], v[218:221], v[80:83]
	v_mfma_f32_16x16x32_bf16 v[108:111], v[174:177], v[190:193], v[108:111]
	v_mfma_f32_16x16x32_bf16 v[104:107], v[182:185], v[190:193], v[104:107]
	v_mfma_f32_16x16x32_bf16 v[92:95], v[174:177], v[198:201], v[92:95]
	v_mfma_f32_16x16x32_bf16 v[88:91], v[182:185], v[198:201], v[88:91]
	v_mfma_f32_16x16x32_bf16 v[76:79], v[174:177], v[206:209], v[76:79]
	v_mfma_f32_16x16x32_bf16 v[72:75], v[182:185], v[206:209], v[72:75]
	v_mfma_f32_16x16x32_bf16 v[68:71], v[174:177], v[214:217], v[68:71]
	v_mfma_f32_16x16x32_bf16 v[64:67], v[182:185], v[214:217], v[64:67]
	v_mfma_f32_16x16x32_bf16 v[108:111], v[178:181], v[194:197], v[108:111]
	v_mfma_f32_16x16x32_bf16 v[104:107], v[186:189], v[194:197], v[104:107]
	v_mfma_f32_16x16x32_bf16 v[92:95], v[178:181], v[202:205], v[92:95]
	v_mfma_f32_16x16x32_bf16 v[88:91], v[186:189], v[202:205], v[88:91]
	v_mfma_f32_16x16x32_bf16 v[76:79], v[178:181], v[210:213], v[76:79]
	v_mfma_f32_16x16x32_bf16 v[72:75], v[186:189], v[210:213], v[72:75]
	v_mfma_f32_16x16x32_bf16 v[68:71], v[178:181], v[218:221], v[68:71]
	v_mfma_f32_16x16x32_bf16 v[64:67], v[186:189], v[218:221], v[64:67]
	s_setprio 0
	s_barrier
; #define PG8_LDA(dst, b, h) do { _Pragma("unroll") for (int m = 0; m < 4; ++m) _Pragma("unroll") for (int k = 0; k < 2; ++k) dst[m][k] = *(const LAS bf16x8*)(lds + PG8_SA(b, h) + aoff + m * 2048 + k * 1024); } while (0)
; #define PG8_MMA(ai, bj, At, Bt) do { __builtin_amdgcn_s_setprio(1); _Pragma("unroll") for (int m = 0; m < 4; ++m) _Pragma("unroll") for (int n = 0; n < 2; ++n) _Pragma("unroll") for (int k = 0; k < 2; ++k) \
;         acc[ai][bj][m][n] = __builtin_amdgcn_mfma_f32_16x16x32_bf16(Bt[n][k], At[m][k], acc[ai][bj][m][n], 0, 0, 0); __builtin_amdgcn_s_setprio(0); } while (0)
; #define PG8_WAIT_V(n) asm volatile("s_waitcnt vmcnt(" #n ")" ::: "memory")
; #define PG8_WAIT_L(n) asm volatile("s_waitcnt lgkmcnt(" #n ")" ::: "memory")
; #define PG8_BAR __builtin_amdgcn_s_barrier()
; #define PG8_SCHED __builtin_amdgcn_sched_barrier(0)
; __device__ __forceinline__ void gemm_phase(LAS unsigned char* lds, const GemmP& g) {
;     ...
;             PG8_LDA(At, 1, 1); PG8_STAGE(PG8_SB(1, 0), b3, voffB); PG8_STAGE(PG8_SB(1, 1), b3 + hstepB, voffB); PG8_STAGE(PG8_SA(1, 0), a3, voffA);
;             PG8_WAIT_V(8); PG8_WAIT_L(0); PG8_BAR; PG8_MMA(1, 0, At, B0); PG8_MMA(1, 1, At, B1); PG8_BAR; PG8_SCHED;
;         }
;         if (wr == 0) PG8_BAR;
	s_mov_b32 m0, s31
	v_lshl_add_u64 v[222:223], s[60:61], 0, v[130:131]
	ds_read_b128 v[190:193], v161 offset:49152
	ds_read_b128 v[194:197], v161 offset:50176
	ds_read_b128 v[198:201], v161 offset:51200
	ds_read_b128 v[202:205], v161 offset:52224
	ds_read_b128 v[206:209], v161 offset:53248
	ds_read_b128 v[210:213], v161 offset:54272
	ds_read_b128 v[214:217], v161 offset:55296
	ds_read_b128 v[218:221], v161 offset:56320
	global_load_lds_dwordx4 v[222:223], off
	v_lshl_add_u64 v[222:223], s[60:61], 0, v[134:135]
	s_mov_b32 m0, s30
	s_nop 0
	global_load_lds_dwordx4 v[222:223], off
	v_lshl_add_u64 v[222:223], s[56:57], 0, v[130:131]
	s_mov_b32 m0, s93
	s_nop 0
	global_load_lds_dwordx4 v[222:223], off
	v_lshl_add_u64 v[222:223], s[56:57], 0, v[134:135]
	s_mov_b32 m0, s92
	s_nop 0
	global_load_lds_dwordx4 v[222:223], off
	v_lshl_add_u64 v[222:223], s[58:59], 0, v[128:129]
	s_mov_b32 m0, s81
	s_nop 0
	global_load_lds_dwordx4 v[222:223], off
	v_lshl_add_u64 v[222:223], s[58:59], 0, v[132:133]
	s_mov_b32 m0, s82
	s_nop 0
	global_load_lds_dwordx4 v[222:223], off
	s_waitcnt vmcnt(8)
	s_waitcnt lgkmcnt(0)
	s_barrier
	s_setprio 1
	s_waitcnt lgkmcnt(0)
	v_mfma_f32_16x16x32_bf16 v[60:63], v[154:157], v[190:193], v[60:63]
	v_mfma_f32_16x16x32_bf16 v[56:59], v[166:169], v[190:193], v[56:59]
	v_mfma_f32_16x16x32_bf16 v[52:55], v[154:157], v[198:201], v[52:55]
	v_mfma_f32_16x16x32_bf16 v[48:51], v[166:169], v[198:201], v[48:51]
	v_mfma_f32_16x16x32_bf16 v[36:39], v[154:157], v[206:209], v[36:39]
	v_mfma_f32_16x16x32_bf16 v[32:35], v[166:169], v[206:209], v[32:35]
	v_mfma_f32_16x16x32_bf16 v[20:23], v[154:157], v[214:217], v[20:23]
	v_mfma_f32_16x16x32_bf16 v[16:19], v[166:169], v[214:217], v[16:19]
	v_mfma_f32_16x16x32_bf16 v[60:63], v[162:165], v[194:197], v[60:63]
	v_mfma_f32_16x16x32_bf16 v[56:59], v[170:173], v[194:197], v[56:59]
	v_mfma_f32_16x16x32_bf16 v[52:55], v[162:165], v[202:205], v[52:55]
	v_mfma_f32_16x16x32_bf16 v[48:51], v[170:173], v[202:205], v[48:51]
	v_mfma_f32_16x16x32_bf16 v[36:39], v[162:165], v[210:213], v[36:39]
	v_mfma_f32_16x16x32_bf16 v[32:35], v[170:173], v[210:213], v[32:35]
	v_mfma_f32_16x16x32_bf16 v[20:23], v[162:165], v[218:221], v[20:23]
	v_mfma_f32_16x16x32_bf16 v[16:19], v[170:173], v[218:221], v[16:19]
	v_mfma_f32_16x16x32_bf16 v[44:47], v[174:177], v[190:193], v[44:47]
	v_mfma_f32_16x16x32_bf16 v[40:43], v[182:185], v[190:193], v[40:43]
	v_mfma_f32_16x16x32_bf16 v[28:31], v[174:177], v[198:201], v[28:31]
	v_mfma_f32_16x16x32_bf16 v[24:27], v[182:185], v[198:201], v[24:27]
	v_mfma_f32_16x16x32_bf16 v[12:15], v[174:177], v[206:209], v[12:15]
	v_mfma_f32_16x16x32_bf16 v[8:11], v[182:185], v[206:209], v[8:11]
	v_mfma_f32_16x16x32_bf16 v[4:7], v[174:177], v[214:217], v[4:7]
	v_mfma_f32_16x16x32_bf16 v[0:3], v[182:185], v[214:217], v[0:3]
	v_mfma_f32_16x16x32_bf16 v[44:47], v[178:181], v[194:197], v[44:47]
	v_mfma_f32_16x16x32_bf16 v[40:43], v[186:189], v[194:197], v[40:43]
	v_mfma_f32_16x16x32_bf16 v[28:31], v[178:181], v[202:205], v[28:31]
	v_mfma_f32_16x16x32_bf16 v[24:27], v[186:189], v[202:205], v[24:27]
	v_mfma_f32_16x16x32_bf16 v[12:15], v[178:181], v[210:213], v[12:15]
	v_mfma_f32_16x16x32_bf16 v[8:11], v[186:189], v[210:213], v[8:11]
	v_mfma_f32_16x16x32_bf16 v[4:7], v[178:181], v[218:221], v[4:7]
	v_mfma_f32_16x16x32_bf16 v[0:3], v[186:189], v[218:221], v[0:3]
	s_setprio 0
	s_barrier
	s_movk_i32 s30, 0x100
	s_andn2_b64 vcc, exec, s[54:55]
	s_mov_b64 s[56:57], -1
	s_mov_b64 s[54:55], 0
	s_cbranch_vccz .LBB0_1100
	s_and_b64 vcc, exec, s[16:17]
	s_cbranch_vccz .LBB0_1103
	s_barrier

; #define PG8_LDA(dst, b, h) do { _Pragma("unroll") for (int m = 0; m < 4; ++m) _Pragma("unroll") for (int k = 0; k < 2; ++k) dst[m][k] = *(const LAS bf16x8*)(lds + PG8_SA(b, h) + aoff + m * 2048 + k * 1024); } while (0)
; #define PG8_LDB(dst, b, h) do { _Pragma("unroll") for (int n = 0; n < 2; ++n) _Pragma("unroll") for (int k = 0; k < 2; ++k) dst[n][k] = *(const LAS bf16x8*)(lds + PG8_SB(b, h) + boff + n * 2048 + k * 1024); } while (0)
; #define PG8_MMA(ai, bj, At, Bt) do { __builtin_amdgcn_s_setprio(1); _Pragma("unroll") for (int m = 0; m < 4; ++m) _Pragma("unroll") for (int n = 0; n < 2; ++n) _Pragma("unroll") for (int k = 0; k < 2; ++k) \
;         acc[ai][bj][m][n] = __builtin_amdgcn_mfma_f32_16x16x32_bf16(Bt[n][k], At[m][k], acc[ai][bj][m][n], 0, 0, 0); __builtin_amdgcn_s_setprio(0); } while (0)
; #define PG8_WAIT_V(n) asm volatile("s_waitcnt vmcnt(" #n ")" ::: "memory")
; #define PG8_WAIT_L(n) asm volatile("s_waitcnt lgkmcnt(" #n ")" ::: "memory")
; #define PG8_BAR __builtin_amdgcn_s_barrier()
; #define PG8_SCHED __builtin_amdgcn_sched_barrier(0)
; __device__ __forceinline__ void gemm_phase(LAS unsigned char* lds, const GemmP& g) {
;     ...
;         for (int t = 0; t < nt; t += 2) {
;             const bool last = (t == nt - 2);
;             const char* a1 = cA + (size_t)(t + 1) * kstep;
;             const char* a2 = last ? nA : cA + (size_t)(t + 2) * kstep; const char* b2 = last ? nB : cB + (size_t)(t + 2) * kstep;
;             const char* a3 = a2 + kstep; const char* b3 = b2 + kstep;
;             PG8_LDB(B0, 0, 0); PG8_LDB(B1, 0, 1); PG8_SCHED; PG8_LDA(At, 0, 0); PG8_STAGE(PG8_SA(1, 1), a1 + hstepA, voffA);
;             PG8_WAIT_V(8); PG8_WAIT_L(0); PG8_BAR; PG8_MMA(0, 0, At, B0); PG8_MMA(0, 1, At, B1); PG8_BAR; PG8_SCHED;
;             PG8_LDA(At, 0, 1); PG8_STAGE(PG8_SB(0, 0), b2, voffB); PG8_STAGE(PG8_SB(0, 1), b2 + hstepB, voffB); PG8_STAGE(PG8_SA(0, 0), a2, voffA);
;             PG8_WAIT_V(8); PG8_WAIT_L(0); PG8_BAR; PG8_MMA(1, 0, At, B0); PG8_MMA(1, 1, At, B1); PG8_BAR; PG8_SCHED;
.LBB0_1303:
	ds_read_b128 v[158:161], v155
	ds_read_b128 v[162:165], v155 offset:1024
	ds_read_b128 v[166:169], v155 offset:2048
	ds_read_b128 v[170:173], v155 offset:3072
	ds_read_b128 v[174:177], v156
	ds_read_b128 v[178:181], v156 offset:1024
	ds_read_b128 v[182:185], v156 offset:2048
	ds_read_b128 v[186:189], v156 offset:3072
	s_cmp_eq_u32 s72, 28
	s_cselect_b32 s56, s15, s17
	s_cselect_b32 s57, s11, s19
	s_cselect_b32 s54, s40, s70
	s_cselect_b32 s55, s41, s71
	s_add_u32 s52, s56, 0x80
	s_addc_u32 s53, s57, 0
	v_lshl_add_u64 v[222:223], s[44:45], 0, v[128:129]
	s_add_i32 m0, s30, 0xc000
	ds_read_b128 v[190:193], v157
	ds_read_b128 v[194:197], v157 offset:1024
	ds_read_b128 v[198:201], v157 offset:2048
	ds_read_b128 v[202:205], v157 offset:3072
	ds_read_b128 v[206:209], v157 offset:4096
	ds_read_b128 v[210:213], v157 offset:5120
	ds_read_b128 v[214:217], v157 offset:6144
	ds_read_b128 v[218:221], v157 offset:7168
	global_load_lds_dwordx4 v[222:223], off
	v_lshl_add_u64 v[222:223], s[44:45], 0, v[132:133]
	s_add_i32 m0, s30, 0xe000
	s_nop 0
	global_load_lds_dwordx4 v[222:223], off
	s_waitcnt vmcnt(8)
	s_waitcnt lgkmcnt(0)
	s_barrier
	s_setprio 1
	s_waitcnt lgkmcnt(0)
	v_mfma_f32_16x16x32_bf16 v[124:127], v[158:161], v[190:193], v[124:127]
	v_mfma_f32_16x16x32_bf16 v[120:123], v[166:169], v[190:193], v[120:123]
	v_mfma_f32_16x16x32_bf16 v[116:119], v[158:161], v[198:201], v[116:119]
	v_mfma_f32_16x16x32_bf16 v[108:111], v[166:169], v[198:201], v[108:111]
	v_mfma_f32_16x16x32_bf16 v[100:103], v[158:161], v[206:209], v[100:103]
	v_mfma_f32_16x16x32_bf16 v[92:95], v[166:169], v[206:209], v[92:95]
	v_mfma_f32_16x16x32_bf16 v[84:87], v[158:161], v[214:217], v[84:87]
	v_mfma_f32_16x16x32_bf16 v[76:79], v[166:169], v[214:217], v[76:79]
	v_mfma_f32_16x16x32_bf16 v[124:127], v[162:165], v[194:197], v[124:127]
	v_mfma_f32_16x16x32_bf16 v[120:123], v[170:173], v[194:197], v[120:123]
	v_mfma_f32_16x16x32_bf16 v[116:119], v[162:165], v[202:205], v[116:119]
	v_mfma_f32_16x16x32_bf16 v[108:111], v[170:173], v[202:205], v[108:111]
	v_mfma_f32_16x16x32_bf16 v[100:103], v[162:165], v[210:213], v[100:103]
	v_mfma_f32_16x16x32_bf16 v[92:95], v[170:173], v[210:213], v[92:95]
	v_mfma_f32_16x16x32_bf16 v[84:87], v[162:165], v[218:221], v[84:87]
	v_mfma_f32_16x16x32_bf16 v[76:79], v[170:173], v[218:221], v[76:79]
	v_mfma_f32_16x16x32_bf16 v[112:115], v[174:177], v[190:193], v[112:115]
	v_mfma_f32_16x16x32_bf16 v[104:107], v[182:185], v[190:193], v[104:107]
	v_mfma_f32_16x16x32_bf16 v[96:99], v[174:177], v[198:201], v[96:99]
	v_mfma_f32_16x16x32_bf16 v[88:91], v[182:185], v[198:201], v[88:91]
	v_mfma_f32_16x16x32_bf16 v[80:83], v[174:177], v[206:209], v[80:83]
	v_mfma_f32_16x16x32_bf16 v[72:75], v[182:185], v[206:209], v[72:75]
	v_mfma_f32_16x16x32_bf16 v[68:71], v[174:177], v[214:217], v[68:71]
	v_mfma_f32_16x16x32_bf16 v[64:67], v[182:185], v[214:217], v[64:67]
	v_mfma_f32_16x16x32_bf16 v[112:115], v[178:181], v[194:197], v[112:115]
	v_mfma_f32_16x16x32_bf16 v[104:107], v[186:189], v[194:197], v[104:107]
	v_mfma_f32_16x16x32_bf16 v[96:99], v[178:181], v[202:205], v[96:99]
	v_mfma_f32_16x16x32_bf16 v[88:91], v[186:189], v[202:205], v[88:91]
	v_mfma_f32_16x16x32_bf16 v[80:83], v[178:181], v[210:213], v[80:83]
	v_mfma_f32_16x16x32_bf16 v[72:75], v[186:189], v[210:213], v[72:75]
	v_mfma_f32_16x16x32_bf16 v[68:71], v[178:181], v[218:221], v[68:71]
	v_mfma_f32_16x16x32_bf16 v[64:67], v[186:189], v[218:221], v[64:67]
	s_setprio 0
	s_barrier
	s_add_i32 s73, s63, s29
	v_lshl_add_u64 v[222:223], s[54:55], 0, v[130:131]
	s_mov_b32 m0, s73
	ds_read_b128 v[190:193], v157 offset:16384
	ds_read_b128 v[194:197], v157 offset:17408
	ds_read_b128 v[198:201], v157 offset:18432
	ds_read_b128 v[202:205], v157 offset:19456
	ds_read_b128 v[206:209], v157 offset:20480
	ds_read_b128 v[210:213], v157 offset:21504
	ds_read_b128 v[214:217], v157 offset:22528
	ds_read_b128 v[218:221], v157 offset:23552
	global_load_lds_dwordx4 v[222:223], off
	s_add_i32 m0, s73, 0x2000
	s_add_u32 s74, s54, 0x80000
	v_lshl_add_u64 v[222:223], s[54:55], 0, v[134:135]
	s_addc_u32 s75, s55, 0
	s_add_i32 s73, s64, s29
	global_load_lds_dwordx4 v[222:223], off
	v_lshl_add_u64 v[222:223], s[74:75], 0, v[130:131]
	s_mov_b32 m0, s73
	s_nop 0
	global_load_lds_dwordx4 v[222:223], off
	v_lshl_add_u64 v[222:223], s[74:75], 0, v[134:135]
	s_add_i32 m0, s73, 0x2000
	s_nop 0
	global_load_lds_dwordx4 v[222:223], off
	v_lshl_add_u64 v[222:223], s[56:57], 0, v[128:129]
	s_mov_b32 m0, s30
	s_nop 0
	global_load_lds_dwordx4 v[222:223], off
	v_lshl_add_u64 v[222:223], s[56:57], 0, v[132:133]
	s_mov_b32 m0, s31
	s_nop 0
	global_load_lds_dwordx4 v[222:223], off
	s_waitcnt vmcnt(8)
	s_waitcnt lgkmcnt(0)
	s_barrier
; #define PG8_LDA(dst, b, h) do { _Pragma("unroll") for (int m = 0; m < 4; ++m) _Pragma("unroll") for (int k = 0; k < 2; ++k) dst[m][k] = *(const LAS bf16x8*)(lds + PG8_SA(b, h) + aoff + m * 2048 + k * 1024); } while (0)
; #define PG8_LDB(dst, b, h) do { _Pragma("unroll") for (int n = 0; n < 2; ++n) _Pragma("unroll") for (int k = 0; k < 2; ++k) dst[n][k] = *(const LAS bf16x8*)(lds + PG8_SB(b, h) + boff + n * 2048 + k * 1024); } while (0)
; #define PG8_MMA(ai, bj, At, Bt) do { __builtin_amdgcn_s_setprio(1); _Pragma("unroll") for (int m = 0; m < 4; ++m) _Pragma("unroll") for (int n = 0; n < 2; ++n) _Pragma("unroll") for (int k = 0; k < 2; ++k) \
;         acc[ai][bj][m][n] = __builtin_amdgcn_mfma_f32_16x16x32_bf16(Bt[n][k], At[m][k], acc[ai][bj][m][n], 0, 0, 0); __builtin_amdgcn_s_setprio(0); } while (0)
; #define PG8_WAIT_V(n) asm volatile("s_waitcnt vmcnt(" #n ")" ::: "memory")
; #define PG8_WAIT_L(n) asm volatile("s_waitcnt lgkmcnt(" #n ")" ::: "memory")
; #define PG8_BAR __builtin_amdgcn_s_barrier()
; #define PG8_SCHED __builtin_amdgcn_sched_barrier(0)
; __device__ __forceinline__ void gemm_phase(LAS unsigned char* lds, const GemmP& g) {
;     ...
;             PG8_WAIT_V(8); PG8_WAIT_L(0); PG8_BAR; PG8_MMA(1, 0, At, B0); PG8_MMA(1, 1, At, B1); PG8_BAR; PG8_SCHED;
;             PG8_LDB(B0, 1, 0); PG8_LDB(B1, 1, 1); PG8_SCHED; PG8_LDA(At, 1, 0); PG8_STAGE(PG8_SA(0, 1), a2 + hstepA, voffA);
;             PG8_WAIT_V(8); PG8_WAIT_L(0); PG8_BAR; PG8_MMA(0, 0, At, B0); PG8_MMA(0, 1, At, B1); PG8_BAR; PG8_SCHED;
	s_setprio 1
	s_waitcnt lgkmcnt(0)
	v_mfma_f32_16x16x32_bf16 v[60:63], v[158:161], v[190:193], v[60:63]
	v_mfma_f32_16x16x32_bf16 v[56:59], v[166:169], v[190:193], v[56:59]
	v_mfma_f32_16x16x32_bf16 v[52:55], v[158:161], v[198:201], v[52:55]
	v_mfma_f32_16x16x32_bf16 v[44:47], v[166:169], v[198:201], v[44:47]
	v_mfma_f32_16x16x32_bf16 v[36:39], v[158:161], v[206:209], v[36:39]
	v_mfma_f32_16x16x32_bf16 v[28:31], v[166:169], v[206:209], v[28:31]
	v_mfma_f32_16x16x32_bf16 v[20:23], v[158:161], v[214:217], v[20:23]
	v_mfma_f32_16x16x32_bf16 v[12:15], v[166:169], v[214:217], v[12:15]
	v_mfma_f32_16x16x32_bf16 v[60:63], v[162:165], v[194:197], v[60:63]
	v_mfma_f32_16x16x32_bf16 v[56:59], v[170:173], v[194:197], v[56:59]
	v_mfma_f32_16x16x32_bf16 v[52:55], v[162:165], v[202:205], v[52:55]
	v_mfma_f32_16x16x32_bf16 v[44:47], v[170:173], v[202:205], v[44:47]
	v_mfma_f32_16x16x32_bf16 v[36:39], v[162:165], v[210:213], v[36:39]
	v_mfma_f32_16x16x32_bf16 v[28:31], v[170:173], v[210:213], v[28:31]
	v_mfma_f32_16x16x32_bf16 v[20:23], v[162:165], v[218:221], v[20:23]
	v_mfma_f32_16x16x32_bf16 v[12:15], v[170:173], v[218:221], v[12:15]
	v_mfma_f32_16x16x32_bf16 v[48:51], v[174:177], v[190:193], v[48:51]
	v_mfma_f32_16x16x32_bf16 v[40:43], v[182:185], v[190:193], v[40:43]
	v_mfma_f32_16x16x32_bf16 v[32:35], v[174:177], v[198:201], v[32:35]
	v_mfma_f32_16x16x32_bf16 v[24:27], v[182:185], v[198:201], v[24:27]
	v_mfma_f32_16x16x32_bf16 v[16:19], v[174:177], v[206:209], v[16:19]
	v_mfma_f32_16x16x32_bf16 v[8:11], v[182:185], v[206:209], v[8:11]
	v_mfma_f32_16x16x32_bf16 v[4:7], v[174:177], v[214:217], v[4:7]
	v_mfma_f32_16x16x32_bf16 v[0:3], v[182:185], v[214:217], v[0:3]
	v_mfma_f32_16x16x32_bf16 v[48:51], v[178:181], v[194:197], v[48:51]
	v_mfma_f32_16x16x32_bf16 v[40:43], v[186:189], v[194:197], v[40:43]
	v_mfma_f32_16x16x32_bf16 v[32:35], v[178:181], v[202:205], v[32:35]
	v_mfma_f32_16x16x32_bf16 v[24:27], v[186:189], v[202:205], v[24:27]
	v_mfma_f32_16x16x32_bf16 v[16:19], v[178:181], v[210:213], v[16:19]
	v_mfma_f32_16x16x32_bf16 v[8:11], v[186:189], v[210:213], v[8:11]
	v_mfma_f32_16x16x32_bf16 v[4:7], v[178:181], v[218:221], v[4:7]
	v_mfma_f32_16x16x32_bf16 v[0:3], v[186:189], v[218:221], v[0:3]
	s_setprio 0
	s_barrier
	s_add_i32 s73, 0, 0x18000
	s_add_i32 s74, 0, 0x1c000
	v_add_u32_e32 v170, s73, v154
	v_add_u32_e32 v186, s74, v154
	ds_read_b128 v[158:161], v170
	ds_read_b128 v[162:165], v170 offset:1024
	ds_read_b128 v[166:169], v170 offset:2048
	ds_read_b128 v[170:173], v170 offset:3072
	ds_read_b128 v[174:177], v186
	ds_read_b128 v[178:181], v186 offset:1024
	ds_read_b128 v[182:185], v186 offset:2048
	ds_read_b128 v[186:189], v186 offset:3072
	s_add_u32 s56, s56, 0x80000
	s_addc_u32 s57, s57, 0
	s_mov_b32 m0, s33
	v_lshl_add_u64 v[222:223], s[56:57], 0, v[128:129]
	ds_read_b128 v[190:193], v157 offset:32768
	ds_read_b128 v[194:197], v157 offset:33792
	ds_read_b128 v[198:201], v157 offset:34816
	ds_read_b128 v[202:205], v157 offset:35840
	ds_read_b128 v[206:209], v157 offset:36864
	ds_read_b128 v[210:213], v157 offset:37888
	ds_read_b128 v[214:217], v157 offset:38912
	ds_read_b128 v[218:221], v157 offset:39936
	global_load_lds_dwordx4 v[222:223], off
	v_lshl_add_u64 v[222:223], s[56:57], 0, v[132:133]
	s_mov_b32 m0, s58
	s_nop 0
	global_load_lds_dwordx4 v[222:223], off
	s_waitcnt vmcnt(8)
	s_waitcnt lgkmcnt(0)
	s_barrier
	s_setprio 1
	s_waitcnt lgkmcnt(0)
	v_mfma_f32_16x16x32_bf16 v[124:127], v[158:161], v[190:193], v[124:127]
	v_mfma_f32_16x16x32_bf16 v[120:123], v[166:169], v[190:193], v[120:123]
	v_mfma_f32_16x16x32_bf16 v[116:119], v[158:161], v[198:201], v[116:119]
	v_mfma_f32_16x16x32_bf16 v[108:111], v[166:169], v[198:201], v[108:111]
	v_mfma_f32_16x16x32_bf16 v[100:103], v[158:161], v[206:209], v[100:103]
	v_mfma_f32_16x16x32_bf16 v[92:95], v[166:169], v[206:209], v[92:95]
	v_mfma_f32_16x16x32_bf16 v[84:87], v[158:161], v[214:217], v[84:87]
	v_mfma_f32_16x16x32_bf16 v[76:79], v[166:169], v[214:217], v[76:79]
	v_mfma_f32_16x16x32_bf16 v[124:127], v[162:165], v[194:197], v[124:127]
	v_mfma_f32_16x16x32_bf16 v[120:123], v[170:173], v[194:197], v[120:123]
	v_mfma_f32_16x16x32_bf16 v[116:119], v[162:165], v[202:205], v[116:119]
	v_mfma_f32_16x16x32_bf16 v[108:111], v[170:173], v[202:205], v[108:111]
	v_mfma_f32_16x16x32_bf16 v[100:103], v[162:165], v[210:213], v[100:103]
	v_mfma_f32_16x16x32_bf16 v[92:95], v[170:173], v[210:213], v[92:95]
	v_mfma_f32_16x16x32_bf16 v[84:87], v[162:165], v[218:221], v[84:87]
	v_mfma_f32_16x16x32_bf16 v[76:79], v[170:173], v[218:221], v[76:79]
	v_mfma_f32_16x16x32_bf16 v[112:115], v[174:177], v[190:193], v[112:115]
	v_mfma_f32_16x16x32_bf16 v[104:107], v[182:185], v[190:193], v[104:107]
	v_mfma_f32_16x16x32_bf16 v[96:99], v[174:177], v[198:201], v[96:99]
	v_mfma_f32_16x16x32_bf16 v[88:91], v[182:185], v[198:201], v[88:91]
	v_mfma_f32_16x16x32_bf16 v[80:83], v[174:177], v[206:209], v[80:83]
	v_mfma_f32_16x16x32_bf16 v[72:75], v[182:185], v[206:209], v[72:75]
	v_mfma_f32_16x16x32_bf16 v[68:71], v[174:177], v[214:217], v[68:71]
	v_mfma_f32_16x16x32_bf16 v[64:67], v[182:185], v[214:217], v[64:67]
	v_mfma_f32_16x16x32_bf16 v[112:115], v[178:181], v[194:197], v[112:115]
	v_mfma_f32_16x16x32_bf16 v[104:107], v[186:189], v[194:197], v[104:107]
	v_mfma_f32_16x16x32_bf16 v[96:99], v[178:181], v[202:205], v[96:99]
	v_mfma_f32_16x16x32_bf16 v[88:91], v[186:189], v[202:205], v[88:91]
	v_mfma_f32_16x16x32_bf16 v[80:83], v[178:181], v[210:213], v[80:83]
	v_mfma_f32_16x16x32_bf16 v[72:75], v[186:189], v[210:213], v[72:75]
	v_mfma_f32_16x16x32_bf16 v[68:71], v[178:181], v[218:221], v[68:71]
	v_mfma_f32_16x16x32_bf16 v[64:67], v[186:189], v[218:221], v[64:67]
	s_setprio 0
	s_barrier
; #define PG8_LDA(dst, b, h) do { _Pragma("unroll") for (int m = 0; m < 4; ++m) _Pragma("unroll") for (int k = 0; k < 2; ++k) dst[m][k] = *(const LAS bf16x8*)(lds + PG8_SA(b, h) + aoff + m * 2048 + k * 1024); } while (0)
; #define PG8_MMA(ai, bj, At, Bt) do { __builtin_amdgcn_s_setprio(1); _Pragma("unroll") for (int m = 0; m < 4; ++m) _Pragma("unroll") for (int n = 0; n < 2; ++n) _Pragma("unroll") for (int k = 0; k < 2; ++k) \
;         acc[ai][bj][m][n] = __builtin_amdgcn_mfma_f32_16x16x32_bf16(Bt[n][k], At[m][k], acc[ai][bj][m][n], 0, 0, 0); __builtin_amdgcn_s_setprio(0); } while (0)
; #define PG8_WAIT_V(n) asm volatile("s_waitcnt vmcnt(" #n ")" ::: "memory")
; #define PG8_WAIT_L(n) asm volatile("s_waitcnt lgkmcnt(" #n ")" ::: "memory")
; #define PG8_BAR __builtin_amdgcn_s_barrier()
; #define PG8_SCHED __builtin_amdgcn_sched_barrier(0)
; __device__ __forceinline__ void gemm_phase(LAS unsigned char* lds, const GemmP& g) {
;     ...
;             PG8_LDA(At, 1, 1); PG8_STAGE(PG8_SB(1, 0), b3, voffB); PG8_STAGE(PG8_SB(1, 1), b3 + hstepB, voffB); PG8_STAGE(PG8_SA(1, 0), a3, voffA);
;             PG8_WAIT_V(8); PG8_WAIT_L(0); PG8_BAR; PG8_MMA(1, 0, At, B0); PG8_MMA(1, 1, At, B1); PG8_BAR; PG8_SCHED;
;         }
;         if (wr == 0) PG8_BAR;
	s_add_u32 s56, s54, 0x80
	s_addc_u32 s57, s55, 0
	s_add_i32 s73, s73, s29
	v_lshl_add_u64 v[222:223], s[56:57], 0, v[130:131]
	s_mov_b32 m0, s73
	ds_read_b128 v[190:193], v157 offset:49152
	ds_read_b128 v[194:197], v157 offset:50176
	ds_read_b128 v[198:201], v157 offset:51200
	ds_read_b128 v[202:205], v157 offset:52224
	ds_read_b128 v[206:209], v157 offset:53248
	ds_read_b128 v[210:213], v157 offset:54272
	ds_read_b128 v[214:217], v157 offset:55296
	ds_read_b128 v[218:221], v157 offset:56320
	global_load_lds_dwordx4 v[222:223], off
	s_add_i32 m0, s73, 0x2000
	s_add_u32 s54, s54, 0x80080
	v_lshl_add_u64 v[222:223], s[56:57], 0, v[134:135]
	s_addc_u32 s55, s55, 0
	s_add_i32 s56, s74, s29
	global_load_lds_dwordx4 v[222:223], off
	v_lshl_add_u64 v[222:223], s[54:55], 0, v[130:131]
	s_mov_b32 m0, s56
	s_nop 0
	global_load_lds_dwordx4 v[222:223], off
	v_lshl_add_u64 v[222:223], s[54:55], 0, v[134:135]
	s_add_i32 m0, s56, 0x2000
	s_nop 0
	global_load_lds_dwordx4 v[222:223], off
	v_lshl_add_u64 v[222:223], s[52:53], 0, v[128:129]
	s_mov_b32 m0, s60
	s_nop 0
	global_load_lds_dwordx4 v[222:223], off
	v_lshl_add_u64 v[222:223], s[52:53], 0, v[132:133]
	s_mov_b32 m0, s61
	s_nop 0
	global_load_lds_dwordx4 v[222:223], off
	s_waitcnt vmcnt(8)
	s_waitcnt lgkmcnt(0)
	s_barrier
	s_setprio 1
	s_waitcnt lgkmcnt(0)
	v_mfma_f32_16x16x32_bf16 v[60:63], v[158:161], v[190:193], v[60:63]
	v_mfma_f32_16x16x32_bf16 v[56:59], v[166:169], v[190:193], v[56:59]
	v_mfma_f32_16x16x32_bf16 v[52:55], v[158:161], v[198:201], v[52:55]
	v_mfma_f32_16x16x32_bf16 v[44:47], v[166:169], v[198:201], v[44:47]
	v_mfma_f32_16x16x32_bf16 v[36:39], v[158:161], v[206:209], v[36:39]
	v_mfma_f32_16x16x32_bf16 v[28:31], v[166:169], v[206:209], v[28:31]
	v_mfma_f32_16x16x32_bf16 v[20:23], v[158:161], v[214:217], v[20:23]
	v_mfma_f32_16x16x32_bf16 v[12:15], v[166:169], v[214:217], v[12:15]
	v_mfma_f32_16x16x32_bf16 v[60:63], v[162:165], v[194:197], v[60:63]
	v_mfma_f32_16x16x32_bf16 v[56:59], v[170:173], v[194:197], v[56:59]
	v_mfma_f32_16x16x32_bf16 v[52:55], v[162:165], v[202:205], v[52:55]
	v_mfma_f32_16x16x32_bf16 v[44:47], v[170:173], v[202:205], v[44:47]
	v_mfma_f32_16x16x32_bf16 v[36:39], v[162:165], v[210:213], v[36:39]
	v_mfma_f32_16x16x32_bf16 v[28:31], v[170:173], v[210:213], v[28:31]
	v_mfma_f32_16x16x32_bf16 v[20:23], v[162:165], v[218:221], v[20:23]
	v_mfma_f32_16x16x32_bf16 v[12:15], v[170:173], v[218:221], v[12:15]
	v_mfma_f32_16x16x32_bf16 v[48:51], v[174:177], v[190:193], v[48:51]
	v_mfma_f32_16x16x32_bf16 v[40:43], v[182:185], v[190:193], v[40:43]
	v_mfma_f32_16x16x32_bf16 v[32:35], v[174:177], v[198:201], v[32:35]
	v_mfma_f32_16x16x32_bf16 v[24:27], v[182:185], v[198:201], v[24:27]
	v_mfma_f32_16x16x32_bf16 v[16:19], v[174:177], v[206:209], v[16:19]
	v_mfma_f32_16x16x32_bf16 v[8:11], v[182:185], v[206:209], v[8:11]
	v_mfma_f32_16x16x32_bf16 v[4:7], v[174:177], v[214:217], v[4:7]
	v_mfma_f32_16x16x32_bf16 v[0:3], v[182:185], v[214:217], v[0:3]
	v_mfma_f32_16x16x32_bf16 v[48:51], v[178:181], v[194:197], v[48:51]
	v_mfma_f32_16x16x32_bf16 v[40:43], v[186:189], v[194:197], v[40:43]
	v_mfma_f32_16x16x32_bf16 v[32:35], v[178:181], v[202:205], v[32:35]
	v_mfma_f32_16x16x32_bf16 v[24:27], v[186:189], v[202:205], v[24:27]
	v_mfma_f32_16x16x32_bf16 v[16:19], v[178:181], v[210:213], v[16:19]
	v_mfma_f32_16x16x32_bf16 v[8:11], v[186:189], v[210:213], v[8:11]
	v_mfma_f32_16x16x32_bf16 v[4:7], v[178:181], v[218:221], v[4:7]
	v_mfma_f32_16x16x32_bf16 v[0:3], v[186:189], v[218:221], v[0:3]
	s_setprio 0
	s_barrier
	s_add_i32 s72, s72, 2
	s_add_u32 s17, s17, 0x100
	s_addc_u32 s19, s19, 0
	s_add_u32 s70, s70, 0x100
	s_addc_u32 s71, s71, 0
	s_add_u32 s44, s44, 0x100
	s_addc_u32 s45, s45, 0
	s_cmp_gt_u32 s72, 29
	s_cbranch_scc0 .LBB0_1303
	s_and_b64 vcc, exec, s[6:7]
	s_cbranch_vccz .LBB0_1306
	s_barrier

; #define PG8_LDA(dst, b, h) do { _Pragma("unroll") for (int m = 0; m < 4; ++m) _Pragma("unroll") for (int k = 0; k < 2; ++k) dst[m][k] = *(const LAS bf16x8*)(lds + PG8_SA(b, h) + aoff + m * 2048 + k * 1024); } while (0)
; #define PG8_LDB(dst, b, h) do { _Pragma("unroll") for (int n = 0; n < 2; ++n) _Pragma("unroll") for (int k = 0; k < 2; ++k) dst[n][k] = *(const LAS bf16x8*)(lds + PG8_SB(b, h) + boff + n * 2048 + k * 1024); } while (0)
; #define PG8_MMA(ai, bj, At, Bt) do { __builtin_amdgcn_s_setprio(1); _Pragma("unroll") for (int m = 0; m < 4; ++m) _Pragma("unroll") for (int n = 0; n < 2; ++n) _Pragma("unroll") for (int k = 0; k < 2; ++k) \
;         acc[ai][bj][m][n] = __builtin_amdgcn_mfma_f32_16x16x32_bf16(Bt[n][k], At[m][k], acc[ai][bj][m][n], 0, 0, 0); __builtin_amdgcn_s_setprio(0); } while (0)
; #define PG8_WAIT_V(n) asm volatile("s_waitcnt vmcnt(" #n ")" ::: "memory")
; #define PG8_WAIT_L(n) asm volatile("s_waitcnt lgkmcnt(" #n ")" ::: "memory")
; #define PG8_BAR __builtin_amdgcn_s_barrier()
; #define PG8_SCHED __builtin_amdgcn_sched_barrier(0)
; __device__ __forceinline__ void gemm_phase(LAS unsigned char* lds, const GemmP& g) {
;     ...
;         for (int t = 0; t < nt; t += 2) {
;             const bool last = (t == nt - 2);
;             const char* a1 = cA + (size_t)(t + 1) * kstep;
;             const char* a2 = last ? nA : cA + (size_t)(t + 2) * kstep; const char* b2 = last ? nB : cB + (size_t)(t + 2) * kstep;
;             const char* a3 = a2 + kstep; const char* b3 = b2 + kstep;
;             PG8_LDB(B0, 0, 0); PG8_LDB(B1, 0, 1); PG8_SCHED; PG8_LDA(At, 0, 0); PG8_STAGE(PG8_SA(1, 1), a1 + hstepA, voffA);
;             PG8_WAIT_V(8); PG8_WAIT_L(0); PG8_BAR; PG8_MMA(0, 0, At, B0); PG8_MMA(0, 1, At, B1); PG8_BAR; PG8_SCHED;
;             PG8_LDA(At, 0, 1); PG8_STAGE(PG8_SB(0, 0), b2, voffB); PG8_STAGE(PG8_SB(0, 1), b2 + hstepB, voffB); PG8_STAGE(PG8_SA(0, 0), a2, voffA);
;             PG8_WAIT_V(8); PG8_WAIT_L(0); PG8_BAR; PG8_MMA(1, 0, At, B0); PG8_MMA(1, 1, At, B1); PG8_BAR; PG8_SCHED;
.LBB0_1382:
	ds_read_b128 v[116:119], v226
	ds_read_b128 v[120:123], v226 offset:1024
	ds_read_b128 v[124:127], v226 offset:2048
	ds_read_b128 v[128:131], v226 offset:3072
	ds_read_b128 v[132:135], v227
	ds_read_b128 v[136:139], v227 offset:1024
	ds_read_b128 v[140:143], v227 offset:2048
	ds_read_b128 v[144:147], v227 offset:3072
	s_cmp_eq_u32 s72, 28
	s_cselect_b32 s56, s20, s30
	s_cselect_b32 s57, s15, s31
	s_cselect_b32 s54, s21, s43
	s_cselect_b32 s55, s17, s45
	s_add_u32 s52, s56, 0x80
	s_addc_u32 s53, s57, 0
	v_lshl_add_u64 v[236:237], s[0:1], 0, v[160:161]
	s_add_i32 m0, s58, 0xc000
	ds_read_b128 v[200:203], v225
	ds_read_b128 v[204:207], v225 offset:1024
	ds_read_b128 v[208:211], v225 offset:2048
	ds_read_b128 v[212:215], v225 offset:3072
	ds_read_b128 v[216:219], v225 offset:4096
	ds_read_b128 v[220:223], v225 offset:5120
	ds_read_b128 v[228:231], v225 offset:6144
	ds_read_b128 v[232:235], v225 offset:7168
	global_load_lds_dwordx4 v[236:237], off
	v_lshl_add_u64 v[236:237], s[0:1], 0, v[162:163]
	s_add_i32 m0, s58, 0xe000
	s_nop 0
	global_load_lds_dwordx4 v[236:237], off
	s_waitcnt vmcnt(8)
	s_waitcnt lgkmcnt(0)
	s_barrier
	s_setprio 1
	s_waitcnt lgkmcnt(0)
	v_mfma_f32_16x16x32_bf16 v[156:159], v[116:119], v[200:203], v[156:159]
	v_mfma_f32_16x16x32_bf16 v[152:155], v[124:127], v[200:203], v[152:155]
	v_mfma_f32_16x16x32_bf16 v[108:111], v[116:119], v[208:211], v[108:111]
	v_mfma_f32_16x16x32_bf16 v[104:107], v[124:127], v[208:211], v[104:107]
	v_mfma_f32_16x16x32_bf16 v[96:99], v[116:119], v[216:219], v[96:99]
	v_mfma_f32_16x16x32_bf16 v[88:91], v[124:127], v[216:219], v[88:91]
	v_mfma_f32_16x16x32_bf16 v[80:83], v[116:119], v[228:231], v[80:83]
	v_mfma_f32_16x16x32_bf16 v[72:75], v[124:127], v[228:231], v[72:75]
	v_mfma_f32_16x16x32_bf16 v[156:159], v[120:123], v[204:207], v[156:159]
	v_mfma_f32_16x16x32_bf16 v[152:155], v[128:131], v[204:207], v[152:155]
	v_mfma_f32_16x16x32_bf16 v[108:111], v[120:123], v[212:215], v[108:111]
	v_mfma_f32_16x16x32_bf16 v[104:107], v[128:131], v[212:215], v[104:107]
	v_mfma_f32_16x16x32_bf16 v[96:99], v[120:123], v[220:223], v[96:99]
	v_mfma_f32_16x16x32_bf16 v[88:91], v[128:131], v[220:223], v[88:91]
	v_mfma_f32_16x16x32_bf16 v[80:83], v[120:123], v[232:235], v[80:83]
	v_mfma_f32_16x16x32_bf16 v[72:75], v[128:131], v[232:235], v[72:75]
	v_mfma_f32_16x16x32_bf16 v[148:151], v[132:135], v[200:203], v[148:151]
	v_mfma_f32_16x16x32_bf16 v[112:115], v[140:143], v[200:203], v[112:115]
	v_mfma_f32_16x16x32_bf16 v[100:103], v[132:135], v[208:211], v[100:103]
	v_mfma_f32_16x16x32_bf16 v[92:95], v[140:143], v[208:211], v[92:95]
	v_mfma_f32_16x16x32_bf16 v[84:87], v[132:135], v[216:219], v[84:87]
	v_mfma_f32_16x16x32_bf16 v[76:79], v[140:143], v[216:219], v[76:79]
	v_mfma_f32_16x16x32_bf16 v[68:71], v[132:135], v[228:231], v[68:71]
	v_mfma_f32_16x16x32_bf16 v[64:67], v[140:143], v[228:231], v[64:67]
	v_mfma_f32_16x16x32_bf16 v[148:151], v[136:139], v[204:207], v[148:151]
	v_mfma_f32_16x16x32_bf16 v[112:115], v[144:147], v[204:207], v[112:115]
	v_mfma_f32_16x16x32_bf16 v[100:103], v[136:139], v[212:215], v[100:103]
	v_mfma_f32_16x16x32_bf16 v[92:95], v[144:147], v[212:215], v[92:95]
	v_mfma_f32_16x16x32_bf16 v[84:87], v[136:139], v[220:223], v[84:87]
	v_mfma_f32_16x16x32_bf16 v[76:79], v[144:147], v[220:223], v[76:79]
	v_mfma_f32_16x16x32_bf16 v[68:71], v[136:139], v[232:235], v[68:71]
	v_mfma_f32_16x16x32_bf16 v[64:67], v[144:147], v[232:235], v[64:67]
	s_setprio 0
	s_barrier
	s_add_i32 s73, s70, s33
	v_lshl_add_u64 v[236:237], s[54:55], 0, v[160:161]
	s_mov_b32 m0, s73
	ds_read_b128 v[200:203], v225 offset:16384
	ds_read_b128 v[204:207], v225 offset:17408
	ds_read_b128 v[208:211], v225 offset:18432
	ds_read_b128 v[212:215], v225 offset:19456
	ds_read_b128 v[216:219], v225 offset:20480
	ds_read_b128 v[220:223], v225 offset:21504
	ds_read_b128 v[228:231], v225 offset:22528
	ds_read_b128 v[232:235], v225 offset:23552
	global_load_lds_dwordx4 v[236:237], off
	s_add_i32 m0, s73, 0x2000
	s_add_u32 s74, s54, 0x80000
	v_lshl_add_u64 v[236:237], s[54:55], 0, v[162:163]
	s_addc_u32 s75, s55, 0
	s_add_i32 s73, s71, s33
	global_load_lds_dwordx4 v[236:237], off
	v_lshl_add_u64 v[236:237], s[74:75], 0, v[160:161]
	s_mov_b32 m0, s73
	s_nop 0
	global_load_lds_dwordx4 v[236:237], off
	v_lshl_add_u64 v[236:237], s[74:75], 0, v[162:163]
	s_add_i32 m0, s73, 0x2000
	s_nop 0
	global_load_lds_dwordx4 v[236:237], off
	v_lshl_add_u64 v[236:237], s[56:57], 0, v[160:161]
	s_mov_b32 m0, s58
	s_nop 0
	global_load_lds_dwordx4 v[236:237], off
	v_lshl_add_u64 v[236:237], s[56:57], 0, v[162:163]
	s_mov_b32 m0, s59
	s_nop 0
	global_load_lds_dwordx4 v[236:237], off
	s_waitcnt vmcnt(8)
	s_waitcnt lgkmcnt(0)
	s_barrier
; #define PG8_LDA(dst, b, h) do { _Pragma("unroll") for (int m = 0; m < 4; ++m) _Pragma("unroll") for (int k = 0; k < 2; ++k) dst[m][k] = *(const LAS bf16x8*)(lds + PG8_SA(b, h) + aoff + m * 2048 + k * 1024); } while (0)
; #define PG8_LDB(dst, b, h) do { _Pragma("unroll") for (int n = 0; n < 2; ++n) _Pragma("unroll") for (int k = 0; k < 2; ++k) dst[n][k] = *(const LAS bf16x8*)(lds + PG8_SB(b, h) + boff + n * 2048 + k * 1024); } while (0)
; #define PG8_MMA(ai, bj, At, Bt) do { __builtin_amdgcn_s_setprio(1); _Pragma("unroll") for (int m = 0; m < 4; ++m) _Pragma("unroll") for (int n = 0; n < 2; ++n) _Pragma("unroll") for (int k = 0; k < 2; ++k) \
;         acc[ai][bj][m][n] = __builtin_amdgcn_mfma_f32_16x16x32_bf16(Bt[n][k], At[m][k], acc[ai][bj][m][n], 0, 0, 0); __builtin_amdgcn_s_setprio(0); } while (0)
; #define PG8_WAIT_V(n) asm volatile("s_waitcnt vmcnt(" #n ")" ::: "memory")
; #define PG8_WAIT_L(n) asm volatile("s_waitcnt lgkmcnt(" #n ")" ::: "memory")
; #define PG8_BAR __builtin_amdgcn_s_barrier()
; #define PG8_SCHED __builtin_amdgcn_sched_barrier(0)
; __device__ __forceinline__ void gemm_phase(LAS unsigned char* lds, const GemmP& g) {
;     ...
;             PG8_WAIT_V(8); PG8_WAIT_L(0); PG8_BAR; PG8_MMA(1, 0, At, B0); PG8_MMA(1, 1, At, B1); PG8_BAR; PG8_SCHED;
;             PG8_LDB(B0, 1, 0); PG8_LDB(B1, 1, 1); PG8_SCHED; PG8_LDA(At, 1, 0); PG8_STAGE(PG8_SA(0, 1), a2 + hstepA, voffA);
;             PG8_WAIT_V(8); PG8_WAIT_L(0); PG8_BAR; PG8_MMA(0, 0, At, B0); PG8_MMA(0, 1, At, B1); PG8_BAR; PG8_SCHED;
	s_setprio 1
	s_waitcnt lgkmcnt(0)
	v_mfma_f32_16x16x32_bf16 v[60:63], v[116:119], v[200:203], v[60:63]
	v_mfma_f32_16x16x32_bf16 v[56:59], v[124:127], v[200:203], v[56:59]
	v_mfma_f32_16x16x32_bf16 v[48:51], v[116:119], v[208:211], v[48:51]
	v_mfma_f32_16x16x32_bf16 v[40:43], v[124:127], v[208:211], v[40:43]
	v_mfma_f32_16x16x32_bf16 v[32:35], v[116:119], v[216:219], v[32:35]
	v_mfma_f32_16x16x32_bf16 v[24:27], v[124:127], v[216:219], v[24:27]
	v_mfma_f32_16x16x32_bf16 v[16:19], v[116:119], v[228:231], v[16:19]
	v_mfma_f32_16x16x32_bf16 v[8:11], v[124:127], v[228:231], v[8:11]
	v_mfma_f32_16x16x32_bf16 v[60:63], v[120:123], v[204:207], v[60:63]
	v_mfma_f32_16x16x32_bf16 v[56:59], v[128:131], v[204:207], v[56:59]
	v_mfma_f32_16x16x32_bf16 v[48:51], v[120:123], v[212:215], v[48:51]
	v_mfma_f32_16x16x32_bf16 v[40:43], v[128:131], v[212:215], v[40:43]
	v_mfma_f32_16x16x32_bf16 v[32:35], v[120:123], v[220:223], v[32:35]
	v_mfma_f32_16x16x32_bf16 v[24:27], v[128:131], v[220:223], v[24:27]
	v_mfma_f32_16x16x32_bf16 v[16:19], v[120:123], v[232:235], v[16:19]
	v_mfma_f32_16x16x32_bf16 v[8:11], v[128:131], v[232:235], v[8:11]
	v_mfma_f32_16x16x32_bf16 v[52:55], v[132:135], v[200:203], v[52:55]
	v_mfma_f32_16x16x32_bf16 v[44:47], v[140:143], v[200:203], v[44:47]
	v_mfma_f32_16x16x32_bf16 v[36:39], v[132:135], v[208:211], v[36:39]
	v_mfma_f32_16x16x32_bf16 v[28:31], v[140:143], v[208:211], v[28:31]
	v_mfma_f32_16x16x32_bf16 v[20:23], v[132:135], v[216:219], v[20:23]
	v_mfma_f32_16x16x32_bf16 v[12:15], v[140:143], v[216:219], v[12:15]
	v_mfma_f32_16x16x32_bf16 v[4:7], v[132:135], v[228:231], v[4:7]
	v_mfma_f32_16x16x32_bf16 v[0:3], v[140:143], v[228:231], v[0:3]
	v_mfma_f32_16x16x32_bf16 v[52:55], v[136:139], v[204:207], v[52:55]
	v_mfma_f32_16x16x32_bf16 v[44:47], v[144:147], v[204:207], v[44:47]
	v_mfma_f32_16x16x32_bf16 v[36:39], v[136:139], v[212:215], v[36:39]
	v_mfma_f32_16x16x32_bf16 v[28:31], v[144:147], v[212:215], v[28:31]
	v_mfma_f32_16x16x32_bf16 v[20:23], v[136:139], v[220:223], v[20:23]
	v_mfma_f32_16x16x32_bf16 v[12:15], v[144:147], v[220:223], v[12:15]
	v_mfma_f32_16x16x32_bf16 v[4:7], v[136:139], v[232:235], v[4:7]
	v_mfma_f32_16x16x32_bf16 v[0:3], v[144:147], v[232:235], v[0:3]
	s_setprio 0
	s_barrier
	s_add_i32 s73, 0, 0x18000
	s_add_i32 s74, 0, 0x1c000
	v_add_u32_e32 v128, s73, v165
	v_add_u32_e32 v144, s74, v165
	ds_read_b128 v[116:119], v128
	ds_read_b128 v[120:123], v128 offset:1024
	ds_read_b128 v[124:127], v128 offset:2048
	ds_read_b128 v[128:131], v128 offset:3072
	ds_read_b128 v[132:135], v144
	ds_read_b128 v[136:139], v144 offset:1024
	ds_read_b128 v[140:143], v144 offset:2048
	ds_read_b128 v[144:147], v144 offset:3072
	s_add_u32 s56, s56, 0x80000
	s_addc_u32 s57, s57, 0
	s_mov_b32 m0, s60
	v_lshl_add_u64 v[236:237], s[56:57], 0, v[160:161]
	ds_read_b128 v[200:203], v225 offset:32768
	ds_read_b128 v[204:207], v225 offset:33792
	ds_read_b128 v[208:211], v225 offset:34816
	ds_read_b128 v[212:215], v225 offset:35840
	ds_read_b128 v[216:219], v225 offset:36864
	ds_read_b128 v[220:223], v225 offset:37888
	ds_read_b128 v[228:231], v225 offset:38912
	ds_read_b128 v[232:235], v225 offset:39936
	global_load_lds_dwordx4 v[236:237], off
	v_lshl_add_u64 v[236:237], s[56:57], 0, v[162:163]
	s_mov_b32 m0, s61
	s_nop 0
	global_load_lds_dwordx4 v[236:237], off
	s_waitcnt vmcnt(8)
	s_waitcnt lgkmcnt(0)
	s_barrier
	s_setprio 1
	s_waitcnt lgkmcnt(0)
	v_mfma_f32_16x16x32_bf16 v[156:159], v[116:119], v[200:203], v[156:159]
	v_mfma_f32_16x16x32_bf16 v[152:155], v[124:127], v[200:203], v[152:155]
	v_mfma_f32_16x16x32_bf16 v[108:111], v[116:119], v[208:211], v[108:111]
	v_mfma_f32_16x16x32_bf16 v[104:107], v[124:127], v[208:211], v[104:107]
	v_mfma_f32_16x16x32_bf16 v[96:99], v[116:119], v[216:219], v[96:99]
	v_mfma_f32_16x16x32_bf16 v[88:91], v[124:127], v[216:219], v[88:91]
	v_mfma_f32_16x16x32_bf16 v[80:83], v[116:119], v[228:231], v[80:83]
	v_mfma_f32_16x16x32_bf16 v[72:75], v[124:127], v[228:231], v[72:75]
	v_mfma_f32_16x16x32_bf16 v[156:159], v[120:123], v[204:207], v[156:159]
	v_mfma_f32_16x16x32_bf16 v[152:155], v[128:131], v[204:207], v[152:155]
	v_mfma_f32_16x16x32_bf16 v[108:111], v[120:123], v[212:215], v[108:111]
	v_mfma_f32_16x16x32_bf16 v[104:107], v[128:131], v[212:215], v[104:107]
	v_mfma_f32_16x16x32_bf16 v[96:99], v[120:123], v[220:223], v[96:99]
	v_mfma_f32_16x16x32_bf16 v[88:91], v[128:131], v[220:223], v[88:91]
	v_mfma_f32_16x16x32_bf16 v[80:83], v[120:123], v[232:235], v[80:83]
	v_mfma_f32_16x16x32_bf16 v[72:75], v[128:131], v[232:235], v[72:75]
	v_mfma_f32_16x16x32_bf16 v[148:151], v[132:135], v[200:203], v[148:151]
	v_mfma_f32_16x16x32_bf16 v[112:115], v[140:143], v[200:203], v[112:115]
	v_mfma_f32_16x16x32_bf16 v[100:103], v[132:135], v[208:211], v[100:103]
	v_mfma_f32_16x16x32_bf16 v[92:95], v[140:143], v[208:211], v[92:95]
	v_mfma_f32_16x16x32_bf16 v[84:87], v[132:135], v[216:219], v[84:87]
	v_mfma_f32_16x16x32_bf16 v[76:79], v[140:143], v[216:219], v[76:79]
	v_mfma_f32_16x16x32_bf16 v[68:71], v[132:135], v[228:231], v[68:71]
	v_mfma_f32_16x16x32_bf16 v[64:67], v[140:143], v[228:231], v[64:67]
	v_mfma_f32_16x16x32_bf16 v[148:151], v[136:139], v[204:207], v[148:151]
	v_mfma_f32_16x16x32_bf16 v[112:115], v[144:147], v[204:207], v[112:115]
	v_mfma_f32_16x16x32_bf16 v[100:103], v[136:139], v[212:215], v[100:103]
	v_mfma_f32_16x16x32_bf16 v[92:95], v[144:147], v[212:215], v[92:95]
	v_mfma_f32_16x16x32_bf16 v[84:87], v[136:139], v[220:223], v[84:87]
	v_mfma_f32_16x16x32_bf16 v[76:79], v[144:147], v[220:223], v[76:79]
	v_mfma_f32_16x16x32_bf16 v[68:71], v[136:139], v[232:235], v[68:71]
	v_mfma_f32_16x16x32_bf16 v[64:67], v[144:147], v[232:235], v[64:67]
	s_setprio 0
	s_barrier
; #define PG8_LDA(dst, b, h) do { _Pragma("unroll") for (int m = 0; m < 4; ++m) _Pragma("unroll") for (int k = 0; k < 2; ++k) dst[m][k] = *(const LAS bf16x8*)(lds + PG8_SA(b, h) + aoff + m * 2048 + k * 1024); } while (0)
; #define PG8_MMA(ai, bj, At, Bt) do { __builtin_amdgcn_s_setprio(1); _Pragma("unroll") for (int m = 0; m < 4; ++m) _Pragma("unroll") for (int n = 0; n < 2; ++n) _Pragma("unroll") for (int k = 0; k < 2; ++k) \
;         acc[ai][bj][m][n] = __builtin_amdgcn_mfma_f32_16x16x32_bf16(Bt[n][k], At[m][k], acc[ai][bj][m][n], 0, 0, 0); __builtin_amdgcn_s_setprio(0); } while (0)
; #define PG8_WAIT_V(n) asm volatile("s_waitcnt vmcnt(" #n ")" ::: "memory")
; #define PG8_WAIT_L(n) asm volatile("s_waitcnt lgkmcnt(" #n ")" ::: "memory")
; #define PG8_BAR __builtin_amdgcn_s_barrier()
; #define PG8_SCHED __builtin_amdgcn_sched_barrier(0)
; __device__ __forceinline__ void gemm_phase(LAS unsigned char* lds, const GemmP& g) {
;     ...
;             PG8_LDA(At, 1, 1); PG8_STAGE(PG8_SB(1, 0), b3, voffB); PG8_STAGE(PG8_SB(1, 1), b3 + hstepB, voffB); PG8_STAGE(PG8_SA(1, 0), a3, voffA);
;             PG8_WAIT_V(8); PG8_WAIT_L(0); PG8_BAR; PG8_MMA(1, 0, At, B0); PG8_MMA(1, 1, At, B1); PG8_BAR; PG8_SCHED;
;         }
;         if (wr == 0) PG8_BAR;
	s_add_u32 s56, s54, 0x80
	s_addc_u32 s57, s55, 0
	s_add_i32 s73, s73, s33
	v_lshl_add_u64 v[236:237], s[56:57], 0, v[160:161]
	s_mov_b32 m0, s73
	ds_read_b128 v[200:203], v225 offset:49152
	ds_read_b128 v[204:207], v225 offset:50176
	ds_read_b128 v[208:211], v225 offset:51200
	ds_read_b128 v[212:215], v225 offset:52224
	ds_read_b128 v[216:219], v225 offset:53248
	ds_read_b128 v[220:223], v225 offset:54272
	ds_read_b128 v[228:231], v225 offset:55296
	ds_read_b128 v[232:235], v225 offset:56320
	global_load_lds_dwordx4 v[236:237], off
	s_add_i32 m0, s73, 0x2000
	s_add_u32 s54, s54, 0x80080
	v_lshl_add_u64 v[236:237], s[56:57], 0, v[162:163]
	s_addc_u32 s55, s55, 0
	s_add_i32 s56, s74, s33
	global_load_lds_dwordx4 v[236:237], off
	v_lshl_add_u64 v[236:237], s[54:55], 0, v[160:161]
	s_mov_b32 m0, s56
	s_nop 0
	global_load_lds_dwordx4 v[236:237], off
	v_lshl_add_u64 v[236:237], s[54:55], 0, v[162:163]
	s_add_i32 m0, s56, 0x2000
	s_nop 0
	global_load_lds_dwordx4 v[236:237], off
	v_lshl_add_u64 v[236:237], s[52:53], 0, v[160:161]
	s_mov_b32 m0, s65
	s_nop 0
	global_load_lds_dwordx4 v[236:237], off
	v_lshl_add_u64 v[236:237], s[52:53], 0, v[162:163]
	s_mov_b32 m0, s68
	s_nop 0
	global_load_lds_dwordx4 v[236:237], off
	s_waitcnt vmcnt(8)
	s_waitcnt lgkmcnt(0)
	s_barrier
	s_setprio 1
	s_waitcnt lgkmcnt(0)
	v_mfma_f32_16x16x32_bf16 v[60:63], v[116:119], v[200:203], v[60:63]
	v_mfma_f32_16x16x32_bf16 v[56:59], v[124:127], v[200:203], v[56:59]
	v_mfma_f32_16x16x32_bf16 v[48:51], v[116:119], v[208:211], v[48:51]
	v_mfma_f32_16x16x32_bf16 v[40:43], v[124:127], v[208:211], v[40:43]
	v_mfma_f32_16x16x32_bf16 v[32:35], v[116:119], v[216:219], v[32:35]
	v_mfma_f32_16x16x32_bf16 v[24:27], v[124:127], v[216:219], v[24:27]
	v_mfma_f32_16x16x32_bf16 v[16:19], v[116:119], v[228:231], v[16:19]
	v_mfma_f32_16x16x32_bf16 v[8:11], v[124:127], v[228:231], v[8:11]
	v_mfma_f32_16x16x32_bf16 v[60:63], v[120:123], v[204:207], v[60:63]
	v_mfma_f32_16x16x32_bf16 v[56:59], v[128:131], v[204:207], v[56:59]
	v_mfma_f32_16x16x32_bf16 v[48:51], v[120:123], v[212:215], v[48:51]
	v_mfma_f32_16x16x32_bf16 v[40:43], v[128:131], v[212:215], v[40:43]
	v_mfma_f32_16x16x32_bf16 v[32:35], v[120:123], v[220:223], v[32:35]
	v_mfma_f32_16x16x32_bf16 v[24:27], v[128:131], v[220:223], v[24:27]
	v_mfma_f32_16x16x32_bf16 v[16:19], v[120:123], v[232:235], v[16:19]
	v_mfma_f32_16x16x32_bf16 v[8:11], v[128:131], v[232:235], v[8:11]
	v_mfma_f32_16x16x32_bf16 v[52:55], v[132:135], v[200:203], v[52:55]
	v_mfma_f32_16x16x32_bf16 v[44:47], v[140:143], v[200:203], v[44:47]
	v_mfma_f32_16x16x32_bf16 v[36:39], v[132:135], v[208:211], v[36:39]
	v_mfma_f32_16x16x32_bf16 v[28:31], v[140:143], v[208:211], v[28:31]
	v_mfma_f32_16x16x32_bf16 v[20:23], v[132:135], v[216:219], v[20:23]
	v_mfma_f32_16x16x32_bf16 v[12:15], v[140:143], v[216:219], v[12:15]
	v_mfma_f32_16x16x32_bf16 v[4:7], v[132:135], v[228:231], v[4:7]
	v_mfma_f32_16x16x32_bf16 v[0:3], v[140:143], v[228:231], v[0:3]
	v_mfma_f32_16x16x32_bf16 v[52:55], v[136:139], v[204:207], v[52:55]
	v_mfma_f32_16x16x32_bf16 v[44:47], v[144:147], v[204:207], v[44:47]
	v_mfma_f32_16x16x32_bf16 v[36:39], v[136:139], v[212:215], v[36:39]
	v_mfma_f32_16x16x32_bf16 v[28:31], v[144:147], v[212:215], v[28:31]
	v_mfma_f32_16x16x32_bf16 v[20:23], v[136:139], v[220:223], v[20:23]
	v_mfma_f32_16x16x32_bf16 v[12:15], v[144:147], v[220:223], v[12:15]
	v_mfma_f32_16x16x32_bf16 v[4:7], v[136:139], v[232:235], v[4:7]
	v_mfma_f32_16x16x32_bf16 v[0:3], v[144:147], v[232:235], v[0:3]
	s_setprio 0
	s_barrier
	s_add_i32 s72, s72, 2
	s_add_u32 s30, s30, 0x100
	s_addc_u32 s31, s31, 0
	s_add_u32 s43, s43, 0x100
	s_addc_u32 s45, s45, 0
	s_add_u32 s0, s0, 0x100
	s_addc_u32 s1, s1, 0
	s_cmp_gt_u32 s72, 29
	s_cbranch_scc0 .LBB0_1382
	s_and_b64 vcc, exec, s[6:7]
	s_cbranch_vccz .LBB0_1385
	s_barrier

; #define PG8_LDA(dst, b, h) do { _Pragma("unroll") for (int m = 0; m < 4; ++m) _Pragma("unroll") for (int k = 0; k < 2; ++k) dst[m][k] = *(const LAS bf16x8*)(lds + PG8_SA(b, h) + aoff + m * 2048 + k * 1024); } while (0)
; #define PG8_LDB(dst, b, h) do { _Pragma("unroll") for (int n = 0; n < 2; ++n) _Pragma("unroll") for (int k = 0; k < 2; ++k) dst[n][k] = *(const LAS bf16x8*)(lds + PG8_SB(b, h) + boff + n * 2048 + k * 1024); } while (0)
; #define PG8_MMA(ai, bj, At, Bt) do { __builtin_amdgcn_s_setprio(1); _Pragma("unroll") for (int m = 0; m < 4; ++m) _Pragma("unroll") for (int n = 0; n < 2; ++n) _Pragma("unroll") for (int k = 0; k < 2; ++k) \
;         acc[ai][bj][m][n] = __builtin_amdgcn_mfma_f32_16x16x32_bf16(Bt[n][k], At[m][k], acc[ai][bj][m][n], 0, 0, 0); __builtin_amdgcn_s_setprio(0); } while (0)
; #define PG8_WAIT_V(n) asm volatile("s_waitcnt vmcnt(" #n ")" ::: "memory")
; #define PG8_WAIT_L(n) asm volatile("s_waitcnt lgkmcnt(" #n ")" ::: "memory")
; #define PG8_BAR __builtin_amdgcn_s_barrier()
; #define PG8_SCHED __builtin_amdgcn_sched_barrier(0)
; __device__ __forceinline__ void gemm_phase(LAS unsigned char* lds, const GemmP& g) {
;     ...
;         for (int t = 0; t < nt; t += 2) {
;             const bool last = (t == nt - 2);
;             const char* a1 = cA + (size_t)(t + 1) * kstep;
;             const char* a2 = last ? nA : cA + (size_t)(t + 2) * kstep; const char* b2 = last ? nB : cB + (size_t)(t + 2) * kstep;
;             const char* a3 = a2 + kstep; const char* b3 = b2 + kstep;
;             PG8_LDB(B0, 0, 0); PG8_LDB(B1, 0, 1); PG8_SCHED; PG8_LDA(At, 0, 0); PG8_STAGE(PG8_SA(1, 1), a1 + hstepA, voffA);
;             PG8_WAIT_V(8); PG8_WAIT_L(0); PG8_BAR; PG8_MMA(0, 0, At, B0); PG8_MMA(0, 1, At, B1); PG8_BAR; PG8_SCHED;
;             PG8_LDA(At, 0, 1); PG8_STAGE(PG8_SB(0, 0), b2, voffB); PG8_STAGE(PG8_SB(0, 1), b2 + hstepB, voffB); PG8_STAGE(PG8_SA(0, 0), a2, voffA);
;             PG8_WAIT_V(8); PG8_WAIT_L(0); PG8_BAR; PG8_MMA(1, 0, At, B0); PG8_MMA(1, 1, At, B1); PG8_BAR; PG8_SCHED;
.LBB0_1536:
	ds_read_b128 v[160:163], v157
	ds_read_b128 v[164:167], v157 offset:1024
	ds_read_b128 v[168:171], v157 offset:2048
	ds_read_b128 v[172:175], v157 offset:3072
	ds_read_b128 v[176:179], v158
	ds_read_b128 v[180:183], v158 offset:1024
	ds_read_b128 v[184:187], v158 offset:2048
	ds_read_b128 v[188:191], v158 offset:3072
	s_cmp_eq_u32 s63, 28
	s_cselect_b32 s44, s17, s59
	s_cselect_b32 s45, s9, s60
	s_cselect_b32 s42, s19, s61
	s_cselect_b32 s43, s11, s62
	s_add_u32 s40, s44, 0x80
	s_addc_u32 s41, s45, 0
	v_lshl_add_u64 v[154:155], s[38:39], 0, v[128:129]
	s_add_i32 m0, s46, 0xc000
	ds_read_b128 v[192:195], v159
	ds_read_b128 v[196:199], v159 offset:1024
	ds_read_b128 v[200:203], v159 offset:2048
	ds_read_b128 v[204:207], v159 offset:3072
	ds_read_b128 v[208:211], v159 offset:4096
	ds_read_b128 v[212:215], v159 offset:5120
	ds_read_b128 v[216:219], v159 offset:6144
	ds_read_b128 v[220:223], v159 offset:7168
	global_load_lds_dwordx4 v[154:155], off
	v_lshl_add_u64 v[154:155], s[38:39], 0, v[132:133]
	s_add_i32 m0, s46, 0xe000
	s_nop 0
	global_load_lds_dwordx4 v[154:155], off
	s_waitcnt vmcnt(8)
	s_waitcnt lgkmcnt(0)
	s_barrier
	s_setprio 1
	s_waitcnt lgkmcnt(0)
	v_mfma_f32_16x16x32_bf16 v[124:127], v[160:163], v[192:195], v[124:127]
	v_mfma_f32_16x16x32_bf16 v[120:123], v[168:171], v[192:195], v[120:123]
	v_mfma_f32_16x16x32_bf16 v[108:111], v[160:163], v[200:203], v[108:111]
	v_mfma_f32_16x16x32_bf16 v[104:107], v[168:171], v[200:203], v[104:107]
	v_mfma_f32_16x16x32_bf16 v[92:95], v[160:163], v[208:211], v[92:95]
	v_mfma_f32_16x16x32_bf16 v[88:91], v[168:171], v[208:211], v[88:91]
	v_mfma_f32_16x16x32_bf16 v[76:79], v[160:163], v[216:219], v[76:79]
	v_mfma_f32_16x16x32_bf16 v[72:75], v[168:171], v[216:219], v[72:75]
	v_mfma_f32_16x16x32_bf16 v[124:127], v[164:167], v[196:199], v[124:127]
	v_mfma_f32_16x16x32_bf16 v[120:123], v[172:175], v[196:199], v[120:123]
	v_mfma_f32_16x16x32_bf16 v[108:111], v[164:167], v[204:207], v[108:111]
	v_mfma_f32_16x16x32_bf16 v[104:107], v[172:175], v[204:207], v[104:107]
	v_mfma_f32_16x16x32_bf16 v[92:95], v[164:167], v[212:215], v[92:95]
	v_mfma_f32_16x16x32_bf16 v[88:91], v[172:175], v[212:215], v[88:91]
	v_mfma_f32_16x16x32_bf16 v[76:79], v[164:167], v[220:223], v[76:79]
	v_mfma_f32_16x16x32_bf16 v[72:75], v[172:175], v[220:223], v[72:75]
	v_mfma_f32_16x16x32_bf16 v[116:119], v[176:179], v[192:195], v[116:119]
	v_mfma_f32_16x16x32_bf16 v[112:115], v[184:187], v[192:195], v[112:115]
	v_mfma_f32_16x16x32_bf16 v[100:103], v[176:179], v[200:203], v[100:103]
	v_mfma_f32_16x16x32_bf16 v[96:99], v[184:187], v[200:203], v[96:99]
	v_mfma_f32_16x16x32_bf16 v[84:87], v[176:179], v[208:211], v[84:87]
	v_mfma_f32_16x16x32_bf16 v[80:83], v[184:187], v[208:211], v[80:83]
	v_mfma_f32_16x16x32_bf16 v[68:71], v[176:179], v[216:219], v[68:71]
	v_mfma_f32_16x16x32_bf16 v[64:67], v[184:187], v[216:219], v[64:67]
	v_mfma_f32_16x16x32_bf16 v[116:119], v[180:183], v[196:199], v[116:119]
	v_mfma_f32_16x16x32_bf16 v[112:115], v[188:191], v[196:199], v[112:115]
	v_mfma_f32_16x16x32_bf16 v[100:103], v[180:183], v[204:207], v[100:103]
	v_mfma_f32_16x16x32_bf16 v[96:99], v[188:191], v[204:207], v[96:99]
	v_mfma_f32_16x16x32_bf16 v[84:87], v[180:183], v[212:215], v[84:87]
	v_mfma_f32_16x16x32_bf16 v[80:83], v[188:191], v[212:215], v[80:83]
	v_mfma_f32_16x16x32_bf16 v[68:71], v[180:183], v[220:223], v[68:71]
	v_mfma_f32_16x16x32_bf16 v[64:67], v[188:191], v[220:223], v[64:67]
	s_setprio 0
	s_barrier
	s_add_i32 s64, s31, s33
	v_lshl_add_u64 v[154:155], s[42:43], 0, v[130:131]
	s_mov_b32 m0, s64
	ds_read_b128 v[192:195], v159 offset:16384
	ds_read_b128 v[196:199], v159 offset:17408
	ds_read_b128 v[200:203], v159 offset:18432
	ds_read_b128 v[204:207], v159 offset:19456
	ds_read_b128 v[208:211], v159 offset:20480
	ds_read_b128 v[212:215], v159 offset:21504
	ds_read_b128 v[216:219], v159 offset:22528
	ds_read_b128 v[220:223], v159 offset:23552
	global_load_lds_dwordx4 v[154:155], off
	s_add_i32 m0, s64, 0x2000
	s_add_u32 s64, s42, 0x80000
	v_lshl_add_u64 v[154:155], s[42:43], 0, v[134:135]
	s_addc_u32 s65, s43, 0
	s_add_i32 s66, s57, s33
	global_load_lds_dwordx4 v[154:155], off
	v_lshl_add_u64 v[154:155], s[64:65], 0, v[130:131]
	s_mov_b32 m0, s66
	s_nop 0
	global_load_lds_dwordx4 v[154:155], off
	v_lshl_add_u64 v[154:155], s[64:65], 0, v[134:135]
	s_add_i32 m0, s66, 0x2000
	s_nop 0
	global_load_lds_dwordx4 v[154:155], off
	v_lshl_add_u64 v[154:155], s[44:45], 0, v[128:129]
	s_mov_b32 m0, s46
	s_nop 0
	global_load_lds_dwordx4 v[154:155], off
	v_lshl_add_u64 v[154:155], s[44:45], 0, v[132:133]
	s_mov_b32 m0, s47
	s_nop 0
	global_load_lds_dwordx4 v[154:155], off
	s_waitcnt vmcnt(8)
	s_waitcnt lgkmcnt(0)
	s_barrier
; #define PG8_LDA(dst, b, h) do { _Pragma("unroll") for (int m = 0; m < 4; ++m) _Pragma("unroll") for (int k = 0; k < 2; ++k) dst[m][k] = *(const LAS bf16x8*)(lds + PG8_SA(b, h) + aoff + m * 2048 + k * 1024); } while (0)
; #define PG8_LDB(dst, b, h) do { _Pragma("unroll") for (int n = 0; n < 2; ++n) _Pragma("unroll") for (int k = 0; k < 2; ++k) dst[n][k] = *(const LAS bf16x8*)(lds + PG8_SB(b, h) + boff + n * 2048 + k * 1024); } while (0)
; #define PG8_MMA(ai, bj, At, Bt) do { __builtin_amdgcn_s_setprio(1); _Pragma("unroll") for (int m = 0; m < 4; ++m) _Pragma("unroll") for (int n = 0; n < 2; ++n) _Pragma("unroll") for (int k = 0; k < 2; ++k) \
;         acc[ai][bj][m][n] = __builtin_amdgcn_mfma_f32_16x16x32_bf16(Bt[n][k], At[m][k], acc[ai][bj][m][n], 0, 0, 0); __builtin_amdgcn_s_setprio(0); } while (0)
; #define PG8_WAIT_V(n) asm volatile("s_waitcnt vmcnt(" #n ")" ::: "memory")
; #define PG8_WAIT_L(n) asm volatile("s_waitcnt lgkmcnt(" #n ")" ::: "memory")
; #define PG8_BAR __builtin_amdgcn_s_barrier()
; #define PG8_SCHED __builtin_amdgcn_sched_barrier(0)
; __device__ __forceinline__ void gemm_phase(LAS unsigned char* lds, const GemmP& g) {
;     ...
;             PG8_WAIT_V(8); PG8_WAIT_L(0); PG8_BAR; PG8_MMA(1, 0, At, B0); PG8_MMA(1, 1, At, B1); PG8_BAR; PG8_SCHED;
;             PG8_LDB(B0, 1, 0); PG8_LDB(B1, 1, 1); PG8_SCHED; PG8_LDA(At, 1, 0); PG8_STAGE(PG8_SA(0, 1), a2 + hstepA, voffA);
;             PG8_WAIT_V(8); PG8_WAIT_L(0); PG8_BAR; PG8_MMA(0, 0, At, B0); PG8_MMA(0, 1, At, B1); PG8_BAR; PG8_SCHED;
	s_setprio 1
	s_waitcnt lgkmcnt(0)
	v_mfma_f32_16x16x32_bf16 v[60:63], v[160:163], v[192:195], v[60:63]
	v_mfma_f32_16x16x32_bf16 v[56:59], v[168:171], v[192:195], v[56:59]
	v_mfma_f32_16x16x32_bf16 v[44:47], v[160:163], v[200:203], v[44:47]
	v_mfma_f32_16x16x32_bf16 v[40:43], v[168:171], v[200:203], v[40:43]
	v_mfma_f32_16x16x32_bf16 v[28:31], v[160:163], v[208:211], v[28:31]
	v_mfma_f32_16x16x32_bf16 v[24:27], v[168:171], v[208:211], v[24:27]
	v_mfma_f32_16x16x32_bf16 v[12:15], v[160:163], v[216:219], v[12:15]
	v_mfma_f32_16x16x32_bf16 v[8:11], v[168:171], v[216:219], v[8:11]
	v_mfma_f32_16x16x32_bf16 v[60:63], v[164:167], v[196:199], v[60:63]
	v_mfma_f32_16x16x32_bf16 v[56:59], v[172:175], v[196:199], v[56:59]
	v_mfma_f32_16x16x32_bf16 v[44:47], v[164:167], v[204:207], v[44:47]
	v_mfma_f32_16x16x32_bf16 v[40:43], v[172:175], v[204:207], v[40:43]
	v_mfma_f32_16x16x32_bf16 v[28:31], v[164:167], v[212:215], v[28:31]
	v_mfma_f32_16x16x32_bf16 v[24:27], v[172:175], v[212:215], v[24:27]
	v_mfma_f32_16x16x32_bf16 v[12:15], v[164:167], v[220:223], v[12:15]
	v_mfma_f32_16x16x32_bf16 v[8:11], v[172:175], v[220:223], v[8:11]
	v_mfma_f32_16x16x32_bf16 v[52:55], v[176:179], v[192:195], v[52:55]
	v_mfma_f32_16x16x32_bf16 v[48:51], v[184:187], v[192:195], v[48:51]
	v_mfma_f32_16x16x32_bf16 v[36:39], v[176:179], v[200:203], v[36:39]
	v_mfma_f32_16x16x32_bf16 v[32:35], v[184:187], v[200:203], v[32:35]
	v_mfma_f32_16x16x32_bf16 v[20:23], v[176:179], v[208:211], v[20:23]
	v_mfma_f32_16x16x32_bf16 v[16:19], v[184:187], v[208:211], v[16:19]
	v_mfma_f32_16x16x32_bf16 v[4:7], v[176:179], v[216:219], v[4:7]
	v_mfma_f32_16x16x32_bf16 v[0:3], v[184:187], v[216:219], v[0:3]
	v_mfma_f32_16x16x32_bf16 v[52:55], v[180:183], v[196:199], v[52:55]
	v_mfma_f32_16x16x32_bf16 v[48:51], v[188:191], v[196:199], v[48:51]
	v_mfma_f32_16x16x32_bf16 v[36:39], v[180:183], v[204:207], v[36:39]
	v_mfma_f32_16x16x32_bf16 v[32:35], v[188:191], v[204:207], v[32:35]
	v_mfma_f32_16x16x32_bf16 v[20:23], v[180:183], v[212:215], v[20:23]
	v_mfma_f32_16x16x32_bf16 v[16:19], v[188:191], v[212:215], v[16:19]
	v_mfma_f32_16x16x32_bf16 v[4:7], v[180:183], v[220:223], v[4:7]
	v_mfma_f32_16x16x32_bf16 v[0:3], v[188:191], v[220:223], v[0:3]
	s_setprio 0
	s_barrier
	s_add_i32 s64, 0, 0x18000
	v_add_u32_e32 v154, s64, v156
	s_add_i32 s65, 0, 0x1c000
	ds_read_b128 v[160:163], v154
	ds_read_b128 v[164:167], v154 offset:1024
	ds_read_b128 v[168:171], v154 offset:2048
	ds_read_b128 v[172:175], v154 offset:3072
	v_add_u32_e32 v154, s65, v156
	ds_read_b128 v[176:179], v154
	ds_read_b128 v[180:183], v154 offset:1024
	ds_read_b128 v[184:187], v154 offset:2048
	ds_read_b128 v[188:191], v154 offset:3072
	s_add_u32 s44, s44, 0x80000
	s_addc_u32 s45, s45, 0
	s_mov_b32 m0, s52
	v_lshl_add_u64 v[154:155], s[44:45], 0, v[128:129]
	ds_read_b128 v[192:195], v159 offset:32768
	ds_read_b128 v[196:199], v159 offset:33792
	ds_read_b128 v[200:203], v159 offset:34816
	ds_read_b128 v[204:207], v159 offset:35840
	ds_read_b128 v[208:211], v159 offset:36864
	ds_read_b128 v[212:215], v159 offset:37888
	ds_read_b128 v[216:219], v159 offset:38912
	ds_read_b128 v[220:223], v159 offset:39936
	global_load_lds_dwordx4 v[154:155], off
	v_lshl_add_u64 v[154:155], s[44:45], 0, v[132:133]
	s_mov_b32 m0, s53
	s_nop 0
	global_load_lds_dwordx4 v[154:155], off
	s_waitcnt vmcnt(8)
	s_waitcnt lgkmcnt(0)
	s_barrier
	s_setprio 1
	s_waitcnt lgkmcnt(0)
	v_mfma_f32_16x16x32_bf16 v[124:127], v[160:163], v[192:195], v[124:127]
	v_mfma_f32_16x16x32_bf16 v[120:123], v[168:171], v[192:195], v[120:123]
	v_mfma_f32_16x16x32_bf16 v[108:111], v[160:163], v[200:203], v[108:111]
	v_mfma_f32_16x16x32_bf16 v[104:107], v[168:171], v[200:203], v[104:107]
	v_mfma_f32_16x16x32_bf16 v[92:95], v[160:163], v[208:211], v[92:95]
	v_mfma_f32_16x16x32_bf16 v[88:91], v[168:171], v[208:211], v[88:91]
	v_mfma_f32_16x16x32_bf16 v[76:79], v[160:163], v[216:219], v[76:79]
	v_mfma_f32_16x16x32_bf16 v[72:75], v[168:171], v[216:219], v[72:75]
	v_mfma_f32_16x16x32_bf16 v[124:127], v[164:167], v[196:199], v[124:127]
	v_mfma_f32_16x16x32_bf16 v[120:123], v[172:175], v[196:199], v[120:123]
	v_mfma_f32_16x16x32_bf16 v[108:111], v[164:167], v[204:207], v[108:111]
	v_mfma_f32_16x16x32_bf16 v[104:107], v[172:175], v[204:207], v[104:107]
	v_mfma_f32_16x16x32_bf16 v[92:95], v[164:167], v[212:215], v[92:95]
	v_mfma_f32_16x16x32_bf16 v[88:91], v[172:175], v[212:215], v[88:91]
	v_mfma_f32_16x16x32_bf16 v[76:79], v[164:167], v[220:223], v[76:79]
	v_mfma_f32_16x16x32_bf16 v[72:75], v[172:175], v[220:223], v[72:75]
	v_mfma_f32_16x16x32_bf16 v[116:119], v[176:179], v[192:195], v[116:119]
	v_mfma_f32_16x16x32_bf16 v[112:115], v[184:187], v[192:195], v[112:115]
	v_mfma_f32_16x16x32_bf16 v[100:103], v[176:179], v[200:203], v[100:103]
	v_mfma_f32_16x16x32_bf16 v[96:99], v[184:187], v[200:203], v[96:99]
	v_mfma_f32_16x16x32_bf16 v[84:87], v[176:179], v[208:211], v[84:87]
	v_mfma_f32_16x16x32_bf16 v[80:83], v[184:187], v[208:211], v[80:83]
	v_mfma_f32_16x16x32_bf16 v[68:71], v[176:179], v[216:219], v[68:71]
	v_mfma_f32_16x16x32_bf16 v[64:67], v[184:187], v[216:219], v[64:67]
	v_mfma_f32_16x16x32_bf16 v[116:119], v[180:183], v[196:199], v[116:119]
	v_mfma_f32_16x16x32_bf16 v[112:115], v[188:191], v[196:199], v[112:115]
	v_mfma_f32_16x16x32_bf16 v[100:103], v[180:183], v[204:207], v[100:103]
	v_mfma_f32_16x16x32_bf16 v[96:99], v[188:191], v[204:207], v[96:99]
	v_mfma_f32_16x16x32_bf16 v[84:87], v[180:183], v[212:215], v[84:87]
	v_mfma_f32_16x16x32_bf16 v[80:83], v[188:191], v[212:215], v[80:83]
	v_mfma_f32_16x16x32_bf16 v[68:71], v[180:183], v[220:223], v[68:71]
	v_mfma_f32_16x16x32_bf16 v[64:67], v[188:191], v[220:223], v[64:67]
	s_setprio 0
	s_barrier
; #define PG8_LDA(dst, b, h) do { _Pragma("unroll") for (int m = 0; m < 4; ++m) _Pragma("unroll") for (int k = 0; k < 2; ++k) dst[m][k] = *(const LAS bf16x8*)(lds + PG8_SA(b, h) + aoff + m * 2048 + k * 1024); } while (0)
; #define PG8_MMA(ai, bj, At, Bt) do { __builtin_amdgcn_s_setprio(1); _Pragma("unroll") for (int m = 0; m < 4; ++m) _Pragma("unroll") for (int n = 0; n < 2; ++n) _Pragma("unroll") for (int k = 0; k < 2; ++k) \
;         acc[ai][bj][m][n] = __builtin_amdgcn_mfma_f32_16x16x32_bf16(Bt[n][k], At[m][k], acc[ai][bj][m][n], 0, 0, 0); __builtin_amdgcn_s_setprio(0); } while (0)
; #define PG8_WAIT_V(n) asm volatile("s_waitcnt vmcnt(" #n ")" ::: "memory")
; #define PG8_WAIT_L(n) asm volatile("s_waitcnt lgkmcnt(" #n ")" ::: "memory")
; #define PG8_BAR __builtin_amdgcn_s_barrier()
; #define PG8_SCHED __builtin_amdgcn_sched_barrier(0)
; __device__ __forceinline__ void gemm_phase(LAS unsigned char* lds, const GemmP& g) {
;     ...
;             PG8_LDA(At, 1, 1); PG8_STAGE(PG8_SB(1, 0), b3, voffB); PG8_STAGE(PG8_SB(1, 1), b3 + hstepB, voffB); PG8_STAGE(PG8_SA(1, 0), a3, voffA);
;             PG8_WAIT_V(8); PG8_WAIT_L(0); PG8_BAR; PG8_MMA(1, 0, At, B0); PG8_MMA(1, 1, At, B1); PG8_BAR; PG8_SCHED;
;         }
;         if (wr == 0) PG8_BAR;
	s_add_u32 s44, s42, 0x80
	s_addc_u32 s45, s43, 0
	s_add_i32 s64, s64, s33
	v_lshl_add_u64 v[154:155], s[44:45], 0, v[130:131]
	s_mov_b32 m0, s64
	ds_read_b128 v[192:195], v159 offset:49152
	ds_read_b128 v[196:199], v159 offset:50176
	ds_read_b128 v[200:203], v159 offset:51200
	ds_read_b128 v[204:207], v159 offset:52224
	ds_read_b128 v[208:211], v159 offset:53248
	ds_read_b128 v[212:215], v159 offset:54272
	ds_read_b128 v[216:219], v159 offset:55296
	ds_read_b128 v[220:223], v159 offset:56320
	global_load_lds_dwordx4 v[154:155], off
	s_add_i32 m0, s64, 0x2000
	s_add_u32 s42, s42, 0x80080
	v_lshl_add_u64 v[154:155], s[44:45], 0, v[134:135]
	s_addc_u32 s43, s43, 0
	s_add_i32 s44, s65, s33
	global_load_lds_dwordx4 v[154:155], off
	v_lshl_add_u64 v[154:155], s[42:43], 0, v[130:131]
	s_mov_b32 m0, s44
	s_nop 0
	global_load_lds_dwordx4 v[154:155], off
	v_lshl_add_u64 v[154:155], s[42:43], 0, v[134:135]
	s_add_i32 m0, s44, 0x2000
	s_nop 0
	global_load_lds_dwordx4 v[154:155], off
	v_lshl_add_u64 v[154:155], s[40:41], 0, v[128:129]
	s_mov_b32 m0, s20
	s_nop 0
	global_load_lds_dwordx4 v[154:155], off
	v_lshl_add_u64 v[154:155], s[40:41], 0, v[132:133]
	s_mov_b32 m0, s21
	s_nop 0
	global_load_lds_dwordx4 v[154:155], off
	s_waitcnt vmcnt(8)
	s_waitcnt lgkmcnt(0)
	s_barrier
	s_setprio 1
	s_waitcnt lgkmcnt(0)
	v_mfma_f32_16x16x32_bf16 v[60:63], v[160:163], v[192:195], v[60:63]
	v_mfma_f32_16x16x32_bf16 v[56:59], v[168:171], v[192:195], v[56:59]
	v_mfma_f32_16x16x32_bf16 v[44:47], v[160:163], v[200:203], v[44:47]
	v_mfma_f32_16x16x32_bf16 v[40:43], v[168:171], v[200:203], v[40:43]
	v_mfma_f32_16x16x32_bf16 v[28:31], v[160:163], v[208:211], v[28:31]
	v_mfma_f32_16x16x32_bf16 v[24:27], v[168:171], v[208:211], v[24:27]
	v_mfma_f32_16x16x32_bf16 v[12:15], v[160:163], v[216:219], v[12:15]
	v_mfma_f32_16x16x32_bf16 v[8:11], v[168:171], v[216:219], v[8:11]
	v_mfma_f32_16x16x32_bf16 v[60:63], v[164:167], v[196:199], v[60:63]
	v_mfma_f32_16x16x32_bf16 v[56:59], v[172:175], v[196:199], v[56:59]
	v_mfma_f32_16x16x32_bf16 v[44:47], v[164:167], v[204:207], v[44:47]
	v_mfma_f32_16x16x32_bf16 v[40:43], v[172:175], v[204:207], v[40:43]
	v_mfma_f32_16x16x32_bf16 v[28:31], v[164:167], v[212:215], v[28:31]
	v_mfma_f32_16x16x32_bf16 v[24:27], v[172:175], v[212:215], v[24:27]
	v_mfma_f32_16x16x32_bf16 v[12:15], v[164:167], v[220:223], v[12:15]
	v_mfma_f32_16x16x32_bf16 v[8:11], v[172:175], v[220:223], v[8:11]
	v_mfma_f32_16x16x32_bf16 v[52:55], v[176:179], v[192:195], v[52:55]
	v_mfma_f32_16x16x32_bf16 v[48:51], v[184:187], v[192:195], v[48:51]
	v_mfma_f32_16x16x32_bf16 v[36:39], v[176:179], v[200:203], v[36:39]
	v_mfma_f32_16x16x32_bf16 v[32:35], v[184:187], v[200:203], v[32:35]
	v_mfma_f32_16x16x32_bf16 v[20:23], v[176:179], v[208:211], v[20:23]
	v_mfma_f32_16x16x32_bf16 v[16:19], v[184:187], v[208:211], v[16:19]
	v_mfma_f32_16x16x32_bf16 v[4:7], v[176:179], v[216:219], v[4:7]
	v_mfma_f32_16x16x32_bf16 v[0:3], v[184:187], v[216:219], v[0:3]
	v_mfma_f32_16x16x32_bf16 v[52:55], v[180:183], v[196:199], v[52:55]
	v_mfma_f32_16x16x32_bf16 v[48:51], v[188:191], v[196:199], v[48:51]
	v_mfma_f32_16x16x32_bf16 v[36:39], v[180:183], v[204:207], v[36:39]
	v_mfma_f32_16x16x32_bf16 v[32:35], v[188:191], v[204:207], v[32:35]
	v_mfma_f32_16x16x32_bf16 v[20:23], v[180:183], v[212:215], v[20:23]
	v_mfma_f32_16x16x32_bf16 v[16:19], v[188:191], v[212:215], v[16:19]
	v_mfma_f32_16x16x32_bf16 v[4:7], v[180:183], v[220:223], v[4:7]
	v_mfma_f32_16x16x32_bf16 v[0:3], v[188:191], v[220:223], v[0:3]
	s_setprio 0
	s_barrier
	s_add_i32 s63, s63, 2
	s_add_u32 s59, s59, 0x100
	s_addc_u32 s60, s60, 0
	s_add_u32 s61, s61, 0x100
	s_addc_u32 s62, s62, 0
	s_add_u32 s38, s38, 0x100
	s_addc_u32 s39, s39, 0
	s_cmp_gt_u32 s63, 29
	s_cbranch_scc0 .LBB0_1536
	s_and_b64 vcc, exec, s[4:5]
	s_cbranch_vccz .LBB0_1539
	s_barrier

; #define PG8_LDA(dst, b, h) do { _Pragma("unroll") for (int m = 0; m < 4; ++m) _Pragma("unroll") for (int k = 0; k < 2; ++k) dst[m][k] = *(const LAS bf16x8*)(lds + PG8_SA(b, h) + aoff + m * 2048 + k * 1024); } while (0)
; #define PG8_LDB(dst, b, h) do { _Pragma("unroll") for (int n = 0; n < 2; ++n) _Pragma("unroll") for (int k = 0; k < 2; ++k) dst[n][k] = *(const LAS bf16x8*)(lds + PG8_SB(b, h) + boff + n * 2048 + k * 1024); } while (0)
; #define PG8_MMA(ai, bj, At, Bt) do { __builtin_amdgcn_s_setprio(1); _Pragma("unroll") for (int m = 0; m < 4; ++m) _Pragma("unroll") for (int n = 0; n < 2; ++n) _Pragma("unroll") for (int k = 0; k < 2; ++k) \
;         acc[ai][bj][m][n] = __builtin_amdgcn_mfma_f32_16x16x32_bf16(Bt[n][k], At[m][k], acc[ai][bj][m][n], 0, 0, 0); __builtin_amdgcn_s_setprio(0); } while (0)
; #define PG8_WAIT_V(n) asm volatile("s_waitcnt vmcnt(" #n ")" ::: "memory")
; #define PG8_WAIT_L(n) asm volatile("s_waitcnt lgkmcnt(" #n ")" ::: "memory")
; #define PG8_BAR __builtin_amdgcn_s_barrier()
; #define PG8_SCHED __builtin_amdgcn_sched_barrier(0)
; __device__ __forceinline__ void gemm_phase(LAS unsigned char* lds, const GemmP& g) {
;     ...
;         for (int t = 0; t < nt; t += 2) {
;             const bool last = (t == nt - 2);
;             const char* a1 = cA + (size_t)(t + 1) * kstep;
;             const char* a2 = last ? nA : cA + (size_t)(t + 2) * kstep; const char* b2 = last ? nB : cB + (size_t)(t + 2) * kstep;
;             const char* a3 = a2 + kstep; const char* b3 = b2 + kstep;
;             PG8_LDB(B0, 0, 0); PG8_LDB(B1, 0, 1); PG8_SCHED; PG8_LDA(At, 0, 0); PG8_STAGE(PG8_SA(1, 1), a1 + hstepA, voffA);
;             PG8_WAIT_V(8); PG8_WAIT_L(0); PG8_BAR; PG8_MMA(0, 0, At, B0); PG8_MMA(0, 1, At, B1); PG8_BAR; PG8_SCHED;
;             PG8_LDA(At, 0, 1); PG8_STAGE(PG8_SB(0, 0), b2, voffB); PG8_STAGE(PG8_SB(0, 1), b2 + hstepB, voffB); PG8_STAGE(PG8_SA(0, 0), a2, voffA);
;             PG8_WAIT_V(8); PG8_WAIT_L(0); PG8_BAR; PG8_MMA(1, 0, At, B0); PG8_MMA(1, 1, At, B1); PG8_BAR; PG8_SCHED;
.LBB0_1615:
	v_add_u32_e32 v140, s36, v149
	v_add_u32_e32 v184, s37, v149
	ds_read_b128 v[128:131], v140
	ds_read_b128 v[132:135], v140 offset:1024
	ds_read_b128 v[136:139], v140 offset:2048
	ds_read_b128 v[140:143], v140 offset:3072
	ds_read_b128 v[188:191], v184
	ds_read_b128 v[192:195], v184 offset:1024
	ds_read_b128 v[196:199], v184 offset:2048
	ds_read_b128 v[200:203], v184 offset:3072
	s_cmpk_eq_i32 s49, 0x7c
	s_cselect_b32 s26, s15, s45
	s_cselect_b32 s27, s7, s46
	s_cselect_b32 s24, s17, s47
	s_cselect_b32 s25, s9, s48
	s_add_u32 s20, s26, 0x80
	s_addc_u32 s21, s27, 0
	v_lshl_add_u64 v[184:185], s[18:19], 0, v[144:145]
	s_add_i32 m0, s33, 0xc000
	ds_read_b128 v[204:207], v186
	ds_read_b128 v[208:211], v186 offset:1024
	ds_read_b128 v[212:215], v186 offset:2048
	ds_read_b128 v[216:219], v186 offset:3072
	ds_read_b128 v[220:223], v186 offset:4096
	ds_read_b128 v[224:227], v186 offset:5120
	ds_read_b128 v[228:231], v186 offset:6144
	ds_read_b128 v[232:235], v186 offset:7168
	global_load_lds_dwordx4 v[184:185], off
	v_lshl_add_u64 v[184:185], s[18:19], 0, v[146:147]
	s_add_i32 m0, s33, 0xe000
	s_nop 0
	global_load_lds_dwordx4 v[184:185], off
	s_waitcnt vmcnt(8)
	s_waitcnt lgkmcnt(0)
	s_barrier
	s_setprio 1
	s_waitcnt lgkmcnt(0)
	v_mfma_f32_16x16x32_bf16 v[124:127], v[128:131], v[204:207], v[124:127]
	v_mfma_f32_16x16x32_bf16 v[120:123], v[136:139], v[204:207], v[120:123]
	v_mfma_f32_16x16x32_bf16 v[112:115], v[128:131], v[212:215], v[112:115]
	v_mfma_f32_16x16x32_bf16 v[104:107], v[136:139], v[212:215], v[104:107]
	v_mfma_f32_16x16x32_bf16 v[96:99], v[128:131], v[220:223], v[96:99]
	v_mfma_f32_16x16x32_bf16 v[88:91], v[136:139], v[220:223], v[88:91]
	v_mfma_f32_16x16x32_bf16 v[80:83], v[128:131], v[228:231], v[80:83]
	v_mfma_f32_16x16x32_bf16 v[72:75], v[136:139], v[228:231], v[72:75]
	v_mfma_f32_16x16x32_bf16 v[124:127], v[132:135], v[208:211], v[124:127]
	v_mfma_f32_16x16x32_bf16 v[120:123], v[140:143], v[208:211], v[120:123]
	v_mfma_f32_16x16x32_bf16 v[112:115], v[132:135], v[216:219], v[112:115]
	v_mfma_f32_16x16x32_bf16 v[104:107], v[140:143], v[216:219], v[104:107]
	v_mfma_f32_16x16x32_bf16 v[96:99], v[132:135], v[224:227], v[96:99]
	v_mfma_f32_16x16x32_bf16 v[88:91], v[140:143], v[224:227], v[88:91]
	v_mfma_f32_16x16x32_bf16 v[80:83], v[132:135], v[232:235], v[80:83]
	v_mfma_f32_16x16x32_bf16 v[72:75], v[140:143], v[232:235], v[72:75]
	v_mfma_f32_16x16x32_bf16 v[116:119], v[188:191], v[204:207], v[116:119]
	v_mfma_f32_16x16x32_bf16 v[108:111], v[196:199], v[204:207], v[108:111]
	v_mfma_f32_16x16x32_bf16 v[100:103], v[188:191], v[212:215], v[100:103]
	v_mfma_f32_16x16x32_bf16 v[92:95], v[196:199], v[212:215], v[92:95]
	v_mfma_f32_16x16x32_bf16 v[84:87], v[188:191], v[220:223], v[84:87]
	v_mfma_f32_16x16x32_bf16 v[76:79], v[196:199], v[220:223], v[76:79]
	v_mfma_f32_16x16x32_bf16 v[68:71], v[188:191], v[228:231], v[68:71]
	v_mfma_f32_16x16x32_bf16 v[64:67], v[196:199], v[228:231], v[64:67]
	v_mfma_f32_16x16x32_bf16 v[116:119], v[192:195], v[208:211], v[116:119]
	v_mfma_f32_16x16x32_bf16 v[108:111], v[200:203], v[208:211], v[108:111]
	v_mfma_f32_16x16x32_bf16 v[100:103], v[192:195], v[216:219], v[100:103]
	v_mfma_f32_16x16x32_bf16 v[92:95], v[200:203], v[216:219], v[92:95]
	v_mfma_f32_16x16x32_bf16 v[84:87], v[192:195], v[224:227], v[84:87]
	v_mfma_f32_16x16x32_bf16 v[76:79], v[200:203], v[224:227], v[76:79]
	v_mfma_f32_16x16x32_bf16 v[68:71], v[192:195], v[232:235], v[68:71]
	v_mfma_f32_16x16x32_bf16 v[64:67], v[200:203], v[232:235], v[64:67]
	s_setprio 0
	s_barrier
	s_add_i32 s50, s36, s31
	v_lshl_add_u64 v[184:185], s[24:25], 0, v[144:145]
	s_mov_b32 m0, s50
	ds_read_b128 v[204:207], v186 offset:16384
	ds_read_b128 v[208:211], v186 offset:17408
	ds_read_b128 v[212:215], v186 offset:18432
	ds_read_b128 v[216:219], v186 offset:19456
	ds_read_b128 v[220:223], v186 offset:20480
	ds_read_b128 v[224:227], v186 offset:21504
	ds_read_b128 v[228:231], v186 offset:22528
	ds_read_b128 v[232:235], v186 offset:23552
	global_load_lds_dwordx4 v[184:185], off
	s_add_i32 m0, s50, 0x2000
	s_add_u32 s50, s24, 0x200000
	v_lshl_add_u64 v[184:185], s[24:25], 0, v[146:147]
	s_addc_u32 s51, s25, 0
	s_add_i32 s52, s37, s31
	global_load_lds_dwordx4 v[184:185], off
	v_lshl_add_u64 v[184:185], s[50:51], 0, v[144:145]
	s_mov_b32 m0, s52
	s_nop 0
	global_load_lds_dwordx4 v[184:185], off
	v_lshl_add_u64 v[184:185], s[50:51], 0, v[146:147]
	s_add_i32 m0, s52, 0x2000
	s_nop 0
	global_load_lds_dwordx4 v[184:185], off
	v_lshl_add_u64 v[184:185], s[26:27], 0, v[144:145]
	s_mov_b32 m0, s33
	s_nop 0
	global_load_lds_dwordx4 v[184:185], off
	v_lshl_add_u64 v[184:185], s[26:27], 0, v[146:147]
	s_mov_b32 m0, s34
	s_nop 0
	global_load_lds_dwordx4 v[184:185], off
	s_waitcnt vmcnt(8)
	s_waitcnt lgkmcnt(0)
	s_barrier
; #define PG8_LDA(dst, b, h) do { _Pragma("unroll") for (int m = 0; m < 4; ++m) _Pragma("unroll") for (int k = 0; k < 2; ++k) dst[m][k] = *(const LAS bf16x8*)(lds + PG8_SA(b, h) + aoff + m * 2048 + k * 1024); } while (0)
; #define PG8_LDB(dst, b, h) do { _Pragma("unroll") for (int n = 0; n < 2; ++n) _Pragma("unroll") for (int k = 0; k < 2; ++k) dst[n][k] = *(const LAS bf16x8*)(lds + PG8_SB(b, h) + boff + n * 2048 + k * 1024); } while (0)
; #define PG8_MMA(ai, bj, At, Bt) do { __builtin_amdgcn_s_setprio(1); _Pragma("unroll") for (int m = 0; m < 4; ++m) _Pragma("unroll") for (int n = 0; n < 2; ++n) _Pragma("unroll") for (int k = 0; k < 2; ++k) \
;         acc[ai][bj][m][n] = __builtin_amdgcn_mfma_f32_16x16x32_bf16(Bt[n][k], At[m][k], acc[ai][bj][m][n], 0, 0, 0); __builtin_amdgcn_s_setprio(0); } while (0)
; #define PG8_WAIT_V(n) asm volatile("s_waitcnt vmcnt(" #n ")" ::: "memory")
; #define PG8_WAIT_L(n) asm volatile("s_waitcnt lgkmcnt(" #n ")" ::: "memory")
; #define PG8_BAR __builtin_amdgcn_s_barrier()
; #define PG8_SCHED __builtin_amdgcn_sched_barrier(0)
; __device__ __forceinline__ void gemm_phase(LAS unsigned char* lds, const GemmP& g) {
;     ...
;             PG8_WAIT_V(8); PG8_WAIT_L(0); PG8_BAR; PG8_MMA(1, 0, At, B0); PG8_MMA(1, 1, At, B1); PG8_BAR; PG8_SCHED;
;             PG8_LDB(B0, 1, 0); PG8_LDB(B1, 1, 1); PG8_SCHED; PG8_LDA(At, 1, 0); PG8_STAGE(PG8_SA(0, 1), a2 + hstepA, voffA);
;             PG8_WAIT_V(8); PG8_WAIT_L(0); PG8_BAR; PG8_MMA(0, 0, At, B0); PG8_MMA(0, 1, At, B1); PG8_BAR; PG8_SCHED;
	s_setprio 1
	s_waitcnt lgkmcnt(0)
	v_mfma_f32_16x16x32_bf16 v[60:63], v[128:131], v[204:207], v[60:63]
	v_mfma_f32_16x16x32_bf16 v[56:59], v[136:139], v[204:207], v[56:59]
	v_mfma_f32_16x16x32_bf16 v[48:51], v[128:131], v[212:215], v[48:51]
	v_mfma_f32_16x16x32_bf16 v[40:43], v[136:139], v[212:215], v[40:43]
	v_mfma_f32_16x16x32_bf16 v[32:35], v[128:131], v[220:223], v[32:35]
	v_mfma_f32_16x16x32_bf16 v[24:27], v[136:139], v[220:223], v[24:27]
	v_mfma_f32_16x16x32_bf16 v[16:19], v[128:131], v[228:231], v[16:19]
	v_mfma_f32_16x16x32_bf16 v[8:11], v[136:139], v[228:231], v[8:11]
	v_mfma_f32_16x16x32_bf16 v[60:63], v[132:135], v[208:211], v[60:63]
	v_mfma_f32_16x16x32_bf16 v[56:59], v[140:143], v[208:211], v[56:59]
	v_mfma_f32_16x16x32_bf16 v[48:51], v[132:135], v[216:219], v[48:51]
	v_mfma_f32_16x16x32_bf16 v[40:43], v[140:143], v[216:219], v[40:43]
	v_mfma_f32_16x16x32_bf16 v[32:35], v[132:135], v[224:227], v[32:35]
	v_mfma_f32_16x16x32_bf16 v[24:27], v[140:143], v[224:227], v[24:27]
	v_mfma_f32_16x16x32_bf16 v[16:19], v[132:135], v[232:235], v[16:19]
	v_mfma_f32_16x16x32_bf16 v[8:11], v[140:143], v[232:235], v[8:11]
	v_mfma_f32_16x16x32_bf16 v[52:55], v[188:191], v[204:207], v[52:55]
	v_mfma_f32_16x16x32_bf16 v[44:47], v[196:199], v[204:207], v[44:47]
	v_mfma_f32_16x16x32_bf16 v[36:39], v[188:191], v[212:215], v[36:39]
	v_mfma_f32_16x16x32_bf16 v[28:31], v[196:199], v[212:215], v[28:31]
	v_mfma_f32_16x16x32_bf16 v[20:23], v[188:191], v[220:223], v[20:23]
	v_mfma_f32_16x16x32_bf16 v[12:15], v[196:199], v[220:223], v[12:15]
	v_mfma_f32_16x16x32_bf16 v[4:7], v[188:191], v[228:231], v[4:7]
	v_mfma_f32_16x16x32_bf16 v[0:3], v[196:199], v[228:231], v[0:3]
	v_mfma_f32_16x16x32_bf16 v[52:55], v[192:195], v[208:211], v[52:55]
	v_mfma_f32_16x16x32_bf16 v[44:47], v[200:203], v[208:211], v[44:47]
	v_mfma_f32_16x16x32_bf16 v[36:39], v[192:195], v[216:219], v[36:39]
	v_mfma_f32_16x16x32_bf16 v[28:31], v[200:203], v[216:219], v[28:31]
	v_mfma_f32_16x16x32_bf16 v[20:23], v[192:195], v[224:227], v[20:23]
	v_mfma_f32_16x16x32_bf16 v[12:15], v[200:203], v[224:227], v[12:15]
	v_mfma_f32_16x16x32_bf16 v[4:7], v[192:195], v[232:235], v[4:7]
	v_mfma_f32_16x16x32_bf16 v[0:3], v[200:203], v[232:235], v[0:3]
	s_setprio 0
	s_barrier
	s_add_i32 s50, 0, 0x18000
	s_add_i32 s51, 0, 0x1c000
	v_add_u32_e32 v140, s50, v149
	v_add_u32_e32 v184, s51, v149
	ds_read_b128 v[128:131], v140
	ds_read_b128 v[132:135], v140 offset:1024
	ds_read_b128 v[136:139], v140 offset:2048
	ds_read_b128 v[140:143], v140 offset:3072
	ds_read_b128 v[188:191], v184
	ds_read_b128 v[192:195], v184 offset:1024
	ds_read_b128 v[196:199], v184 offset:2048
	ds_read_b128 v[200:203], v184 offset:3072
	s_add_u32 s26, s26, 0x200000
	s_addc_u32 s27, s27, 0
	s_mov_b32 m0, s35
	v_lshl_add_u64 v[184:185], s[26:27], 0, v[144:145]
	ds_read_b128 v[204:207], v186 offset:32768
	ds_read_b128 v[208:211], v186 offset:33792
	ds_read_b128 v[212:215], v186 offset:34816
	ds_read_b128 v[216:219], v186 offset:35840
	ds_read_b128 v[220:223], v186 offset:36864
	ds_read_b128 v[224:227], v186 offset:37888
	ds_read_b128 v[228:231], v186 offset:38912
	ds_read_b128 v[232:235], v186 offset:39936
	global_load_lds_dwordx4 v[184:185], off
	v_lshl_add_u64 v[184:185], s[26:27], 0, v[146:147]
	s_mov_b32 m0, s38
	s_nop 0
	global_load_lds_dwordx4 v[184:185], off
	s_waitcnt vmcnt(8)
	s_waitcnt lgkmcnt(0)
	s_barrier
	s_setprio 1
	s_waitcnt lgkmcnt(0)
	v_mfma_f32_16x16x32_bf16 v[124:127], v[128:131], v[204:207], v[124:127]
	v_mfma_f32_16x16x32_bf16 v[120:123], v[136:139], v[204:207], v[120:123]
	v_mfma_f32_16x16x32_bf16 v[112:115], v[128:131], v[212:215], v[112:115]
	v_mfma_f32_16x16x32_bf16 v[104:107], v[136:139], v[212:215], v[104:107]
	v_mfma_f32_16x16x32_bf16 v[96:99], v[128:131], v[220:223], v[96:99]
	v_mfma_f32_16x16x32_bf16 v[88:91], v[136:139], v[220:223], v[88:91]
	v_mfma_f32_16x16x32_bf16 v[80:83], v[128:131], v[228:231], v[80:83]
	v_mfma_f32_16x16x32_bf16 v[72:75], v[136:139], v[228:231], v[72:75]
	v_mfma_f32_16x16x32_bf16 v[124:127], v[132:135], v[208:211], v[124:127]
	v_mfma_f32_16x16x32_bf16 v[120:123], v[140:143], v[208:211], v[120:123]
	v_mfma_f32_16x16x32_bf16 v[112:115], v[132:135], v[216:219], v[112:115]
	v_mfma_f32_16x16x32_bf16 v[104:107], v[140:143], v[216:219], v[104:107]
	v_mfma_f32_16x16x32_bf16 v[96:99], v[132:135], v[224:227], v[96:99]
	v_mfma_f32_16x16x32_bf16 v[88:91], v[140:143], v[224:227], v[88:91]
	v_mfma_f32_16x16x32_bf16 v[80:83], v[132:135], v[232:235], v[80:83]
	v_mfma_f32_16x16x32_bf16 v[72:75], v[140:143], v[232:235], v[72:75]
	v_mfma_f32_16x16x32_bf16 v[116:119], v[188:191], v[204:207], v[116:119]
	v_mfma_f32_16x16x32_bf16 v[108:111], v[196:199], v[204:207], v[108:111]
	v_mfma_f32_16x16x32_bf16 v[100:103], v[188:191], v[212:215], v[100:103]
	v_mfma_f32_16x16x32_bf16 v[92:95], v[196:199], v[212:215], v[92:95]
	v_mfma_f32_16x16x32_bf16 v[84:87], v[188:191], v[220:223], v[84:87]
	v_mfma_f32_16x16x32_bf16 v[76:79], v[196:199], v[220:223], v[76:79]
	v_mfma_f32_16x16x32_bf16 v[68:71], v[188:191], v[228:231], v[68:71]
	v_mfma_f32_16x16x32_bf16 v[64:67], v[196:199], v[228:231], v[64:67]
	v_mfma_f32_16x16x32_bf16 v[116:119], v[192:195], v[208:211], v[116:119]
	v_mfma_f32_16x16x32_bf16 v[108:111], v[200:203], v[208:211], v[108:111]
	v_mfma_f32_16x16x32_bf16 v[100:103], v[192:195], v[216:219], v[100:103]
	v_mfma_f32_16x16x32_bf16 v[92:95], v[200:203], v[216:219], v[92:95]
	v_mfma_f32_16x16x32_bf16 v[84:87], v[192:195], v[224:227], v[84:87]
	v_mfma_f32_16x16x32_bf16 v[76:79], v[200:203], v[224:227], v[76:79]
	v_mfma_f32_16x16x32_bf16 v[68:71], v[192:195], v[232:235], v[68:71]
	v_mfma_f32_16x16x32_bf16 v[64:67], v[200:203], v[232:235], v[64:67]
	s_setprio 0
	s_barrier
; #define PG8_LDA(dst, b, h) do { _Pragma("unroll") for (int m = 0; m < 4; ++m) _Pragma("unroll") for (int k = 0; k < 2; ++k) dst[m][k] = *(const LAS bf16x8*)(lds + PG8_SA(b, h) + aoff + m * 2048 + k * 1024); } while (0)
; #define PG8_MMA(ai, bj, At, Bt) do { __builtin_amdgcn_s_setprio(1); _Pragma("unroll") for (int m = 0; m < 4; ++m) _Pragma("unroll") for (int n = 0; n < 2; ++n) _Pragma("unroll") for (int k = 0; k < 2; ++k) \
;         acc[ai][bj][m][n] = __builtin_amdgcn_mfma_f32_16x16x32_bf16(Bt[n][k], At[m][k], acc[ai][bj][m][n], 0, 0, 0); __builtin_amdgcn_s_setprio(0); } while (0)
; #define PG8_WAIT_V(n) asm volatile("s_waitcnt vmcnt(" #n ")" ::: "memory")
; #define PG8_WAIT_L(n) asm volatile("s_waitcnt lgkmcnt(" #n ")" ::: "memory")
; #define PG8_BAR __builtin_amdgcn_s_barrier()
; #define PG8_SCHED __builtin_amdgcn_sched_barrier(0)
; __device__ __forceinline__ void gemm_phase(LAS unsigned char* lds, const GemmP& g) {
;     ...
;             PG8_LDA(At, 1, 1); PG8_STAGE(PG8_SB(1, 0), b3, voffB); PG8_STAGE(PG8_SB(1, 1), b3 + hstepB, voffB); PG8_STAGE(PG8_SA(1, 0), a3, voffA);
;             PG8_WAIT_V(8); PG8_WAIT_L(0); PG8_BAR; PG8_MMA(1, 0, At, B0); PG8_MMA(1, 1, At, B1); PG8_BAR; PG8_SCHED;
;         }
;         if (wr == 0) PG8_BAR;
	s_add_u32 s26, s24, 0x80
	s_addc_u32 s27, s25, 0
	s_add_i32 s50, s50, s31
	v_lshl_add_u64 v[184:185], s[26:27], 0, v[144:145]
	s_mov_b32 m0, s50
	ds_read_b128 v[204:207], v186 offset:49152
	ds_read_b128 v[208:211], v186 offset:50176
	ds_read_b128 v[212:215], v186 offset:51200
	ds_read_b128 v[216:219], v186 offset:52224
	ds_read_b128 v[220:223], v186 offset:53248
	ds_read_b128 v[224:227], v186 offset:54272
	ds_read_b128 v[228:231], v186 offset:55296
	ds_read_b128 v[232:235], v186 offset:56320
	global_load_lds_dwordx4 v[184:185], off
	s_add_i32 m0, s50, 0x2000
	s_add_u32 s24, s24, 0x200080
	v_lshl_add_u64 v[184:185], s[26:27], 0, v[146:147]
	s_addc_u32 s25, s25, 0
	s_add_i32 s26, s51, s31
	global_load_lds_dwordx4 v[184:185], off
	v_lshl_add_u64 v[184:185], s[24:25], 0, v[144:145]
	s_mov_b32 m0, s26
	s_nop 0
	global_load_lds_dwordx4 v[184:185], off
	v_lshl_add_u64 v[184:185], s[24:25], 0, v[146:147]
	s_add_i32 m0, s26, 0x2000
	s_nop 0
	global_load_lds_dwordx4 v[184:185], off
	v_lshl_add_u64 v[184:185], s[20:21], 0, v[144:145]
	s_mov_b32 m0, s42
	s_nop 0
	global_load_lds_dwordx4 v[184:185], off
	v_lshl_add_u64 v[184:185], s[20:21], 0, v[146:147]
	s_mov_b32 m0, s43
	s_nop 0
	global_load_lds_dwordx4 v[184:185], off
	s_waitcnt vmcnt(8)
	s_waitcnt lgkmcnt(0)
	s_barrier
	s_setprio 1
	s_waitcnt lgkmcnt(0)
	v_mfma_f32_16x16x32_bf16 v[60:63], v[128:131], v[204:207], v[60:63]
	v_mfma_f32_16x16x32_bf16 v[56:59], v[136:139], v[204:207], v[56:59]
	v_mfma_f32_16x16x32_bf16 v[48:51], v[128:131], v[212:215], v[48:51]
	v_mfma_f32_16x16x32_bf16 v[40:43], v[136:139], v[212:215], v[40:43]
	v_mfma_f32_16x16x32_bf16 v[32:35], v[128:131], v[220:223], v[32:35]
	v_mfma_f32_16x16x32_bf16 v[24:27], v[136:139], v[220:223], v[24:27]
	v_mfma_f32_16x16x32_bf16 v[16:19], v[128:131], v[228:231], v[16:19]
	v_mfma_f32_16x16x32_bf16 v[8:11], v[136:139], v[228:231], v[8:11]
	v_mfma_f32_16x16x32_bf16 v[60:63], v[132:135], v[208:211], v[60:63]
	v_mfma_f32_16x16x32_bf16 v[56:59], v[140:143], v[208:211], v[56:59]
	v_mfma_f32_16x16x32_bf16 v[48:51], v[132:135], v[216:219], v[48:51]
	v_mfma_f32_16x16x32_bf16 v[40:43], v[140:143], v[216:219], v[40:43]
	v_mfma_f32_16x16x32_bf16 v[32:35], v[132:135], v[224:227], v[32:35]
	v_mfma_f32_16x16x32_bf16 v[24:27], v[140:143], v[224:227], v[24:27]
	v_mfma_f32_16x16x32_bf16 v[16:19], v[132:135], v[232:235], v[16:19]
	v_mfma_f32_16x16x32_bf16 v[8:11], v[140:143], v[232:235], v[8:11]
	v_mfma_f32_16x16x32_bf16 v[52:55], v[188:191], v[204:207], v[52:55]
	v_mfma_f32_16x16x32_bf16 v[44:47], v[196:199], v[204:207], v[44:47]
	v_mfma_f32_16x16x32_bf16 v[36:39], v[188:191], v[212:215], v[36:39]
	v_mfma_f32_16x16x32_bf16 v[28:31], v[196:199], v[212:215], v[28:31]
	v_mfma_f32_16x16x32_bf16 v[20:23], v[188:191], v[220:223], v[20:23]
	v_mfma_f32_16x16x32_bf16 v[12:15], v[196:199], v[220:223], v[12:15]
	v_mfma_f32_16x16x32_bf16 v[4:7], v[188:191], v[228:231], v[4:7]
	v_mfma_f32_16x16x32_bf16 v[0:3], v[196:199], v[228:231], v[0:3]
	v_mfma_f32_16x16x32_bf16 v[52:55], v[192:195], v[208:211], v[52:55]
	v_mfma_f32_16x16x32_bf16 v[44:47], v[200:203], v[208:211], v[44:47]
	v_mfma_f32_16x16x32_bf16 v[36:39], v[192:195], v[216:219], v[36:39]
	v_mfma_f32_16x16x32_bf16 v[28:31], v[200:203], v[216:219], v[28:31]
	v_mfma_f32_16x16x32_bf16 v[20:23], v[192:195], v[224:227], v[20:23]
	v_mfma_f32_16x16x32_bf16 v[12:15], v[200:203], v[224:227], v[12:15]
	v_mfma_f32_16x16x32_bf16 v[4:7], v[192:195], v[232:235], v[4:7]
	v_mfma_f32_16x16x32_bf16 v[0:3], v[200:203], v[232:235], v[0:3]
	s_setprio 0
	s_barrier
	s_add_i32 s49, s49, 2
	s_add_u32 s45, s45, 0x100
	s_addc_u32 s46, s46, 0
	s_add_u32 s47, s47, 0x100
	s_addc_u32 s48, s48, 0
	s_add_u32 s18, s18, 0x100
	s_addc_u32 s19, s19, 0
	s_cmpk_gt_u32 s49, 0x7d
	s_cbranch_scc0 .LBB0_1615
	s_and_b64 vcc, exec, s[2:3]
	s_cbranch_vccz .LBB0_1618
	s_barrier
